# v7 plus peeled first K iteration of each GEMM unit (accumulator zeroing removed, first MFMAs take constant 0 as C)
# speedup vs baseline: 1.0170x; 1.0024x over previous
; __device__ __forceinline__ float row_rstd(const u64* ssq, int r) { return __builtin_amdgcn_rsqf(fx_to_pos(ssq[r]) * (1.0f / 4096.0f) + RMS_EPS); }
; #define PG8_STAGE(bufoff, gbase, voff) do { _Pragma("unroll") for (int _i = 0; _i < 2; ++_i) \
;         __builtin_amdgcn_global_load_lds((const unsigned*)((const char*)(gbase) + (voff)[_i]), (PG8_LAS unsigned*)(lds + (bufoff) + ldsw + _i * 8192), 16, 0, 0); } while (0)
; #define PG8_LDA(dst, b, h) do { _Pragma("unroll") for (int m = 0; m < 4; ++m) _Pragma("unroll") for (int k = 0; k < 2; ++k) dst[m][k] = *(const PG8_LAS bf16x8*)(lds + PG8_SA(b, h) + aoff + m * 2048 + k * 1024); } while (0)
; #define PG8_LDB(dst, b, h) do { _Pragma("unroll") for (int n = 0; n < 2; ++n) _Pragma("unroll") for (int k = 0; k < 2; ++k) dst[n][k] = *(const PG8_LAS bf16x8*)(lds + PG8_SB(b, h) + boff + n * 2048 + k * 1024); } while (0)
; #define PG8_WAIT_V(n) asm volatile("s_waitcnt vmcnt(" #n ")" ::: "memory")
; #define PG8_BAR __builtin_amdgcn_s_barrier()
;     __device__ __forceinline__ void operator()(const f32x4 (&acc)[2][2][4][2], const Unit& u, int wr, int wc, int fr, int fq) const {
;     ...
;                 for (int m = 0; m < 4; ++m) { const int r = row0 + ai * HALF + m * 16; const float rs = row_rstd(ssq, r); bf16_t* rowp = Z + (size_t)r * AB_Z + col0;
; template <class Epi, class Sched, bool ALIGN_EPI = false, bool SP2 = false>
; __device__ __forceinline__ void gemm_phase(PG8_LAS unsigned char* lds, const Gemm g, const Sched& S, const Epi& E, const int wid) {
;     ...
;             const char* a1 = cA + (size_t)(t + 1) * kstep;
;             const char* a2 = last ? nA : cA + (size_t)(t + 2) * kstep; const char* b2 = last ? nB : cB + (size_t)(t + 2) * kstep;
;             const char* a3 = a2 + kstep; const char* b3 = b2 + kstep;
;             if (last && has_next) S.a_ready(nxt);
;             if constexpr (SP2) {
;             PG8_LDB(B0, 0, 0); PG8_LDB(B1, 0, 1); PG8_SCHED; PG8_LDA(At, 0, 0); PG8_STAGE(PG8_SA(1, 1), a1 + hstep, voffA);
;             PG8_WAIT_V(8); PG8_WAIT_L(0); PG8_BAR; PG8_MMA(0, 0, At, B0); PG8_MMA(0, 1, At, B1); PG8_BAR; PG8_SCHED;
;             PG8_LDA(At, 0, 1); PG8_STAGE(PG8_SB(0, 0), b2, voffB); PG8_STAGE(PG8_SB(0, 1), b2 + hstep, voffB); PG8_STAGE(PG8_SA(0, 0), a2, voffA);
;             PG8_WAIT_V(8); PG8_WAIT_L(0); PG8_BAR; PG8_MMA(1, 0, At, B0); PG8_MMA(1, 1, At, B1); PG8_BAR; PG8_SCHED;
.LBB0_248:
	s_ashr_i32 s15, s14, 31
	s_lshl_b64 s[16:17], s[14:15], 21
	s_add_u32 s16, s78, s16
	s_addc_u32 s17, s79, s17
	s_and_b64 s[18:19], s[0:1], exec
	s_cselect_b32 s15, s17, s23
	s_cselect_b32 s21, s16, s22
	s_ashr_i32 s13, s12, 31
	s_lshl_b64 s[18:19], s[12:13], 21
	s_add_u32 s18, s82, s18
	s_addc_u32 s19, s83, s19
	s_and_b64 s[26:27], s[0:1], exec
	s_cselect_b32 s13, s19, s25
	s_cselect_b32 s45, s18, s24
	s_add_u32 s22, s22, 0x100080
	s_addc_u32 s23, s23, 0
	s_add_u32 s46, s24, 0x100
	s_addc_u32 s47, s25, 0
	s_mov_b32 s48, -2
	v_add_u32_e32 v246, 0x18000, v158
	v_add_u32_e32 v248, 0x1c000, v158
	ds_read_b128 v[148:151], v160
	ds_read_b128 v[152:155], v160 offset:1024
	ds_read_b128 v[164:167], v160 offset:2048
	ds_read_b128 v[168:171], v160 offset:3072
	ds_read_b128 v[172:175], v161
	ds_read_b128 v[176:179], v161 offset:1024
	ds_read_b128 v[180:183], v161 offset:2048
	ds_read_b128 v[184:187], v161 offset:3072
	s_add_u32 s24, s22, 0xfff00080
	s_addc_u32 s25, s23, -1
	s_cmp_eq_u32 s48, 60
	s_cselect_b32 s27, s15, s25
	s_cselect_b32 s26, s21, s24
	s_cselect_b32 s25, s13, s47
	s_cselect_b32 s24, s45, s46
	s_add_i32 m0, s30, 0xc000
	ds_read_b128 v[188:191], v162
	ds_read_b128 v[192:195], v162 offset:1024
	ds_read_b128 v[196:199], v162 offset:2048
	ds_read_b128 v[200:203], v162 offset:3072
	ds_read_b128 v[204:207], v162 offset:4096
	ds_read_b128 v[208:211], v162 offset:5120
	ds_read_b128 v[212:215], v162 offset:6144
	ds_read_b128 v[216:219], v162 offset:7168
	global_load_lds_dwordx4 v140, s[22:23]
	s_add_i32 m0, s30, 0xe000
	s_nop 0
	global_load_lds_dwordx4 v142, s[22:23]
	s_waitcnt vmcnt(8)
	s_waitcnt lgkmcnt(0)
	v_lshl_add_u32 v244, s20, 8, v157
	v_ashrrev_i32_e32 v245, 31, v244
	v_lshl_add_u64 v[244:245], v[244:245], 3, s[4:5]
	global_load_dwordx2 v[230:231], v[244:245], off
	global_load_dwordx2 v[232:233], v[244:245], off offset:128
	global_load_dwordx2 v[234:235], v[244:245], off offset:256
	global_load_dwordx2 v[236:237], v[244:245], off offset:384
	global_load_dwordx2 v[238:239], v[244:245], off offset:1024
	global_load_dwordx2 v[240:241], v[244:245], off offset:1152
	global_load_dwordx2 v[242:243], v[244:245], off offset:1280
	global_load_dwordx2 v[244:245], v[244:245], off offset:1408
	s_setprio 1
	s_barrier
	v_mfma_f32_16x16x32_bf16 v[124:127], v[148:151], v[188:191], 0
	v_mfma_f32_16x16x32_bf16 v[120:123], v[164:167], v[188:191], 0
	v_mfma_f32_16x16x32_bf16 v[108:111], v[148:151], v[196:199], 0
	v_mfma_f32_16x16x32_bf16 v[104:107], v[164:167], v[196:199], 0
	v_mfma_f32_16x16x32_bf16 v[92:95], v[148:151], v[204:207], 0
	v_mfma_f32_16x16x32_bf16 v[88:91], v[164:167], v[204:207], 0
	v_mfma_f32_16x16x32_bf16 v[76:79], v[148:151], v[212:215], 0
	v_mfma_f32_16x16x32_bf16 v[72:75], v[164:167], v[212:215], 0
	v_mfma_f32_16x16x32_bf16 v[124:127], v[152:155], v[192:195], v[124:127]
	v_mfma_f32_16x16x32_bf16 v[120:123], v[168:171], v[192:195], v[120:123]
	v_mfma_f32_16x16x32_bf16 v[108:111], v[152:155], v[200:203], v[108:111]
	v_mfma_f32_16x16x32_bf16 v[104:107], v[168:171], v[200:203], v[104:107]
	v_mfma_f32_16x16x32_bf16 v[92:95], v[152:155], v[208:211], v[92:95]
	v_mfma_f32_16x16x32_bf16 v[88:91], v[168:171], v[208:211], v[88:91]
	v_mfma_f32_16x16x32_bf16 v[76:79], v[152:155], v[216:219], v[76:79]
	v_mfma_f32_16x16x32_bf16 v[72:75], v[168:171], v[216:219], v[72:75]
	v_mfma_f32_16x16x32_bf16 v[116:119], v[172:175], v[188:191], 0
	v_mfma_f32_16x16x32_bf16 v[112:115], v[180:183], v[188:191], 0
	v_mfma_f32_16x16x32_bf16 v[100:103], v[172:175], v[196:199], 0
	v_mfma_f32_16x16x32_bf16 v[96:99], v[180:183], v[196:199], 0
	v_mfma_f32_16x16x32_bf16 v[84:87], v[172:175], v[204:207], 0
	v_mfma_f32_16x16x32_bf16 v[80:83], v[180:183], v[204:207], 0
	v_mfma_f32_16x16x32_bf16 v[68:71], v[172:175], v[212:215], 0
	v_mfma_f32_16x16x32_bf16 v[64:67], v[180:183], v[212:215], 0
	v_mfma_f32_16x16x32_bf16 v[116:119], v[176:179], v[192:195], v[116:119]
	v_mfma_f32_16x16x32_bf16 v[112:115], v[184:187], v[192:195], v[112:115]
	v_mfma_f32_16x16x32_bf16 v[100:103], v[176:179], v[200:203], v[100:103]
	v_mfma_f32_16x16x32_bf16 v[96:99], v[184:187], v[200:203], v[96:99]
	v_mfma_f32_16x16x32_bf16 v[84:87], v[176:179], v[208:211], v[84:87]
	v_mfma_f32_16x16x32_bf16 v[80:83], v[184:187], v[208:211], v[80:83]
	v_mfma_f32_16x16x32_bf16 v[68:71], v[176:179], v[216:219], v[68:71]
	v_mfma_f32_16x16x32_bf16 v[64:67], v[184:187], v[216:219], v[64:67]
	s_barrier
	s_setprio 0
	s_add_i32 s49, s40, s29
	s_mov_b32 m0, s49
	ds_read_b128 v[188:191], v162 offset:16384
	ds_read_b128 v[192:195], v162 offset:17408
	ds_read_b128 v[196:199], v162 offset:18432
	ds_read_b128 v[200:203], v162 offset:19456
	ds_read_b128 v[204:207], v162 offset:20480
	ds_read_b128 v[208:211], v162 offset:21504
	ds_read_b128 v[212:215], v162 offset:22528
	ds_read_b128 v[216:219], v162 offset:23552
	global_load_lds_dwordx4 v130, s[24:25]
	s_add_i32 m0, s49, 0x2000
	s_add_u32 s50, s24, 0x100000
	s_addc_u32 s51, s25, 0
	s_add_i32 s49, s41, s29
	global_load_lds_dwordx4 v134, s[24:25]
	s_mov_b32 m0, s49
	global_load_lds_dwordx4 v130, s[50:51]
	s_add_i32 m0, s49, 0x2000
	s_nop 0
	global_load_lds_dwordx4 v134, s[50:51]
	s_mov_b32 m0, s30
	s_nop 0
	global_load_lds_dwordx4 v128, s[26:27]
	s_mov_b32 m0, s31
	s_nop 0
	global_load_lds_dwordx4 v132, s[26:27]
	s_waitcnt vmcnt(8)
	s_waitcnt lgkmcnt(0)
	s_setprio 1
	s_barrier
; #define PG8_STAGE(bufoff, gbase, voff) do { _Pragma("unroll") for (int _i = 0; _i < 2; ++_i) \
;         __builtin_amdgcn_global_load_lds((const unsigned*)((const char*)(gbase) + (voff)[_i]), (PG8_LAS unsigned*)(lds + (bufoff) + ldsw + _i * 8192), 16, 0, 0); } while (0)
; #define PG8_LDA(dst, b, h) do { _Pragma("unroll") for (int m = 0; m < 4; ++m) _Pragma("unroll") for (int k = 0; k < 2; ++k) dst[m][k] = *(const PG8_LAS bf16x8*)(lds + PG8_SA(b, h) + aoff + m * 2048 + k * 1024); } while (0)
; #define PG8_LDB(dst, b, h) do { _Pragma("unroll") for (int n = 0; n < 2; ++n) _Pragma("unroll") for (int k = 0; k < 2; ++k) dst[n][k] = *(const PG8_LAS bf16x8*)(lds + PG8_SB(b, h) + boff + n * 2048 + k * 1024); } while (0)
; #define PG8_MMA(ai, bj, At, Bt) do { __builtin_amdgcn_s_setprio(1); _Pragma("unroll") for (int m = 0; m < 4; ++m) _Pragma("unroll") for (int n = 0; n < 2; ++n) _Pragma("unroll") for (int k = 0; k < 2; ++k) \
;         acc[ai][bj][m][n] = __builtin_amdgcn_mfma_f32_16x16x32_bf16(Bt[n][k], At[m][k], acc[ai][bj][m][n], 0, 0, 0); __builtin_amdgcn_s_setprio(0); } while (0)
; #define PG8_WAIT_V(n) asm volatile("s_waitcnt vmcnt(" #n ")" ::: "memory")
; #define PG8_WAIT_L(n) asm volatile("s_waitcnt lgkmcnt(" #n ")" ::: "memory")
; #define PG8_BAR __builtin_amdgcn_s_barrier()
; #define PG8_SCHED __builtin_amdgcn_sched_barrier(0)
; template <class Epi, class Sched, bool ALIGN_EPI = false, bool SP2 = false>
; __device__ __forceinline__ void gemm_phase(PG8_LAS unsigned char* lds, const Gemm g, const Sched& S, const Epi& E, const int wid) {
;     ...
;             PG8_WAIT_V(8); PG8_WAIT_L(0); PG8_BAR; PG8_MMA(1, 0, At, B0); PG8_MMA(1, 1, At, B1); PG8_BAR; PG8_SCHED;
;             PG8_LDB(B0, 1, 0); PG8_LDB(B1, 1, 1); PG8_SCHED; PG8_LDA(At, 1, 0); PG8_STAGE(PG8_SA(0, 1), a2 + hstep, voffA);
;             PG8_WAIT_V(8); PG8_WAIT_L(0); PG8_BAR; PG8_MMA(0, 0, At, B0); PG8_MMA(0, 1, At, B1); PG8_BAR; PG8_SCHED;
	v_mfma_f32_16x16x32_bf16 v[60:63], v[148:151], v[188:191], 0
	v_mfma_f32_16x16x32_bf16 v[56:59], v[164:167], v[188:191], 0
	v_mfma_f32_16x16x32_bf16 v[44:47], v[148:151], v[196:199], 0
	v_mfma_f32_16x16x32_bf16 v[40:43], v[164:167], v[196:199], 0
	v_mfma_f32_16x16x32_bf16 v[28:31], v[148:151], v[204:207], 0
	v_mfma_f32_16x16x32_bf16 v[24:27], v[164:167], v[204:207], 0
	v_mfma_f32_16x16x32_bf16 v[12:15], v[148:151], v[212:215], 0
	v_mfma_f32_16x16x32_bf16 v[8:11], v[164:167], v[212:215], 0
	v_mfma_f32_16x16x32_bf16 v[60:63], v[152:155], v[192:195], v[60:63]
	v_mfma_f32_16x16x32_bf16 v[56:59], v[168:171], v[192:195], v[56:59]
	v_mfma_f32_16x16x32_bf16 v[44:47], v[152:155], v[200:203], v[44:47]
	v_mfma_f32_16x16x32_bf16 v[40:43], v[168:171], v[200:203], v[40:43]
	v_mfma_f32_16x16x32_bf16 v[28:31], v[152:155], v[208:211], v[28:31]
	v_mfma_f32_16x16x32_bf16 v[24:27], v[168:171], v[208:211], v[24:27]
	v_mfma_f32_16x16x32_bf16 v[12:15], v[152:155], v[216:219], v[12:15]
	v_mfma_f32_16x16x32_bf16 v[8:11], v[168:171], v[216:219], v[8:11]
	v_mfma_f32_16x16x32_bf16 v[52:55], v[172:175], v[188:191], 0
	v_mfma_f32_16x16x32_bf16 v[48:51], v[180:183], v[188:191], 0
	v_mfma_f32_16x16x32_bf16 v[36:39], v[172:175], v[196:199], 0
	v_mfma_f32_16x16x32_bf16 v[32:35], v[180:183], v[196:199], 0
	v_mfma_f32_16x16x32_bf16 v[20:23], v[172:175], v[204:207], 0
	v_mfma_f32_16x16x32_bf16 v[16:19], v[180:183], v[204:207], 0
	v_mfma_f32_16x16x32_bf16 v[4:7], v[172:175], v[212:215], 0
	v_mfma_f32_16x16x32_bf16 v[0:3], v[180:183], v[212:215], 0
	v_mfma_f32_16x16x32_bf16 v[52:55], v[176:179], v[192:195], v[52:55]
	v_mfma_f32_16x16x32_bf16 v[48:51], v[184:187], v[192:195], v[48:51]
	v_mfma_f32_16x16x32_bf16 v[36:39], v[176:179], v[200:203], v[36:39]
	v_mfma_f32_16x16x32_bf16 v[32:35], v[184:187], v[200:203], v[32:35]
	v_mfma_f32_16x16x32_bf16 v[20:23], v[176:179], v[208:211], v[20:23]
	v_mfma_f32_16x16x32_bf16 v[16:19], v[184:187], v[208:211], v[16:19]
	v_mfma_f32_16x16x32_bf16 v[4:7], v[176:179], v[216:219], v[4:7]
	v_mfma_f32_16x16x32_bf16 v[0:3], v[184:187], v[216:219], v[0:3]
	s_barrier
	s_setprio 0
	s_add_i32 s49, 0, 0x18000
	s_add_i32 s50, 0, 0x1c000
	ds_read_b128 v[148:151], v246
	ds_read_b128 v[152:155], v246 offset:1024
	ds_read_b128 v[164:167], v246 offset:2048
	ds_read_b128 v[168:171], v246 offset:3072
	ds_read_b128 v[172:175], v248
	ds_read_b128 v[176:179], v248 offset:1024
	ds_read_b128 v[180:183], v248 offset:2048
	ds_read_b128 v[184:187], v248 offset:3072
	s_add_u32 s26, s26, 0x100000
	s_addc_u32 s27, s27, 0
	s_mov_b32 m0, s34
	ds_read_b128 v[188:191], v162 offset:32768
	ds_read_b128 v[192:195], v162 offset:33792
	ds_read_b128 v[196:199], v162 offset:34816
	ds_read_b128 v[200:203], v162 offset:35840
	ds_read_b128 v[204:207], v162 offset:36864
	ds_read_b128 v[208:211], v162 offset:37888
	ds_read_b128 v[212:215], v162 offset:38912
	ds_read_b128 v[216:219], v162 offset:39936
	global_load_lds_dwordx4 v128, s[26:27]
	s_mov_b32 m0, s35
	s_nop 0
	global_load_lds_dwordx4 v132, s[26:27]
	s_waitcnt vmcnt(8)
	s_waitcnt lgkmcnt(0)
	s_setprio 1
	s_barrier
	v_mfma_f32_16x16x32_bf16 v[124:127], v[148:151], v[188:191], v[124:127]
	v_mfma_f32_16x16x32_bf16 v[120:123], v[164:167], v[188:191], v[120:123]
	v_mfma_f32_16x16x32_bf16 v[108:111], v[148:151], v[196:199], v[108:111]
	v_mfma_f32_16x16x32_bf16 v[104:107], v[164:167], v[196:199], v[104:107]
	v_mfma_f32_16x16x32_bf16 v[92:95], v[148:151], v[204:207], v[92:95]
	v_mfma_f32_16x16x32_bf16 v[88:91], v[164:167], v[204:207], v[88:91]
	v_mfma_f32_16x16x32_bf16 v[76:79], v[148:151], v[212:215], v[76:79]
	v_mfma_f32_16x16x32_bf16 v[72:75], v[164:167], v[212:215], v[72:75]
	v_mfma_f32_16x16x32_bf16 v[124:127], v[152:155], v[192:195], v[124:127]
	v_mfma_f32_16x16x32_bf16 v[120:123], v[168:171], v[192:195], v[120:123]
	v_mfma_f32_16x16x32_bf16 v[108:111], v[152:155], v[200:203], v[108:111]
	v_mfma_f32_16x16x32_bf16 v[104:107], v[168:171], v[200:203], v[104:107]
	v_mfma_f32_16x16x32_bf16 v[92:95], v[152:155], v[208:211], v[92:95]
	v_mfma_f32_16x16x32_bf16 v[88:91], v[168:171], v[208:211], v[88:91]
	v_mfma_f32_16x16x32_bf16 v[76:79], v[152:155], v[216:219], v[76:79]
	v_mfma_f32_16x16x32_bf16 v[72:75], v[168:171], v[216:219], v[72:75]
	v_mfma_f32_16x16x32_bf16 v[116:119], v[172:175], v[188:191], v[116:119]
	v_mfma_f32_16x16x32_bf16 v[112:115], v[180:183], v[188:191], v[112:115]
	v_mfma_f32_16x16x32_bf16 v[100:103], v[172:175], v[196:199], v[100:103]
	v_mfma_f32_16x16x32_bf16 v[96:99], v[180:183], v[196:199], v[96:99]
	v_mfma_f32_16x16x32_bf16 v[84:87], v[172:175], v[204:207], v[84:87]
	v_mfma_f32_16x16x32_bf16 v[80:83], v[180:183], v[204:207], v[80:83]
	v_mfma_f32_16x16x32_bf16 v[68:71], v[172:175], v[212:215], v[68:71]
	v_mfma_f32_16x16x32_bf16 v[64:67], v[180:183], v[212:215], v[64:67]
	v_mfma_f32_16x16x32_bf16 v[116:119], v[176:179], v[192:195], v[116:119]
	v_mfma_f32_16x16x32_bf16 v[112:115], v[184:187], v[192:195], v[112:115]
	v_mfma_f32_16x16x32_bf16 v[100:103], v[176:179], v[200:203], v[100:103]
	v_mfma_f32_16x16x32_bf16 v[96:99], v[184:187], v[200:203], v[96:99]
	v_mfma_f32_16x16x32_bf16 v[84:87], v[176:179], v[208:211], v[84:87]
	v_mfma_f32_16x16x32_bf16 v[80:83], v[184:187], v[208:211], v[80:83]
	v_mfma_f32_16x16x32_bf16 v[68:71], v[176:179], v[216:219], v[68:71]
	v_mfma_f32_16x16x32_bf16 v[64:67], v[184:187], v[216:219], v[64:67]
	s_barrier
; #define PG8_STAGE(bufoff, gbase, voff) do { _Pragma("unroll") for (int _i = 0; _i < 2; ++_i) \
;         __builtin_amdgcn_global_load_lds((const unsigned*)((const char*)(gbase) + (voff)[_i]), (PG8_LAS unsigned*)(lds + (bufoff) + ldsw + _i * 8192), 16, 0, 0); } while (0)
; #define PG8_LDA(dst, b, h) do { _Pragma("unroll") for (int m = 0; m < 4; ++m) _Pragma("unroll") for (int k = 0; k < 2; ++k) dst[m][k] = *(const PG8_LAS bf16x8*)(lds + PG8_SA(b, h) + aoff + m * 2048 + k * 1024); } while (0)
; #define PG8_MMA(ai, bj, At, Bt) do { __builtin_amdgcn_s_setprio(1); _Pragma("unroll") for (int m = 0; m < 4; ++m) _Pragma("unroll") for (int n = 0; n < 2; ++n) _Pragma("unroll") for (int k = 0; k < 2; ++k) \
;         acc[ai][bj][m][n] = __builtin_amdgcn_mfma_f32_16x16x32_bf16(Bt[n][k], At[m][k], acc[ai][bj][m][n], 0, 0, 0); __builtin_amdgcn_s_setprio(0); } while (0)
; #define PG8_WAIT_V(n) asm volatile("s_waitcnt vmcnt(" #n ")" ::: "memory")
; #define PG8_WAIT_L(n) asm volatile("s_waitcnt lgkmcnt(" #n ")" ::: "memory")
; #define PG8_BAR __builtin_amdgcn_s_barrier()
; #define PG8_SCHED __builtin_amdgcn_sched_barrier(0)
; template <class Epi, class Sched, bool ALIGN_EPI = false, bool SP2 = false>
; __device__ __forceinline__ void gemm_phase(PG8_LAS unsigned char* lds, const Gemm g, const Sched& S, const Epi& E, const int wid) {
;     ...
;         for (int t = 0; t < nt; t += 2) {
;     ...
;             PG8_LDA(At, 1, 1); PG8_STAGE(PG8_SB(1, 0), b3, voffB); PG8_STAGE(PG8_SB(1, 1), b3 + hstep, voffB); PG8_STAGE(PG8_SA(1, 0), a3, voffA);
;             PG8_WAIT_V(8); PG8_WAIT_L(0); PG8_BAR; PG8_MMA(1, 0, At, B0); PG8_MMA(1, 1, At, B1); PG8_BAR; PG8_SCHED;
	s_setprio 0
	s_add_u32 s98, s24, 0x80
	s_addc_u32 s99, s25, 0
	s_add_u32 s100, s26, 0xfff00080
	s_addc_u32 s101, s27, -1
	s_add_i32 s26, s49, s29
	s_mov_b32 m0, s26
	ds_read_b128 v[188:191], v162 offset:49152
	ds_read_b128 v[192:195], v162 offset:50176
	ds_read_b128 v[196:199], v162 offset:51200
	ds_read_b128 v[200:203], v162 offset:52224
	ds_read_b128 v[204:207], v162 offset:53248
	ds_read_b128 v[208:211], v162 offset:54272
	ds_read_b128 v[212:215], v162 offset:55296
	ds_read_b128 v[216:219], v162 offset:56320
	global_load_lds_dwordx4 v130, s[98:99]
	s_add_i32 m0, s26, 0x2000
	s_add_u32 s24, s24, 0x100080
	s_addc_u32 s25, s25, 0
	s_add_i32 s26, s50, s29
	global_load_lds_dwordx4 v134, s[98:99]
	s_mov_b32 m0, s26
	s_nop 0
	global_load_lds_dwordx4 v130, s[24:25]
	s_add_i32 m0, s26, 0x2000
	s_nop 0
	global_load_lds_dwordx4 v134, s[24:25]
	s_mov_b32 m0, s37
	s_nop 0
	global_load_lds_dwordx4 v128, s[100:101]
	s_mov_b32 m0, s38
	s_nop 0
	global_load_lds_dwordx4 v132, s[100:101]
	s_waitcnt vmcnt(8)
	s_waitcnt lgkmcnt(0)
	s_setprio 1
	s_barrier
	v_mfma_f32_16x16x32_bf16 v[60:63], v[148:151], v[188:191], v[60:63]
	v_mfma_f32_16x16x32_bf16 v[56:59], v[164:167], v[188:191], v[56:59]
	v_mfma_f32_16x16x32_bf16 v[44:47], v[148:151], v[196:199], v[44:47]
	v_mfma_f32_16x16x32_bf16 v[40:43], v[164:167], v[196:199], v[40:43]
	v_mfma_f32_16x16x32_bf16 v[28:31], v[148:151], v[204:207], v[28:31]
	v_mfma_f32_16x16x32_bf16 v[24:27], v[164:167], v[204:207], v[24:27]
	v_mfma_f32_16x16x32_bf16 v[12:15], v[148:151], v[212:215], v[12:15]
	v_mfma_f32_16x16x32_bf16 v[8:11], v[164:167], v[212:215], v[8:11]
	v_mfma_f32_16x16x32_bf16 v[60:63], v[152:155], v[192:195], v[60:63]
	v_mfma_f32_16x16x32_bf16 v[56:59], v[168:171], v[192:195], v[56:59]
	v_mfma_f32_16x16x32_bf16 v[44:47], v[152:155], v[200:203], v[44:47]
	v_mfma_f32_16x16x32_bf16 v[40:43], v[168:171], v[200:203], v[40:43]
	v_mfma_f32_16x16x32_bf16 v[28:31], v[152:155], v[208:211], v[28:31]
	v_mfma_f32_16x16x32_bf16 v[24:27], v[168:171], v[208:211], v[24:27]
	v_mfma_f32_16x16x32_bf16 v[12:15], v[152:155], v[216:219], v[12:15]
	v_mfma_f32_16x16x32_bf16 v[8:11], v[168:171], v[216:219], v[8:11]
	v_mfma_f32_16x16x32_bf16 v[52:55], v[172:175], v[188:191], v[52:55]
	v_mfma_f32_16x16x32_bf16 v[48:51], v[180:183], v[188:191], v[48:51]
	v_mfma_f32_16x16x32_bf16 v[36:39], v[172:175], v[196:199], v[36:39]
	v_mfma_f32_16x16x32_bf16 v[32:35], v[180:183], v[196:199], v[32:35]
	v_mfma_f32_16x16x32_bf16 v[20:23], v[172:175], v[204:207], v[20:23]
	v_mfma_f32_16x16x32_bf16 v[16:19], v[180:183], v[204:207], v[16:19]
	v_mfma_f32_16x16x32_bf16 v[4:7], v[172:175], v[212:215], v[4:7]
	v_mfma_f32_16x16x32_bf16 v[0:3], v[180:183], v[212:215], v[0:3]
	v_mfma_f32_16x16x32_bf16 v[52:55], v[176:179], v[192:195], v[52:55]
	v_mfma_f32_16x16x32_bf16 v[48:51], v[184:187], v[192:195], v[48:51]
	v_mfma_f32_16x16x32_bf16 v[36:39], v[176:179], v[200:203], v[36:39]
	v_mfma_f32_16x16x32_bf16 v[32:35], v[184:187], v[200:203], v[32:35]
	v_mfma_f32_16x16x32_bf16 v[20:23], v[176:179], v[208:211], v[20:23]
	v_mfma_f32_16x16x32_bf16 v[16:19], v[184:187], v[208:211], v[16:19]
	v_mfma_f32_16x16x32_bf16 v[4:7], v[176:179], v[216:219], v[4:7]
	v_mfma_f32_16x16x32_bf16 v[0:3], v[184:187], v[216:219], v[0:3]
	s_barrier
	s_setprio 0
	s_add_i32 s48, s48, 2
	s_add_u32 s22, s22, 0x100
	s_addc_u32 s23, s23, 0
	s_add_u32 s46, s46, 0x100
	s_addc_u32 s47, s47, 0
	s_cmp_gt_u32 s48, 61
	s_cbranch_scc0 .LBB0_249
	s_branch .Lpeel_exit_0

; #define PG8_BAR __builtin_amdgcn_s_barrier()
;     __device__ __forceinline__ void operator()(const f32x4 (&acc)[2][2][4][2], const Unit& u, int wr, int wc, int fr, int fq) const {
;     ...
;         if (u.pn < 40) {
; template <class Epi, class Sched, bool ALIGN_EPI = false, bool SP2 = false>
; __device__ __forceinline__ void gemm_phase(PG8_LAS unsigned char* lds, const Gemm g, const Sched& S, const Epi& E, const int wid) {
;     ...
;         if constexpr (ALIGN_EPI) { if (wr == 0) PG8_BAR; }
;         if constexpr (!Epi::AFTER_DRAIN) { E(acc, cur, wr, wc, fr, fq); S.done(cur); }
;         if (!has_next) break;
.Lpeel_exit_0:
	s_and_b64 vcc, exec, s[8:9]
	s_cbranch_vccnz .LBB0_254
	v_lshl_add_u32 v148, s20, 8, v157
	s_cmp_gt_i32 s44, 39
	s_mov_b64 s[20:21], -1
	s_cbranch_scc1 .LBB0_255

; #define PG8_STAGE(bufoff, gbase, voff) do { _Pragma("unroll") for (int _i = 0; _i < 2; ++_i) \
;         __builtin_amdgcn_global_load_lds((const unsigned*)((const char*)(gbase) + (voff)[_i]), (PG8_LAS unsigned*)(lds + (bufoff) + ldsw + _i * 8192), 16, 0, 0); } while (0)
; #define PG8_LDA(dst, b, h) do { _Pragma("unroll") for (int m = 0; m < 4; ++m) _Pragma("unroll") for (int k = 0; k < 2; ++k) dst[m][k] = *(const PG8_LAS bf16x8*)(lds + PG8_SA(b, h) + aoff + m * 2048 + k * 1024); } while (0)
; #define PG8_LDB(dst, b, h) do { _Pragma("unroll") for (int n = 0; n < 2; ++n) _Pragma("unroll") for (int k = 0; k < 2; ++k) dst[n][k] = *(const PG8_LAS bf16x8*)(lds + PG8_SB(b, h) + boff + n * 2048 + k * 1024); } while (0)
; #define PG8_MMA(ai, bj, At, Bt) do { __builtin_amdgcn_s_setprio(1); _Pragma("unroll") for (int m = 0; m < 4; ++m) _Pragma("unroll") for (int n = 0; n < 2; ++n) _Pragma("unroll") for (int k = 0; k < 2; ++k) \
;         acc[ai][bj][m][n] = __builtin_amdgcn_mfma_f32_16x16x32_bf16(Bt[n][k], At[m][k], acc[ai][bj][m][n], 0, 0, 0); __builtin_amdgcn_s_setprio(0); } while (0)
; #define PG8_WAIT_V(n) asm volatile("s_waitcnt vmcnt(" #n ")" ::: "memory")
; #define PG8_WAIT_L(n) asm volatile("s_waitcnt lgkmcnt(" #n ")" ::: "memory")
; #define PG8_BAR __builtin_amdgcn_s_barrier()
; #define PG8_SCHED __builtin_amdgcn_sched_barrier(0)
; template <class Epi, class Sched, bool ALIGN_EPI = false, bool SP2 = false>
; __device__ __forceinline__ void gemm_phase(PG8_LAS unsigned char* lds, const Gemm g, const Sched& S, const Epi& E, const int wid) {
;     ...
;             const char* a2 = last ? nA : cA + (size_t)(t + 2) * kstep; const char* b2 = last ? nB : cB + (size_t)(t + 2) * kstep;
;             const char* a3 = a2 + kstep; const char* b3 = b2 + kstep;
;             if (last && has_next) S.a_ready(nxt);
;             if constexpr (SP2) {
;             PG8_LDB(B0, 0, 0); PG8_LDB(B1, 0, 1); PG8_SCHED; PG8_LDA(At, 0, 0); PG8_STAGE(PG8_SA(1, 1), a1 + hstep, voffA);
;             PG8_WAIT_V(8); PG8_WAIT_L(0); PG8_BAR; PG8_MMA(0, 0, At, B0); PG8_MMA(0, 1, At, B1); PG8_BAR; PG8_SCHED;
;             PG8_LDA(At, 0, 1); PG8_STAGE(PG8_SB(0, 0), b2, voffB); PG8_STAGE(PG8_SB(0, 1), b2 + hstep, voffB); PG8_STAGE(PG8_SA(0, 0), a2, voffA);
;             PG8_WAIT_V(8); PG8_WAIT_L(0); PG8_BAR; PG8_MMA(1, 0, At, B0); PG8_MMA(1, 1, At, B1); PG8_BAR; PG8_SCHED;
.LBB0_842:
	s_ashr_i32 s15, s14, 31
	s_lshl_b64 s[18:19], s[14:15], 21
	s_add_u32 s13, s90, s18
	s_addc_u32 s15, s91, s19
	s_ashr_i32 s11, s10, 31
	s_lshl_b64 s[20:21], s[10:11], 7
	s_add_u32 s18, s13, s20
	s_addc_u32 s19, s15, s21
	s_and_b64 s[30:31], s[16:17], exec
	s_cselect_b32 s11, s19, s27
	s_cselect_b32 s15, s18, s26
	s_ashr_i32 s13, s12, 31
	s_lshl_b64 s[30:31], s[12:13], 21
	s_add_u32 s13, s34, s30
	s_addc_u32 s23, s35, s31
	s_add_u32 s20, s13, s20
	s_addc_u32 s21, s23, s21
	s_and_b64 s[30:31], s[16:17], exec
	s_cselect_b32 s13, s21, s29
	s_cselect_b32 s23, s20, s28
	s_add_i32 s25, s55, -2
	s_add_u32 s26, s26, 0x100080
	s_addc_u32 s27, s27, 0
	s_add_u32 s56, s28, 0x100
	s_addc_u32 s57, s29, 0
	s_mov_b32 s28, 0
	v_add_u32_e32 v246, 0x18000, v179
	v_add_u32_e32 v248, 0x1c000, v179
	ds_read_b128 v[128:131], v181
	ds_read_b128 v[132:135], v181 offset:1024
	ds_read_b128 v[136:139], v181 offset:2048
	ds_read_b128 v[140:143], v181 offset:3072
	ds_read_b128 v[166:169], v182
	ds_read_b128 v[170:173], v182 offset:1024
	ds_read_b128 v[184:187], v182 offset:2048
	ds_read_b128 v[188:191], v182 offset:3072
	s_add_i32 s58, s28, 2
	s_add_u32 s29, s26, 0xfff00080
	s_addc_u32 s30, s27, -1
	s_cmp_eq_u32 s25, s28
	s_cselect_b32 s28, s23, s56
	s_cselect_b32 s31, s11, s30
	s_cselect_b32 s30, s15, s29
	s_cselect_b32 s29, s13, s57
	s_add_i32 m0, s37, 0xc000
	ds_read_b128 v[192:195], v183
	ds_read_b128 v[196:199], v183 offset:1024
	ds_read_b128 v[200:203], v183 offset:2048
	ds_read_b128 v[204:207], v183 offset:3072
	ds_read_b128 v[208:211], v183 offset:4096
	ds_read_b128 v[212:215], v183 offset:5120
	ds_read_b128 v[216:219], v183 offset:6144
	ds_read_b128 v[220:223], v183 offset:7168
	global_load_lds_dwordx4 v160, s[26:27]
	s_add_i32 m0, s37, 0xe000
	s_nop 0
	global_load_lds_dwordx4 v162, s[26:27]
	s_waitcnt vmcnt(8)
	s_waitcnt lgkmcnt(0)
	s_setprio 1
	s_barrier
	v_mfma_f32_16x16x32_bf16 v[60:63], v[128:131], v[192:195], 0
	v_mfma_f32_16x16x32_bf16 v[56:59], v[136:139], v[192:195], 0
	v_mfma_f32_16x16x32_bf16 v[44:47], v[128:131], v[200:203], 0
	v_mfma_f32_16x16x32_bf16 v[40:43], v[136:139], v[200:203], 0
	v_mfma_f32_16x16x32_bf16 v[28:31], v[128:131], v[208:211], 0
	v_mfma_f32_16x16x32_bf16 v[24:27], v[136:139], v[208:211], 0
	v_mfma_f32_16x16x32_bf16 v[12:15], v[128:131], v[216:219], 0
	v_mfma_f32_16x16x32_bf16 v[8:11], v[136:139], v[216:219], 0
	v_mfma_f32_16x16x32_bf16 v[60:63], v[132:135], v[196:199], v[60:63]
	v_mfma_f32_16x16x32_bf16 v[56:59], v[140:143], v[196:199], v[56:59]
	v_mfma_f32_16x16x32_bf16 v[44:47], v[132:135], v[204:207], v[44:47]
	v_mfma_f32_16x16x32_bf16 v[40:43], v[140:143], v[204:207], v[40:43]
	v_mfma_f32_16x16x32_bf16 v[28:31], v[132:135], v[212:215], v[28:31]
	v_mfma_f32_16x16x32_bf16 v[24:27], v[140:143], v[212:215], v[24:27]
	v_mfma_f32_16x16x32_bf16 v[12:15], v[132:135], v[220:223], v[12:15]
	v_mfma_f32_16x16x32_bf16 v[8:11], v[140:143], v[220:223], v[8:11]
	v_mfma_f32_16x16x32_bf16 v[52:55], v[166:169], v[192:195], 0
	v_mfma_f32_16x16x32_bf16 v[48:51], v[184:187], v[192:195], 0
	v_mfma_f32_16x16x32_bf16 v[36:39], v[166:169], v[200:203], 0
	v_mfma_f32_16x16x32_bf16 v[32:35], v[184:187], v[200:203], 0
	v_mfma_f32_16x16x32_bf16 v[20:23], v[166:169], v[208:211], 0
	v_mfma_f32_16x16x32_bf16 v[16:19], v[184:187], v[208:211], 0
	v_mfma_f32_16x16x32_bf16 v[4:7], v[166:169], v[216:219], 0
	v_mfma_f32_16x16x32_bf16 v[0:3], v[184:187], v[216:219], 0
	v_mfma_f32_16x16x32_bf16 v[52:55], v[170:173], v[196:199], v[52:55]
	v_mfma_f32_16x16x32_bf16 v[48:51], v[188:191], v[196:199], v[48:51]
	v_mfma_f32_16x16x32_bf16 v[36:39], v[170:173], v[204:207], v[36:39]
	v_mfma_f32_16x16x32_bf16 v[32:35], v[188:191], v[204:207], v[32:35]
	v_mfma_f32_16x16x32_bf16 v[20:23], v[170:173], v[212:215], v[20:23]
	v_mfma_f32_16x16x32_bf16 v[16:19], v[188:191], v[212:215], v[16:19]
	v_mfma_f32_16x16x32_bf16 v[4:7], v[170:173], v[220:223], v[4:7]
	v_mfma_f32_16x16x32_bf16 v[0:3], v[188:191], v[220:223], v[0:3]
	s_barrier
	s_setprio 0
	s_add_i32 s59, s48, s36
	s_mov_b32 m0, s59
	ds_read_b128 v[192:195], v183 offset:16384
	ds_read_b128 v[196:199], v183 offset:17408
	ds_read_b128 v[200:203], v183 offset:18432
	ds_read_b128 v[204:207], v183 offset:19456
	ds_read_b128 v[208:211], v183 offset:20480
	ds_read_b128 v[212:215], v183 offset:21504
	ds_read_b128 v[216:219], v183 offset:22528
	ds_read_b128 v[220:223], v183 offset:23552
	global_load_lds_dwordx4 v146, s[28:29]
	s_add_i32 m0, s59, 0x2000
	s_add_u32 s60, s28, 0x100000
	s_addc_u32 s61, s29, 0
	s_add_i32 s59, s49, s36
	global_load_lds_dwordx4 v150, s[28:29]
	s_mov_b32 m0, s59
	global_load_lds_dwordx4 v146, s[60:61]
	s_add_i32 m0, s59, 0x2000
	s_nop 0
	global_load_lds_dwordx4 v150, s[60:61]
	s_mov_b32 m0, s37
	s_nop 0
	global_load_lds_dwordx4 v144, s[30:31]
	s_mov_b32 m0, s38
	s_nop 0
	global_load_lds_dwordx4 v148, s[30:31]
	s_waitcnt vmcnt(8)
	s_waitcnt lgkmcnt(0)
	s_setprio 1
	s_barrier
; #define PG8_STAGE(bufoff, gbase, voff) do { _Pragma("unroll") for (int _i = 0; _i < 2; ++_i) \
;         __builtin_amdgcn_global_load_lds((const unsigned*)((const char*)(gbase) + (voff)[_i]), (PG8_LAS unsigned*)(lds + (bufoff) + ldsw + _i * 8192), 16, 0, 0); } while (0)
; #define PG8_LDA(dst, b, h) do { _Pragma("unroll") for (int m = 0; m < 4; ++m) _Pragma("unroll") for (int k = 0; k < 2; ++k) dst[m][k] = *(const PG8_LAS bf16x8*)(lds + PG8_SA(b, h) + aoff + m * 2048 + k * 1024); } while (0)
; #define PG8_LDB(dst, b, h) do { _Pragma("unroll") for (int n = 0; n < 2; ++n) _Pragma("unroll") for (int k = 0; k < 2; ++k) dst[n][k] = *(const PG8_LAS bf16x8*)(lds + PG8_SB(b, h) + boff + n * 2048 + k * 1024); } while (0)
; #define PG8_MMA(ai, bj, At, Bt) do { __builtin_amdgcn_s_setprio(1); _Pragma("unroll") for (int m = 0; m < 4; ++m) _Pragma("unroll") for (int n = 0; n < 2; ++n) _Pragma("unroll") for (int k = 0; k < 2; ++k) \
;         acc[ai][bj][m][n] = __builtin_amdgcn_mfma_f32_16x16x32_bf16(Bt[n][k], At[m][k], acc[ai][bj][m][n], 0, 0, 0); __builtin_amdgcn_s_setprio(0); } while (0)
; #define PG8_WAIT_V(n) asm volatile("s_waitcnt vmcnt(" #n ")" ::: "memory")
; #define PG8_WAIT_L(n) asm volatile("s_waitcnt lgkmcnt(" #n ")" ::: "memory")
; #define PG8_BAR __builtin_amdgcn_s_barrier()
; #define PG8_SCHED __builtin_amdgcn_sched_barrier(0)
; template <class Epi, class Sched, bool ALIGN_EPI = false, bool SP2 = false>
; __device__ __forceinline__ void gemm_phase(PG8_LAS unsigned char* lds, const Gemm g, const Sched& S, const Epi& E, const int wid) {
;     ...
;             PG8_WAIT_V(8); PG8_WAIT_L(0); PG8_BAR; PG8_MMA(1, 0, At, B0); PG8_MMA(1, 1, At, B1); PG8_BAR; PG8_SCHED;
;             PG8_LDB(B0, 1, 0); PG8_LDB(B1, 1, 1); PG8_SCHED; PG8_LDA(At, 1, 0); PG8_STAGE(PG8_SA(0, 1), a2 + hstep, voffA);
;             PG8_WAIT_V(8); PG8_WAIT_L(0); PG8_BAR; PG8_MMA(0, 0, At, B0); PG8_MMA(0, 1, At, B1); PG8_BAR; PG8_SCHED;
	v_mfma_f32_16x16x32_bf16 v[124:127], v[128:131], v[192:195], 0
	v_mfma_f32_16x16x32_bf16 v[120:123], v[136:139], v[192:195], 0
	v_mfma_f32_16x16x32_bf16 v[108:111], v[128:131], v[200:203], 0
	v_mfma_f32_16x16x32_bf16 v[104:107], v[136:139], v[200:203], 0
	v_mfma_f32_16x16x32_bf16 v[92:95], v[128:131], v[208:211], 0
	v_mfma_f32_16x16x32_bf16 v[88:91], v[136:139], v[208:211], 0
	v_mfma_f32_16x16x32_bf16 v[76:79], v[128:131], v[216:219], 0
	v_mfma_f32_16x16x32_bf16 v[72:75], v[136:139], v[216:219], 0
	v_mfma_f32_16x16x32_bf16 v[124:127], v[132:135], v[196:199], v[124:127]
	v_mfma_f32_16x16x32_bf16 v[120:123], v[140:143], v[196:199], v[120:123]
	v_mfma_f32_16x16x32_bf16 v[108:111], v[132:135], v[204:207], v[108:111]
	v_mfma_f32_16x16x32_bf16 v[104:107], v[140:143], v[204:207], v[104:107]
	v_mfma_f32_16x16x32_bf16 v[92:95], v[132:135], v[212:215], v[92:95]
	v_mfma_f32_16x16x32_bf16 v[88:91], v[140:143], v[212:215], v[88:91]
	v_mfma_f32_16x16x32_bf16 v[76:79], v[132:135], v[220:223], v[76:79]
	v_mfma_f32_16x16x32_bf16 v[72:75], v[140:143], v[220:223], v[72:75]
	v_mfma_f32_16x16x32_bf16 v[116:119], v[166:169], v[192:195], 0
	v_mfma_f32_16x16x32_bf16 v[112:115], v[184:187], v[192:195], 0
	v_mfma_f32_16x16x32_bf16 v[100:103], v[166:169], v[200:203], 0
	v_mfma_f32_16x16x32_bf16 v[96:99], v[184:187], v[200:203], 0
	v_mfma_f32_16x16x32_bf16 v[84:87], v[166:169], v[208:211], 0
	v_mfma_f32_16x16x32_bf16 v[80:83], v[184:187], v[208:211], 0
	v_mfma_f32_16x16x32_bf16 v[68:71], v[166:169], v[216:219], 0
	v_mfma_f32_16x16x32_bf16 v[64:67], v[184:187], v[216:219], 0
	v_mfma_f32_16x16x32_bf16 v[116:119], v[170:173], v[196:199], v[116:119]
	v_mfma_f32_16x16x32_bf16 v[112:115], v[188:191], v[196:199], v[112:115]
	v_mfma_f32_16x16x32_bf16 v[100:103], v[170:173], v[204:207], v[100:103]
	v_mfma_f32_16x16x32_bf16 v[96:99], v[188:191], v[204:207], v[96:99]
	v_mfma_f32_16x16x32_bf16 v[84:87], v[170:173], v[212:215], v[84:87]
	v_mfma_f32_16x16x32_bf16 v[80:83], v[188:191], v[212:215], v[80:83]
	v_mfma_f32_16x16x32_bf16 v[68:71], v[170:173], v[220:223], v[68:71]
	v_mfma_f32_16x16x32_bf16 v[64:67], v[188:191], v[220:223], v[64:67]
	s_barrier
	s_setprio 0
	s_add_i32 s59, 0, 0x18000
	s_add_i32 s60, 0, 0x1c000
	ds_read_b128 v[128:131], v246
	ds_read_b128 v[132:135], v246 offset:1024
	ds_read_b128 v[136:139], v246 offset:2048
	ds_read_b128 v[140:143], v246 offset:3072
	ds_read_b128 v[166:169], v248
	ds_read_b128 v[170:173], v248 offset:1024
	ds_read_b128 v[184:187], v248 offset:2048
	ds_read_b128 v[188:191], v248 offset:3072
	s_add_u32 s30, s30, 0x100000
	s_addc_u32 s31, s31, 0
	s_mov_b32 m0, s39
	ds_read_b128 v[192:195], v183 offset:32768
	ds_read_b128 v[196:199], v183 offset:33792
	ds_read_b128 v[200:203], v183 offset:34816
	ds_read_b128 v[204:207], v183 offset:35840
	ds_read_b128 v[208:211], v183 offset:36864
	ds_read_b128 v[212:215], v183 offset:37888
	ds_read_b128 v[216:219], v183 offset:38912
	ds_read_b128 v[220:223], v183 offset:39936
	global_load_lds_dwordx4 v144, s[30:31]
	s_mov_b32 m0, s40
	s_nop 0
	global_load_lds_dwordx4 v148, s[30:31]
	s_waitcnt vmcnt(8)
	s_waitcnt lgkmcnt(0)
	s_setprio 1
	s_barrier
	v_mfma_f32_16x16x32_bf16 v[60:63], v[128:131], v[192:195], v[60:63]
	v_mfma_f32_16x16x32_bf16 v[56:59], v[136:139], v[192:195], v[56:59]
	v_mfma_f32_16x16x32_bf16 v[44:47], v[128:131], v[200:203], v[44:47]
	v_mfma_f32_16x16x32_bf16 v[40:43], v[136:139], v[200:203], v[40:43]
	v_mfma_f32_16x16x32_bf16 v[28:31], v[128:131], v[208:211], v[28:31]
	v_mfma_f32_16x16x32_bf16 v[24:27], v[136:139], v[208:211], v[24:27]
	v_mfma_f32_16x16x32_bf16 v[12:15], v[128:131], v[216:219], v[12:15]
	v_mfma_f32_16x16x32_bf16 v[8:11], v[136:139], v[216:219], v[8:11]
	v_mfma_f32_16x16x32_bf16 v[60:63], v[132:135], v[196:199], v[60:63]
	v_mfma_f32_16x16x32_bf16 v[56:59], v[140:143], v[196:199], v[56:59]
	v_mfma_f32_16x16x32_bf16 v[44:47], v[132:135], v[204:207], v[44:47]
	v_mfma_f32_16x16x32_bf16 v[40:43], v[140:143], v[204:207], v[40:43]
	v_mfma_f32_16x16x32_bf16 v[28:31], v[132:135], v[212:215], v[28:31]
	v_mfma_f32_16x16x32_bf16 v[24:27], v[140:143], v[212:215], v[24:27]
	v_mfma_f32_16x16x32_bf16 v[12:15], v[132:135], v[220:223], v[12:15]
	v_mfma_f32_16x16x32_bf16 v[8:11], v[140:143], v[220:223], v[8:11]
	v_mfma_f32_16x16x32_bf16 v[52:55], v[166:169], v[192:195], v[52:55]
	v_mfma_f32_16x16x32_bf16 v[48:51], v[184:187], v[192:195], v[48:51]
	v_mfma_f32_16x16x32_bf16 v[36:39], v[166:169], v[200:203], v[36:39]
	v_mfma_f32_16x16x32_bf16 v[32:35], v[184:187], v[200:203], v[32:35]
	v_mfma_f32_16x16x32_bf16 v[20:23], v[166:169], v[208:211], v[20:23]
	v_mfma_f32_16x16x32_bf16 v[16:19], v[184:187], v[208:211], v[16:19]
	v_mfma_f32_16x16x32_bf16 v[4:7], v[166:169], v[216:219], v[4:7]
	v_mfma_f32_16x16x32_bf16 v[0:3], v[184:187], v[216:219], v[0:3]
	v_mfma_f32_16x16x32_bf16 v[52:55], v[170:173], v[196:199], v[52:55]
	v_mfma_f32_16x16x32_bf16 v[48:51], v[188:191], v[196:199], v[48:51]
	v_mfma_f32_16x16x32_bf16 v[36:39], v[170:173], v[204:207], v[36:39]
	v_mfma_f32_16x16x32_bf16 v[32:35], v[188:191], v[204:207], v[32:35]
	v_mfma_f32_16x16x32_bf16 v[20:23], v[170:173], v[212:215], v[20:23]
	v_mfma_f32_16x16x32_bf16 v[16:19], v[188:191], v[212:215], v[16:19]
	v_mfma_f32_16x16x32_bf16 v[4:7], v[170:173], v[220:223], v[4:7]
	v_mfma_f32_16x16x32_bf16 v[0:3], v[188:191], v[220:223], v[0:3]
	s_barrier
; #define PG8_STAGE(bufoff, gbase, voff) do { _Pragma("unroll") for (int _i = 0; _i < 2; ++_i) \
;         __builtin_amdgcn_global_load_lds((const unsigned*)((const char*)(gbase) + (voff)[_i]), (PG8_LAS unsigned*)(lds + (bufoff) + ldsw + _i * 8192), 16, 0, 0); } while (0)
; #define PG8_LDA(dst, b, h) do { _Pragma("unroll") for (int m = 0; m < 4; ++m) _Pragma("unroll") for (int k = 0; k < 2; ++k) dst[m][k] = *(const PG8_LAS bf16x8*)(lds + PG8_SA(b, h) + aoff + m * 2048 + k * 1024); } while (0)
; #define PG8_MMA(ai, bj, At, Bt) do { __builtin_amdgcn_s_setprio(1); _Pragma("unroll") for (int m = 0; m < 4; ++m) _Pragma("unroll") for (int n = 0; n < 2; ++n) _Pragma("unroll") for (int k = 0; k < 2; ++k) \
;         acc[ai][bj][m][n] = __builtin_amdgcn_mfma_f32_16x16x32_bf16(Bt[n][k], At[m][k], acc[ai][bj][m][n], 0, 0, 0); __builtin_amdgcn_s_setprio(0); } while (0)
; #define PG8_WAIT_V(n) asm volatile("s_waitcnt vmcnt(" #n ")" ::: "memory")
; #define PG8_WAIT_L(n) asm volatile("s_waitcnt lgkmcnt(" #n ")" ::: "memory")
; #define PG8_BAR __builtin_amdgcn_s_barrier()
; #define PG8_SCHED __builtin_amdgcn_sched_barrier(0)
; template <class Epi, class Sched, bool ALIGN_EPI = false, bool SP2 = false>
; __device__ __forceinline__ void gemm_phase(PG8_LAS unsigned char* lds, const Gemm g, const Sched& S, const Epi& E, const int wid) {
;     ...
;         for (int t = 0; t < nt; t += 2) {
;     ...
;             PG8_LDA(At, 1, 1); PG8_STAGE(PG8_SB(1, 0), b3, voffB); PG8_STAGE(PG8_SB(1, 1), b3 + hstep, voffB); PG8_STAGE(PG8_SA(1, 0), a3, voffA);
;             PG8_WAIT_V(8); PG8_WAIT_L(0); PG8_BAR; PG8_MMA(1, 0, At, B0); PG8_MMA(1, 1, At, B1); PG8_BAR; PG8_SCHED;
	s_setprio 0
	s_add_u32 s98, s28, 0x80
	s_addc_u32 s99, s29, 0
	s_add_u32 s100, s30, 0xfff00080
	s_addc_u32 s101, s31, -1
	s_add_i32 s30, s59, s36
	s_mov_b32 m0, s30
	ds_read_b128 v[192:195], v183 offset:49152
	ds_read_b128 v[196:199], v183 offset:50176
	ds_read_b128 v[200:203], v183 offset:51200
	ds_read_b128 v[204:207], v183 offset:52224
	ds_read_b128 v[208:211], v183 offset:53248
	ds_read_b128 v[212:215], v183 offset:54272
	ds_read_b128 v[216:219], v183 offset:55296
	ds_read_b128 v[220:223], v183 offset:56320
	global_load_lds_dwordx4 v146, s[98:99]
	s_add_i32 m0, s30, 0x2000
	s_add_u32 s28, s28, 0x100080
	s_addc_u32 s29, s29, 0
	s_add_i32 s30, s60, s36
	global_load_lds_dwordx4 v150, s[98:99]
	s_mov_b32 m0, s30
	s_nop 0
	global_load_lds_dwordx4 v146, s[28:29]
	s_add_i32 m0, s30, 0x2000
	s_nop 0
	global_load_lds_dwordx4 v150, s[28:29]
	s_mov_b32 m0, s42
	s_nop 0
	global_load_lds_dwordx4 v144, s[100:101]
	s_mov_b32 m0, s43
	s_nop 0
	global_load_lds_dwordx4 v148, s[100:101]
	s_waitcnt vmcnt(8)
	s_waitcnt lgkmcnt(0)
	s_setprio 1
	s_barrier
	v_mfma_f32_16x16x32_bf16 v[124:127], v[128:131], v[192:195], v[124:127]
	v_mfma_f32_16x16x32_bf16 v[120:123], v[136:139], v[192:195], v[120:123]
	v_mfma_f32_16x16x32_bf16 v[108:111], v[128:131], v[200:203], v[108:111]
	v_mfma_f32_16x16x32_bf16 v[104:107], v[136:139], v[200:203], v[104:107]
	v_mfma_f32_16x16x32_bf16 v[92:95], v[128:131], v[208:211], v[92:95]
	v_mfma_f32_16x16x32_bf16 v[88:91], v[136:139], v[208:211], v[88:91]
	v_mfma_f32_16x16x32_bf16 v[76:79], v[128:131], v[216:219], v[76:79]
	v_mfma_f32_16x16x32_bf16 v[72:75], v[136:139], v[216:219], v[72:75]
	v_mfma_f32_16x16x32_bf16 v[124:127], v[132:135], v[196:199], v[124:127]
	v_mfma_f32_16x16x32_bf16 v[120:123], v[140:143], v[196:199], v[120:123]
	v_mfma_f32_16x16x32_bf16 v[108:111], v[132:135], v[204:207], v[108:111]
	v_mfma_f32_16x16x32_bf16 v[104:107], v[140:143], v[204:207], v[104:107]
	v_mfma_f32_16x16x32_bf16 v[92:95], v[132:135], v[212:215], v[92:95]
	v_mfma_f32_16x16x32_bf16 v[88:91], v[140:143], v[212:215], v[88:91]
	v_mfma_f32_16x16x32_bf16 v[76:79], v[132:135], v[220:223], v[76:79]
	v_mfma_f32_16x16x32_bf16 v[72:75], v[140:143], v[220:223], v[72:75]
	v_mfma_f32_16x16x32_bf16 v[116:119], v[166:169], v[192:195], v[116:119]
	v_mfma_f32_16x16x32_bf16 v[112:115], v[184:187], v[192:195], v[112:115]
	v_mfma_f32_16x16x32_bf16 v[100:103], v[166:169], v[200:203], v[100:103]
	v_mfma_f32_16x16x32_bf16 v[96:99], v[184:187], v[200:203], v[96:99]
	v_mfma_f32_16x16x32_bf16 v[84:87], v[166:169], v[208:211], v[84:87]
	v_mfma_f32_16x16x32_bf16 v[80:83], v[184:187], v[208:211], v[80:83]
	v_mfma_f32_16x16x32_bf16 v[68:71], v[166:169], v[216:219], v[68:71]
	v_mfma_f32_16x16x32_bf16 v[64:67], v[184:187], v[216:219], v[64:67]
	v_mfma_f32_16x16x32_bf16 v[116:119], v[170:173], v[196:199], v[116:119]
	v_mfma_f32_16x16x32_bf16 v[112:115], v[188:191], v[196:199], v[112:115]
	v_mfma_f32_16x16x32_bf16 v[100:103], v[170:173], v[204:207], v[100:103]
	v_mfma_f32_16x16x32_bf16 v[96:99], v[188:191], v[204:207], v[96:99]
	v_mfma_f32_16x16x32_bf16 v[84:87], v[170:173], v[212:215], v[84:87]
	v_mfma_f32_16x16x32_bf16 v[80:83], v[188:191], v[212:215], v[80:83]
	v_mfma_f32_16x16x32_bf16 v[68:71], v[170:173], v[220:223], v[68:71]
	v_mfma_f32_16x16x32_bf16 v[64:67], v[188:191], v[220:223], v[64:67]
	s_barrier
	s_setprio 0
	s_add_u32 s26, s26, 0x100
	s_addc_u32 s27, s27, 0
	s_add_u32 s56, s56, 0x100
	s_addc_u32 s57, s57, 0
	s_cmp_ge_i32 s58, s55
	s_mov_b32 s28, s58
	s_cbranch_scc0 .LBB0_843
	s_branch .Lpeel_exit_1

; #define PG8_BAR __builtin_amdgcn_s_barrier()
; template <class Epi, class Sched, bool ALIGN_EPI = false, bool SP2 = false>
; __device__ __forceinline__ void gemm_phase(PG8_LAS unsigned char* lds, const Gemm g, const Sched& S, const Epi& E, const int wid) {
;     ...
;         if constexpr (ALIGN_EPI) { if (wr == 0) PG8_BAR; }
;         if constexpr (!Epi::AFTER_DRAIN) { E(acc, cur, wr, wc, fr, fq); S.done(cur); }
.Lpeel_exit_1:
	s_and_b64 vcc, exec, s[8:9]
	s_cbranch_vccz .LBB0_846
	s_barrier

; __device__ __forceinline__ float row_rstd(const u64* ssq, int r) { return __builtin_amdgcn_rsqf(fx_to_pos(ssq[r]) * (1.0f / 4096.0f) + RMS_EPS); }
; #define PG8_STAGE(bufoff, gbase, voff) do { _Pragma("unroll") for (int _i = 0; _i < 2; ++_i) \
;         __builtin_amdgcn_global_load_lds((const unsigned*)((const char*)(gbase) + (voff)[_i]), (PG8_LAS unsigned*)(lds + (bufoff) + ldsw + _i * 8192), 16, 0, 0); } while (0)
; #define PG8_LDA(dst, b, h) do { _Pragma("unroll") for (int m = 0; m < 4; ++m) _Pragma("unroll") for (int k = 0; k < 2; ++k) dst[m][k] = *(const PG8_LAS bf16x8*)(lds + PG8_SA(b, h) + aoff + m * 2048 + k * 1024); } while (0)
; #define PG8_LDB(dst, b, h) do { _Pragma("unroll") for (int n = 0; n < 2; ++n) _Pragma("unroll") for (int k = 0; k < 2; ++k) dst[n][k] = *(const PG8_LAS bf16x8*)(lds + PG8_SB(b, h) + boff + n * 2048 + k * 1024); } while (0)
; #define PG8_WAIT_V(n) asm volatile("s_waitcnt vmcnt(" #n ")" ::: "memory")
; #define PG8_WAIT_L(n) asm volatile("s_waitcnt lgkmcnt(" #n ")" ::: "memory")
;     __device__ __forceinline__ void operator()(const f32x4 (&acc)[2][2][4][2], const Unit& u, int wr, int wc, int fr, int fq) const {
;     ...
;             for (int m = 0; m < 4; ++m) { const int r = row0 + ai * HALF + m * 16; const float rs = row_rstd(ssq, r); f32x4 o[2];
; template <class Epi, class Sched, bool ALIGN_EPI = false, bool SP2 = false>
; __device__ __forceinline__ void gemm_phase(PG8_LAS unsigned char* lds, const Gemm g, const Sched& S, const Epi& E, const int wid) {
;     ...
;             const char* a1 = cA + (size_t)(t + 1) * kstep;
;             const char* a2 = last ? nA : cA + (size_t)(t + 2) * kstep; const char* b2 = last ? nB : cB + (size_t)(t + 2) * kstep;
;             const char* a3 = a2 + kstep; const char* b3 = b2 + kstep;
;             if (last && has_next) S.a_ready(nxt);
;             if constexpr (SP2) {
;             PG8_LDB(B0, 0, 0); PG8_LDB(B1, 0, 1); PG8_SCHED; PG8_LDA(At, 0, 0); PG8_STAGE(PG8_SA(1, 1), a1 + hstep, voffA);
;             PG8_WAIT_V(8); PG8_WAIT_L(0); PG8_BAR; PG8_MMA(0, 0, At, B0); PG8_MMA(0, 1, At, B1); PG8_BAR; PG8_SCHED;
;             PG8_LDA(At, 0, 1); PG8_STAGE(PG8_SB(0, 0), b2, voffB); PG8_STAGE(PG8_SB(0, 1), b2 + hstep, voffB); PG8_STAGE(PG8_SA(0, 0), a2, voffA);
;             PG8_WAIT_V(8); PG8_WAIT_L(0); PG8_BAR; PG8_MMA(1, 0, At, B0); PG8_MMA(1, 1, At, B1); PG8_BAR; PG8_SCHED;
.LBB0_962:
	s_ashr_i32 s15, s14, 31
	s_lshl_b64 s[16:17], s[14:15], 21
	s_add_u32 s16, s78, s16
	s_addc_u32 s17, s79, s17
	s_and_b64 s[18:19], s[0:1], exec
	s_cselect_b32 s15, s17, s23
	s_cselect_b32 s48, s16, s22
	s_ashr_i32 s13, s12, 31
	s_lshl_b64 s[18:19], s[12:13], 21
	s_add_u32 s18, s30, s18
	s_addc_u32 s19, s31, s19
	s_and_b64 s[26:27], s[0:1], exec
	s_cselect_b32 s13, s19, s25
	s_cselect_b32 s49, s18, s24
	s_add_u32 s22, s22, 0x100080
	s_addc_u32 s23, s23, 0
	s_add_u32 s50, s24, 0x100
	s_addc_u32 s51, s25, 0
	s_mov_b32 s52, -2
	v_add_u32_e32 v246, 0x18000, v152
	v_add_u32_e32 v248, 0x1c000, v152
	ds_read_b128 v[146:149], v154
	ds_read_b128 v[158:161], v154 offset:1024
	ds_read_b128 v[162:165], v154 offset:2048
	ds_read_b128 v[166:169], v154 offset:3072
	ds_read_b128 v[170:173], v155
	ds_read_b128 v[174:177], v155 offset:1024
	ds_read_b128 v[178:181], v155 offset:2048
	ds_read_b128 v[182:185], v155 offset:3072
	s_add_u32 s24, s22, 0xfff00080
	s_addc_u32 s25, s23, -1
	s_cmp_eq_u32 s52, 60
	s_cselect_b32 s27, s15, s25
	s_cselect_b32 s26, s48, s24
	s_cselect_b32 s25, s13, s51
	s_cselect_b32 s24, s49, s50
	s_add_i32 m0, s21, 0xc000
	ds_read_b128 v[186:189], v156
	ds_read_b128 v[190:193], v156 offset:1024
	ds_read_b128 v[194:197], v156 offset:2048
	ds_read_b128 v[198:201], v156 offset:3072
	ds_read_b128 v[202:205], v156 offset:4096
	ds_read_b128 v[206:209], v156 offset:5120
	ds_read_b128 v[210:213], v156 offset:6144
	ds_read_b128 v[214:217], v156 offset:7168
	global_load_lds_dwordx4 v138, s[22:23]
	s_add_i32 m0, s21, 0xe000
	s_nop 0
	global_load_lds_dwordx4 v140, s[22:23]
	s_waitcnt vmcnt(8)
	s_waitcnt lgkmcnt(0)
	v_lshl_add_u32 v244, s20, 8, v151
	v_ashrrev_i32_e32 v245, 31, v244
	v_lshl_add_u64 v[244:245], v[244:245], 3, s[2:3]
	global_load_dwordx2 v[228:229], v[244:245], off
	global_load_dwordx2 v[230:231], v[244:245], off offset:128
	global_load_dwordx2 v[232:233], v[244:245], off offset:256
	global_load_dwordx2 v[234:235], v[244:245], off offset:384
	global_load_dwordx2 v[236:237], v[244:245], off offset:1024
	global_load_dwordx2 v[238:239], v[244:245], off offset:1152
	global_load_dwordx2 v[240:241], v[244:245], off offset:1280
	global_load_dwordx2 v[242:243], v[244:245], off offset:1408
	s_setprio 1
	s_barrier
	v_mfma_f32_16x16x32_bf16 v[124:127], v[146:149], v[186:189], 0
	v_mfma_f32_16x16x32_bf16 v[120:123], v[162:165], v[186:189], 0
	v_mfma_f32_16x16x32_bf16 v[108:111], v[146:149], v[194:197], 0
	v_mfma_f32_16x16x32_bf16 v[104:107], v[162:165], v[194:197], 0
	v_mfma_f32_16x16x32_bf16 v[92:95], v[146:149], v[202:205], 0
	v_mfma_f32_16x16x32_bf16 v[88:91], v[162:165], v[202:205], 0
	v_mfma_f32_16x16x32_bf16 v[76:79], v[146:149], v[210:213], 0
	v_mfma_f32_16x16x32_bf16 v[72:75], v[162:165], v[210:213], 0
	v_mfma_f32_16x16x32_bf16 v[124:127], v[158:161], v[190:193], v[124:127]
	v_mfma_f32_16x16x32_bf16 v[120:123], v[166:169], v[190:193], v[120:123]
	v_mfma_f32_16x16x32_bf16 v[108:111], v[158:161], v[198:201], v[108:111]
	v_mfma_f32_16x16x32_bf16 v[104:107], v[166:169], v[198:201], v[104:107]
	v_mfma_f32_16x16x32_bf16 v[92:95], v[158:161], v[206:209], v[92:95]
	v_mfma_f32_16x16x32_bf16 v[88:91], v[166:169], v[206:209], v[88:91]
	v_mfma_f32_16x16x32_bf16 v[76:79], v[158:161], v[214:217], v[76:79]
	v_mfma_f32_16x16x32_bf16 v[72:75], v[166:169], v[214:217], v[72:75]
	v_mfma_f32_16x16x32_bf16 v[116:119], v[170:173], v[186:189], 0
	v_mfma_f32_16x16x32_bf16 v[112:115], v[178:181], v[186:189], 0
	v_mfma_f32_16x16x32_bf16 v[100:103], v[170:173], v[194:197], 0
	v_mfma_f32_16x16x32_bf16 v[96:99], v[178:181], v[194:197], 0
	v_mfma_f32_16x16x32_bf16 v[84:87], v[170:173], v[202:205], 0
	v_mfma_f32_16x16x32_bf16 v[80:83], v[178:181], v[202:205], 0
	v_mfma_f32_16x16x32_bf16 v[68:71], v[170:173], v[210:213], 0
	v_mfma_f32_16x16x32_bf16 v[64:67], v[178:181], v[210:213], 0
	v_mfma_f32_16x16x32_bf16 v[116:119], v[174:177], v[190:193], v[116:119]
	v_mfma_f32_16x16x32_bf16 v[112:115], v[182:185], v[190:193], v[112:115]
	v_mfma_f32_16x16x32_bf16 v[100:103], v[174:177], v[198:201], v[100:103]
	v_mfma_f32_16x16x32_bf16 v[96:99], v[182:185], v[198:201], v[96:99]
	v_mfma_f32_16x16x32_bf16 v[84:87], v[174:177], v[206:209], v[84:87]
	v_mfma_f32_16x16x32_bf16 v[80:83], v[182:185], v[206:209], v[80:83]
	v_mfma_f32_16x16x32_bf16 v[68:71], v[174:177], v[214:217], v[68:71]
	v_mfma_f32_16x16x32_bf16 v[64:67], v[182:185], v[214:217], v[64:67]
	s_barrier
	s_setprio 0
	s_add_i32 s53, s41, s29
	s_mov_b32 m0, s53
	ds_read_b128 v[186:189], v156 offset:16384
	ds_read_b128 v[190:193], v156 offset:17408
	ds_read_b128 v[194:197], v156 offset:18432
	ds_read_b128 v[198:201], v156 offset:19456
	ds_read_b128 v[202:205], v156 offset:20480
	ds_read_b128 v[206:209], v156 offset:21504
	ds_read_b128 v[210:213], v156 offset:22528
	ds_read_b128 v[214:217], v156 offset:23552
	global_load_lds_dwordx4 v130, s[24:25]
	s_add_i32 m0, s53, 0x2000
	s_add_u32 s54, s24, 0x100000
	s_addc_u32 s55, s25, 0
	s_add_i32 s53, s42, s29
	global_load_lds_dwordx4 v134, s[24:25]
	s_mov_b32 m0, s53
	global_load_lds_dwordx4 v130, s[54:55]
	s_add_i32 m0, s53, 0x2000
	s_nop 0
	global_load_lds_dwordx4 v134, s[54:55]
	s_mov_b32 m0, s21
	s_nop 0
	global_load_lds_dwordx4 v128, s[26:27]
	s_mov_b32 m0, s34
	s_nop 0
	global_load_lds_dwordx4 v132, s[26:27]
	s_waitcnt vmcnt(8)
	s_waitcnt lgkmcnt(0)
	s_setprio 1
	s_barrier
; #define PG8_STAGE(bufoff, gbase, voff) do { _Pragma("unroll") for (int _i = 0; _i < 2; ++_i) \
;         __builtin_amdgcn_global_load_lds((const unsigned*)((const char*)(gbase) + (voff)[_i]), (PG8_LAS unsigned*)(lds + (bufoff) + ldsw + _i * 8192), 16, 0, 0); } while (0)
; #define PG8_LDA(dst, b, h) do { _Pragma("unroll") for (int m = 0; m < 4; ++m) _Pragma("unroll") for (int k = 0; k < 2; ++k) dst[m][k] = *(const PG8_LAS bf16x8*)(lds + PG8_SA(b, h) + aoff + m * 2048 + k * 1024); } while (0)
; #define PG8_LDB(dst, b, h) do { _Pragma("unroll") for (int n = 0; n < 2; ++n) _Pragma("unroll") for (int k = 0; k < 2; ++k) dst[n][k] = *(const PG8_LAS bf16x8*)(lds + PG8_SB(b, h) + boff + n * 2048 + k * 1024); } while (0)
; #define PG8_MMA(ai, bj, At, Bt) do { __builtin_amdgcn_s_setprio(1); _Pragma("unroll") for (int m = 0; m < 4; ++m) _Pragma("unroll") for (int n = 0; n < 2; ++n) _Pragma("unroll") for (int k = 0; k < 2; ++k) \
;         acc[ai][bj][m][n] = __builtin_amdgcn_mfma_f32_16x16x32_bf16(Bt[n][k], At[m][k], acc[ai][bj][m][n], 0, 0, 0); __builtin_amdgcn_s_setprio(0); } while (0)
; #define PG8_WAIT_V(n) asm volatile("s_waitcnt vmcnt(" #n ")" ::: "memory")
; #define PG8_WAIT_L(n) asm volatile("s_waitcnt lgkmcnt(" #n ")" ::: "memory")
; #define PG8_BAR __builtin_amdgcn_s_barrier()
; #define PG8_SCHED __builtin_amdgcn_sched_barrier(0)
; template <class Epi, class Sched, bool ALIGN_EPI = false, bool SP2 = false>
; __device__ __forceinline__ void gemm_phase(PG8_LAS unsigned char* lds, const Gemm g, const Sched& S, const Epi& E, const int wid) {
;     ...
;             PG8_WAIT_V(8); PG8_WAIT_L(0); PG8_BAR; PG8_MMA(1, 0, At, B0); PG8_MMA(1, 1, At, B1); PG8_BAR; PG8_SCHED;
;             PG8_LDB(B0, 1, 0); PG8_LDB(B1, 1, 1); PG8_SCHED; PG8_LDA(At, 1, 0); PG8_STAGE(PG8_SA(0, 1), a2 + hstep, voffA);
;             PG8_WAIT_V(8); PG8_WAIT_L(0); PG8_BAR; PG8_MMA(0, 0, At, B0); PG8_MMA(0, 1, At, B1); PG8_BAR; PG8_SCHED;
	v_mfma_f32_16x16x32_bf16 v[60:63], v[146:149], v[186:189], 0
	v_mfma_f32_16x16x32_bf16 v[56:59], v[162:165], v[186:189], 0
	v_mfma_f32_16x16x32_bf16 v[44:47], v[146:149], v[194:197], 0
	v_mfma_f32_16x16x32_bf16 v[40:43], v[162:165], v[194:197], 0
	v_mfma_f32_16x16x32_bf16 v[28:31], v[146:149], v[202:205], 0
	v_mfma_f32_16x16x32_bf16 v[24:27], v[162:165], v[202:205], 0
	v_mfma_f32_16x16x32_bf16 v[12:15], v[146:149], v[210:213], 0
	v_mfma_f32_16x16x32_bf16 v[8:11], v[162:165], v[210:213], 0
	v_mfma_f32_16x16x32_bf16 v[60:63], v[158:161], v[190:193], v[60:63]
	v_mfma_f32_16x16x32_bf16 v[56:59], v[166:169], v[190:193], v[56:59]
	v_mfma_f32_16x16x32_bf16 v[44:47], v[158:161], v[198:201], v[44:47]
	v_mfma_f32_16x16x32_bf16 v[40:43], v[166:169], v[198:201], v[40:43]
	v_mfma_f32_16x16x32_bf16 v[28:31], v[158:161], v[206:209], v[28:31]
	v_mfma_f32_16x16x32_bf16 v[24:27], v[166:169], v[206:209], v[24:27]
	v_mfma_f32_16x16x32_bf16 v[12:15], v[158:161], v[214:217], v[12:15]
	v_mfma_f32_16x16x32_bf16 v[8:11], v[166:169], v[214:217], v[8:11]
	v_mfma_f32_16x16x32_bf16 v[52:55], v[170:173], v[186:189], 0
	v_mfma_f32_16x16x32_bf16 v[48:51], v[178:181], v[186:189], 0
	v_mfma_f32_16x16x32_bf16 v[36:39], v[170:173], v[194:197], 0
	v_mfma_f32_16x16x32_bf16 v[32:35], v[178:181], v[194:197], 0
	v_mfma_f32_16x16x32_bf16 v[20:23], v[170:173], v[202:205], 0
	v_mfma_f32_16x16x32_bf16 v[16:19], v[178:181], v[202:205], 0
	v_mfma_f32_16x16x32_bf16 v[4:7], v[170:173], v[210:213], 0
	v_mfma_f32_16x16x32_bf16 v[0:3], v[178:181], v[210:213], 0
	v_mfma_f32_16x16x32_bf16 v[52:55], v[174:177], v[190:193], v[52:55]
	v_mfma_f32_16x16x32_bf16 v[48:51], v[182:185], v[190:193], v[48:51]
	v_mfma_f32_16x16x32_bf16 v[36:39], v[174:177], v[198:201], v[36:39]
	v_mfma_f32_16x16x32_bf16 v[32:35], v[182:185], v[198:201], v[32:35]
	v_mfma_f32_16x16x32_bf16 v[20:23], v[174:177], v[206:209], v[20:23]
	v_mfma_f32_16x16x32_bf16 v[16:19], v[182:185], v[206:209], v[16:19]
	v_mfma_f32_16x16x32_bf16 v[4:7], v[174:177], v[214:217], v[4:7]
	v_mfma_f32_16x16x32_bf16 v[0:3], v[182:185], v[214:217], v[0:3]
	s_barrier
	s_setprio 0
	s_add_i32 s53, 0, 0x18000
	s_add_i32 s54, 0, 0x1c000
	ds_read_b128 v[146:149], v246
	ds_read_b128 v[158:161], v246 offset:1024
	ds_read_b128 v[162:165], v246 offset:2048
	ds_read_b128 v[166:169], v246 offset:3072
	ds_read_b128 v[170:173], v248
	ds_read_b128 v[174:177], v248 offset:1024
	ds_read_b128 v[178:181], v248 offset:2048
	ds_read_b128 v[182:185], v248 offset:3072
	s_add_u32 s26, s26, 0x100000
	s_addc_u32 s27, s27, 0
	s_mov_b32 m0, s35
	ds_read_b128 v[186:189], v156 offset:32768
	ds_read_b128 v[190:193], v156 offset:33792
	ds_read_b128 v[194:197], v156 offset:34816
	ds_read_b128 v[198:201], v156 offset:35840
	ds_read_b128 v[202:205], v156 offset:36864
	ds_read_b128 v[206:209], v156 offset:37888
	ds_read_b128 v[210:213], v156 offset:38912
	ds_read_b128 v[214:217], v156 offset:39936
	global_load_lds_dwordx4 v128, s[26:27]
	s_mov_b32 m0, s36
	s_nop 0
	global_load_lds_dwordx4 v132, s[26:27]
	s_waitcnt vmcnt(8)
	s_waitcnt lgkmcnt(0)
	s_setprio 1
	s_barrier
	v_mfma_f32_16x16x32_bf16 v[124:127], v[146:149], v[186:189], v[124:127]
	v_mfma_f32_16x16x32_bf16 v[120:123], v[162:165], v[186:189], v[120:123]
	v_mfma_f32_16x16x32_bf16 v[108:111], v[146:149], v[194:197], v[108:111]
	v_mfma_f32_16x16x32_bf16 v[104:107], v[162:165], v[194:197], v[104:107]
	v_mfma_f32_16x16x32_bf16 v[92:95], v[146:149], v[202:205], v[92:95]
	v_mfma_f32_16x16x32_bf16 v[88:91], v[162:165], v[202:205], v[88:91]
	v_mfma_f32_16x16x32_bf16 v[76:79], v[146:149], v[210:213], v[76:79]
	v_mfma_f32_16x16x32_bf16 v[72:75], v[162:165], v[210:213], v[72:75]
	v_mfma_f32_16x16x32_bf16 v[124:127], v[158:161], v[190:193], v[124:127]
	v_mfma_f32_16x16x32_bf16 v[120:123], v[166:169], v[190:193], v[120:123]
	v_mfma_f32_16x16x32_bf16 v[108:111], v[158:161], v[198:201], v[108:111]
	v_mfma_f32_16x16x32_bf16 v[104:107], v[166:169], v[198:201], v[104:107]
	v_mfma_f32_16x16x32_bf16 v[92:95], v[158:161], v[206:209], v[92:95]
	v_mfma_f32_16x16x32_bf16 v[88:91], v[166:169], v[206:209], v[88:91]
	v_mfma_f32_16x16x32_bf16 v[76:79], v[158:161], v[214:217], v[76:79]
	v_mfma_f32_16x16x32_bf16 v[72:75], v[166:169], v[214:217], v[72:75]
	v_mfma_f32_16x16x32_bf16 v[116:119], v[170:173], v[186:189], v[116:119]
	v_mfma_f32_16x16x32_bf16 v[112:115], v[178:181], v[186:189], v[112:115]
	v_mfma_f32_16x16x32_bf16 v[100:103], v[170:173], v[194:197], v[100:103]
	v_mfma_f32_16x16x32_bf16 v[96:99], v[178:181], v[194:197], v[96:99]
	v_mfma_f32_16x16x32_bf16 v[84:87], v[170:173], v[202:205], v[84:87]
	v_mfma_f32_16x16x32_bf16 v[80:83], v[178:181], v[202:205], v[80:83]
	v_mfma_f32_16x16x32_bf16 v[68:71], v[170:173], v[210:213], v[68:71]
	v_mfma_f32_16x16x32_bf16 v[64:67], v[178:181], v[210:213], v[64:67]
	v_mfma_f32_16x16x32_bf16 v[116:119], v[174:177], v[190:193], v[116:119]
	v_mfma_f32_16x16x32_bf16 v[112:115], v[182:185], v[190:193], v[112:115]
	v_mfma_f32_16x16x32_bf16 v[100:103], v[174:177], v[198:201], v[100:103]
	v_mfma_f32_16x16x32_bf16 v[96:99], v[182:185], v[198:201], v[96:99]
	v_mfma_f32_16x16x32_bf16 v[84:87], v[174:177], v[206:209], v[84:87]
	v_mfma_f32_16x16x32_bf16 v[80:83], v[182:185], v[206:209], v[80:83]
	v_mfma_f32_16x16x32_bf16 v[68:71], v[174:177], v[214:217], v[68:71]
	v_mfma_f32_16x16x32_bf16 v[64:67], v[182:185], v[214:217], v[64:67]
	s_barrier
; #define PG8_STAGE(bufoff, gbase, voff) do { _Pragma("unroll") for (int _i = 0; _i < 2; ++_i) \
;         __builtin_amdgcn_global_load_lds((const unsigned*)((const char*)(gbase) + (voff)[_i]), (PG8_LAS unsigned*)(lds + (bufoff) + ldsw + _i * 8192), 16, 0, 0); } while (0)
; #define PG8_LDA(dst, b, h) do { _Pragma("unroll") for (int m = 0; m < 4; ++m) _Pragma("unroll") for (int k = 0; k < 2; ++k) dst[m][k] = *(const PG8_LAS bf16x8*)(lds + PG8_SA(b, h) + aoff + m * 2048 + k * 1024); } while (0)
; #define PG8_MMA(ai, bj, At, Bt) do { __builtin_amdgcn_s_setprio(1); _Pragma("unroll") for (int m = 0; m < 4; ++m) _Pragma("unroll") for (int n = 0; n < 2; ++n) _Pragma("unroll") for (int k = 0; k < 2; ++k) \
;         acc[ai][bj][m][n] = __builtin_amdgcn_mfma_f32_16x16x32_bf16(Bt[n][k], At[m][k], acc[ai][bj][m][n], 0, 0, 0); __builtin_amdgcn_s_setprio(0); } while (0)
; #define PG8_WAIT_V(n) asm volatile("s_waitcnt vmcnt(" #n ")" ::: "memory")
; #define PG8_WAIT_L(n) asm volatile("s_waitcnt lgkmcnt(" #n ")" ::: "memory")
; #define PG8_BAR __builtin_amdgcn_s_barrier()
; #define PG8_SCHED __builtin_amdgcn_sched_barrier(0)
; template <class Epi, class Sched, bool ALIGN_EPI = false, bool SP2 = false>
; __device__ __forceinline__ void gemm_phase(PG8_LAS unsigned char* lds, const Gemm g, const Sched& S, const Epi& E, const int wid) {
;     ...
;         for (int t = 0; t < nt; t += 2) {
;     ...
;             PG8_LDA(At, 1, 1); PG8_STAGE(PG8_SB(1, 0), b3, voffB); PG8_STAGE(PG8_SB(1, 1), b3 + hstep, voffB); PG8_STAGE(PG8_SA(1, 0), a3, voffA);
;             PG8_WAIT_V(8); PG8_WAIT_L(0); PG8_BAR; PG8_MMA(1, 0, At, B0); PG8_MMA(1, 1, At, B1); PG8_BAR; PG8_SCHED;
	s_setprio 0
	s_add_u32 s98, s24, 0x80
	s_addc_u32 s99, s25, 0
	s_add_u32 s100, s26, 0xfff00080
	s_addc_u32 s101, s27, -1
	s_add_i32 s26, s53, s29
	s_mov_b32 m0, s26
	ds_read_b128 v[186:189], v156 offset:49152
	ds_read_b128 v[190:193], v156 offset:50176
	ds_read_b128 v[194:197], v156 offset:51200
	ds_read_b128 v[198:201], v156 offset:52224
	ds_read_b128 v[202:205], v156 offset:53248
	ds_read_b128 v[206:209], v156 offset:54272
	ds_read_b128 v[210:213], v156 offset:55296
	ds_read_b128 v[214:217], v156 offset:56320
	global_load_lds_dwordx4 v130, s[98:99]
	s_add_i32 m0, s26, 0x2000
	s_add_u32 s24, s24, 0x100080
	s_addc_u32 s25, s25, 0
	s_add_i32 s26, s54, s29
	global_load_lds_dwordx4 v134, s[98:99]
	s_mov_b32 m0, s26
	s_nop 0
	global_load_lds_dwordx4 v130, s[24:25]
	s_add_i32 m0, s26, 0x2000
	s_nop 0
	global_load_lds_dwordx4 v134, s[24:25]
	s_mov_b32 m0, s38
	s_nop 0
	global_load_lds_dwordx4 v128, s[100:101]
	s_mov_b32 m0, s39
	s_nop 0
	global_load_lds_dwordx4 v132, s[100:101]
	s_waitcnt vmcnt(8)
	s_waitcnt lgkmcnt(0)
	s_setprio 1
	s_barrier
	v_mfma_f32_16x16x32_bf16 v[60:63], v[146:149], v[186:189], v[60:63]
	v_mfma_f32_16x16x32_bf16 v[56:59], v[162:165], v[186:189], v[56:59]
	v_mfma_f32_16x16x32_bf16 v[44:47], v[146:149], v[194:197], v[44:47]
	v_mfma_f32_16x16x32_bf16 v[40:43], v[162:165], v[194:197], v[40:43]
	v_mfma_f32_16x16x32_bf16 v[28:31], v[146:149], v[202:205], v[28:31]
	v_mfma_f32_16x16x32_bf16 v[24:27], v[162:165], v[202:205], v[24:27]
	v_mfma_f32_16x16x32_bf16 v[12:15], v[146:149], v[210:213], v[12:15]
	v_mfma_f32_16x16x32_bf16 v[8:11], v[162:165], v[210:213], v[8:11]
	v_mfma_f32_16x16x32_bf16 v[60:63], v[158:161], v[190:193], v[60:63]
	v_mfma_f32_16x16x32_bf16 v[56:59], v[166:169], v[190:193], v[56:59]
	v_mfma_f32_16x16x32_bf16 v[44:47], v[158:161], v[198:201], v[44:47]
	v_mfma_f32_16x16x32_bf16 v[40:43], v[166:169], v[198:201], v[40:43]
	v_mfma_f32_16x16x32_bf16 v[28:31], v[158:161], v[206:209], v[28:31]
	v_mfma_f32_16x16x32_bf16 v[24:27], v[166:169], v[206:209], v[24:27]
	v_mfma_f32_16x16x32_bf16 v[12:15], v[158:161], v[214:217], v[12:15]
	v_mfma_f32_16x16x32_bf16 v[8:11], v[166:169], v[214:217], v[8:11]
	v_mfma_f32_16x16x32_bf16 v[52:55], v[170:173], v[186:189], v[52:55]
	v_mfma_f32_16x16x32_bf16 v[48:51], v[178:181], v[186:189], v[48:51]
	v_mfma_f32_16x16x32_bf16 v[36:39], v[170:173], v[194:197], v[36:39]
	v_mfma_f32_16x16x32_bf16 v[32:35], v[178:181], v[194:197], v[32:35]
	v_mfma_f32_16x16x32_bf16 v[20:23], v[170:173], v[202:205], v[20:23]
	v_mfma_f32_16x16x32_bf16 v[16:19], v[178:181], v[202:205], v[16:19]
	v_mfma_f32_16x16x32_bf16 v[4:7], v[170:173], v[210:213], v[4:7]
	v_mfma_f32_16x16x32_bf16 v[0:3], v[178:181], v[210:213], v[0:3]
	v_mfma_f32_16x16x32_bf16 v[52:55], v[174:177], v[190:193], v[52:55]
	v_mfma_f32_16x16x32_bf16 v[48:51], v[182:185], v[190:193], v[48:51]
	v_mfma_f32_16x16x32_bf16 v[36:39], v[174:177], v[198:201], v[36:39]
	v_mfma_f32_16x16x32_bf16 v[32:35], v[182:185], v[198:201], v[32:35]
	v_mfma_f32_16x16x32_bf16 v[20:23], v[174:177], v[206:209], v[20:23]
	v_mfma_f32_16x16x32_bf16 v[16:19], v[182:185], v[206:209], v[16:19]
	v_mfma_f32_16x16x32_bf16 v[4:7], v[174:177], v[214:217], v[4:7]
	v_mfma_f32_16x16x32_bf16 v[0:3], v[182:185], v[214:217], v[0:3]
	s_barrier
	s_setprio 0
	s_add_i32 s52, s52, 2
	s_add_u32 s22, s22, 0x100
	s_addc_u32 s23, s23, 0
	s_add_u32 s50, s50, 0x100
	s_addc_u32 s51, s51, 0
	s_cmp_gt_u32 s52, 61
	s_cbranch_scc0 .LBB0_963
	s_branch .Lpeel_exit_2

; #define PG8_BAR __builtin_amdgcn_s_barrier()
; template <class Epi, class Sched, bool ALIGN_EPI = false, bool SP2 = false>
; __device__ __forceinline__ void gemm_phase(PG8_LAS unsigned char* lds, const Gemm g, const Sched& S, const Epi& E, const int wid) {
;     ...
;         if constexpr (ALIGN_EPI) { if (wr == 0) PG8_BAR; }
;         if constexpr (!Epi::AFTER_DRAIN) { E(acc, cur, wr, wc, fr, fq); S.done(cur); }
.Lpeel_exit_2:
	s_and_b64 vcc, exec, s[10:11]
	s_cbranch_vccz .LBB0_966
	s_barrier

; #define PG8_STAGE(bufoff, gbase, voff) do { _Pragma("unroll") for (int _i = 0; _i < 2; ++_i) \
;         __builtin_amdgcn_global_load_lds((const unsigned*)((const char*)(gbase) + (voff)[_i]), (PG8_LAS unsigned*)(lds + (bufoff) + ldsw + _i * 8192), 16, 0, 0); } while (0)
; #define PG8_LDA(dst, b, h) do { _Pragma("unroll") for (int m = 0; m < 4; ++m) _Pragma("unroll") for (int k = 0; k < 2; ++k) dst[m][k] = *(const PG8_LAS bf16x8*)(lds + PG8_SA(b, h) + aoff + m * 2048 + k * 1024); } while (0)
; #define PG8_LDB(dst, b, h) do { _Pragma("unroll") for (int n = 0; n < 2; ++n) _Pragma("unroll") for (int k = 0; k < 2; ++k) dst[n][k] = *(const PG8_LAS bf16x8*)(lds + PG8_SB(b, h) + boff + n * 2048 + k * 1024); } while (0)
; #define PG8_MMA(ai, bj, At, Bt) do { __builtin_amdgcn_s_setprio(1); _Pragma("unroll") for (int m = 0; m < 4; ++m) _Pragma("unroll") for (int n = 0; n < 2; ++n) _Pragma("unroll") for (int k = 0; k < 2; ++k) \
;         acc[ai][bj][m][n] = __builtin_amdgcn_mfma_f32_16x16x32_bf16(Bt[n][k], At[m][k], acc[ai][bj][m][n], 0, 0, 0); __builtin_amdgcn_s_setprio(0); } while (0)
; #define PG8_WAIT_V(n) asm volatile("s_waitcnt vmcnt(" #n ")" ::: "memory")
; #define PG8_WAIT_L(n) asm volatile("s_waitcnt lgkmcnt(" #n ")" ::: "memory")
; #define PG8_BAR __builtin_amdgcn_s_barrier()
; #define PG8_SCHED __builtin_amdgcn_sched_barrier(0)
; template <class Epi, class Sched, bool ALIGN_EPI = false, bool SP2 = false>
; __device__ __forceinline__ void gemm_phase(PG8_LAS unsigned char* lds, const Gemm g, const Sched& S, const Epi& E, const int wid) {
;     ...
;             const char* a2 = last ? nA : cA + (size_t)(t + 2) * kstep; const char* b2 = last ? nB : cB + (size_t)(t + 2) * kstep;
;             const char* a3 = a2 + kstep; const char* b3 = b2 + kstep;
;             if (last && has_next) S.a_ready(nxt);
;             if constexpr (SP2) {
;             PG8_LDB(B0, 0, 0); PG8_LDB(B1, 0, 1); PG8_SCHED; PG8_LDA(At, 0, 0); PG8_STAGE(PG8_SA(1, 1), a1 + hstep, voffA);
;             PG8_WAIT_V(8); PG8_WAIT_L(0); PG8_BAR; PG8_MMA(0, 0, At, B0); PG8_MMA(0, 1, At, B1); PG8_BAR; PG8_SCHED;
;             PG8_LDA(At, 0, 1); PG8_STAGE(PG8_SB(0, 0), b2, voffB); PG8_STAGE(PG8_SB(0, 1), b2 + hstep, voffB); PG8_STAGE(PG8_SA(0, 0), a2, voffA);
;             PG8_WAIT_V(8); PG8_WAIT_L(0); PG8_BAR; PG8_MMA(1, 0, At, B0); PG8_MMA(1, 1, At, B1); PG8_BAR; PG8_SCHED;
.LBB0_1137:
	s_add_i32 s13, s53, -2
	s_add_u32 s54, s20, 0x100
	s_addc_u32 s55, s21, 0
	s_mov_b32 s22, 0
	v_add_u32_e32 v246, 0x18000, v195
	v_add_u32_e32 v248, 0x1c000, v195
	ds_read_b128 v[128:131], v197
	ds_read_b128 v[132:135], v197 offset:1024
	ds_read_b128 v[136:139], v197 offset:2048
	ds_read_b128 v[140:143], v197 offset:3072
	ds_read_b128 v[144:147], v198
	ds_read_b128 v[148:151], v198 offset:1024
	ds_read_b128 v[174:177], v198 offset:2048
	ds_read_b128 v[178:181], v198 offset:3072
	s_add_i32 s56, s22, 2
	s_add_u32 s20, s18, 0x100
	s_addc_u32 s21, s19, 0
	s_cmp_eq_u32 s13, s22
	s_cselect_b32 s22, s16, s54
	s_cselect_b32 s25, s15, s21
	s_cselect_b32 s24, s14, s20
	s_cselect_b32 s23, s17, s55
	s_add_i32 m0, s29, 0xc000
	ds_read_b128 v[182:185], v199
	ds_read_b128 v[186:189], v199 offset:1024
	ds_read_b128 v[200:203], v199 offset:2048
	ds_read_b128 v[204:207], v199 offset:3072
	ds_read_b128 v[208:211], v199 offset:4096
	ds_read_b128 v[212:215], v199 offset:5120
	ds_read_b128 v[216:219], v199 offset:6144
	ds_read_b128 v[220:223], v199 offset:7168
	global_load_lds_dwordx4 v168, s[18:19]
	s_add_i32 m0, s29, 0xe000
	s_nop 0
	global_load_lds_dwordx4 v170, s[18:19]
	s_waitcnt vmcnt(8)
	s_waitcnt lgkmcnt(0)
	s_setprio 1
	s_barrier
	v_mfma_f32_16x16x32_bf16 v[60:63], v[128:131], v[182:185], 0
	v_mfma_f32_16x16x32_bf16 v[56:59], v[136:139], v[182:185], 0
	v_mfma_f32_16x16x32_bf16 v[44:47], v[128:131], v[200:203], 0
	v_mfma_f32_16x16x32_bf16 v[40:43], v[136:139], v[200:203], 0
	v_mfma_f32_16x16x32_bf16 v[28:31], v[128:131], v[208:211], 0
	v_mfma_f32_16x16x32_bf16 v[24:27], v[136:139], v[208:211], 0
	v_mfma_f32_16x16x32_bf16 v[12:15], v[128:131], v[216:219], 0
	v_mfma_f32_16x16x32_bf16 v[8:11], v[136:139], v[216:219], 0
	v_mfma_f32_16x16x32_bf16 v[60:63], v[132:135], v[186:189], v[60:63]
	v_mfma_f32_16x16x32_bf16 v[56:59], v[140:143], v[186:189], v[56:59]
	v_mfma_f32_16x16x32_bf16 v[44:47], v[132:135], v[204:207], v[44:47]
	v_mfma_f32_16x16x32_bf16 v[40:43], v[140:143], v[204:207], v[40:43]
	v_mfma_f32_16x16x32_bf16 v[28:31], v[132:135], v[212:215], v[28:31]
	v_mfma_f32_16x16x32_bf16 v[24:27], v[140:143], v[212:215], v[24:27]
	v_mfma_f32_16x16x32_bf16 v[12:15], v[132:135], v[220:223], v[12:15]
	v_mfma_f32_16x16x32_bf16 v[8:11], v[140:143], v[220:223], v[8:11]
	v_mfma_f32_16x16x32_bf16 v[52:55], v[144:147], v[182:185], 0
	v_mfma_f32_16x16x32_bf16 v[48:51], v[174:177], v[182:185], 0
	v_mfma_f32_16x16x32_bf16 v[36:39], v[144:147], v[200:203], 0
	v_mfma_f32_16x16x32_bf16 v[32:35], v[174:177], v[200:203], 0
	v_mfma_f32_16x16x32_bf16 v[20:23], v[144:147], v[208:211], 0
	v_mfma_f32_16x16x32_bf16 v[16:19], v[174:177], v[208:211], 0
	v_mfma_f32_16x16x32_bf16 v[4:7], v[144:147], v[216:219], 0
	v_mfma_f32_16x16x32_bf16 v[0:3], v[174:177], v[216:219], 0
	v_mfma_f32_16x16x32_bf16 v[52:55], v[148:151], v[186:189], v[52:55]
	v_mfma_f32_16x16x32_bf16 v[48:51], v[178:181], v[186:189], v[48:51]
	v_mfma_f32_16x16x32_bf16 v[36:39], v[148:151], v[204:207], v[36:39]
	v_mfma_f32_16x16x32_bf16 v[32:35], v[178:181], v[204:207], v[32:35]
	v_mfma_f32_16x16x32_bf16 v[20:23], v[148:151], v[212:215], v[20:23]
	v_mfma_f32_16x16x32_bf16 v[16:19], v[178:181], v[212:215], v[16:19]
	v_mfma_f32_16x16x32_bf16 v[4:7], v[148:151], v[220:223], v[4:7]
	v_mfma_f32_16x16x32_bf16 v[0:3], v[178:181], v[220:223], v[0:3]
	s_barrier
	s_setprio 0
	s_add_i32 s18, s40, s28
	s_mov_b32 m0, s18
	ds_read_b128 v[182:185], v199 offset:16384
	ds_read_b128 v[186:189], v199 offset:17408
	ds_read_b128 v[200:203], v199 offset:18432
	ds_read_b128 v[204:207], v199 offset:19456
	ds_read_b128 v[208:211], v199 offset:20480
	ds_read_b128 v[212:215], v199 offset:21504
	ds_read_b128 v[216:219], v199 offset:22528
	ds_read_b128 v[220:223], v199 offset:23552
	global_load_lds_dwordx4 v154, s[22:23]
	s_add_i32 m0, s18, 0x2000
	s_add_u32 s18, s22, 0x2b0000
	s_addc_u32 s19, s23, 0
	s_add_i32 s57, s41, s28
	global_load_lds_dwordx4 v158, s[22:23]
	s_mov_b32 m0, s57
	global_load_lds_dwordx4 v154, s[18:19]
	s_add_i32 m0, s57, 0x2000
	s_nop 0
	global_load_lds_dwordx4 v158, s[18:19]
	s_mov_b32 m0, s29
	s_nop 0
	global_load_lds_dwordx4 v152, s[24:25]
	s_mov_b32 m0, s30
	s_nop 0
	global_load_lds_dwordx4 v156, s[24:25]
	s_waitcnt vmcnt(8)
	s_waitcnt lgkmcnt(0)
	s_setprio 1
	s_barrier
	v_mfma_f32_16x16x32_bf16 v[124:127], v[128:131], v[182:185], 0
	v_mfma_f32_16x16x32_bf16 v[120:123], v[136:139], v[182:185], 0
	v_mfma_f32_16x16x32_bf16 v[108:111], v[128:131], v[200:203], 0
	v_mfma_f32_16x16x32_bf16 v[104:107], v[136:139], v[200:203], 0
	v_mfma_f32_16x16x32_bf16 v[92:95], v[128:131], v[208:211], 0
	v_mfma_f32_16x16x32_bf16 v[88:91], v[136:139], v[208:211], 0
	v_mfma_f32_16x16x32_bf16 v[76:79], v[128:131], v[216:219], 0
	v_mfma_f32_16x16x32_bf16 v[72:75], v[136:139], v[216:219], 0
	v_mfma_f32_16x16x32_bf16 v[124:127], v[132:135], v[186:189], v[124:127]
	v_mfma_f32_16x16x32_bf16 v[120:123], v[140:143], v[186:189], v[120:123]
	v_mfma_f32_16x16x32_bf16 v[108:111], v[132:135], v[204:207], v[108:111]
	v_mfma_f32_16x16x32_bf16 v[104:107], v[140:143], v[204:207], v[104:107]
	v_mfma_f32_16x16x32_bf16 v[92:95], v[132:135], v[212:215], v[92:95]
	v_mfma_f32_16x16x32_bf16 v[88:91], v[140:143], v[212:215], v[88:91]
	v_mfma_f32_16x16x32_bf16 v[76:79], v[132:135], v[220:223], v[76:79]
	v_mfma_f32_16x16x32_bf16 v[72:75], v[140:143], v[220:223], v[72:75]
	v_mfma_f32_16x16x32_bf16 v[116:119], v[144:147], v[182:185], 0
	v_mfma_f32_16x16x32_bf16 v[112:115], v[174:177], v[182:185], 0
	v_mfma_f32_16x16x32_bf16 v[100:103], v[144:147], v[200:203], 0
	v_mfma_f32_16x16x32_bf16 v[96:99], v[174:177], v[200:203], 0
	v_mfma_f32_16x16x32_bf16 v[84:87], v[144:147], v[208:211], 0
	v_mfma_f32_16x16x32_bf16 v[80:83], v[174:177], v[208:211], 0
	v_mfma_f32_16x16x32_bf16 v[68:71], v[144:147], v[216:219], 0
	v_mfma_f32_16x16x32_bf16 v[64:67], v[174:177], v[216:219], 0
	v_mfma_f32_16x16x32_bf16 v[116:119], v[148:151], v[186:189], v[116:119]
	v_mfma_f32_16x16x32_bf16 v[112:115], v[178:181], v[186:189], v[112:115]
	v_mfma_f32_16x16x32_bf16 v[100:103], v[148:151], v[204:207], v[100:103]
	v_mfma_f32_16x16x32_bf16 v[96:99], v[178:181], v[204:207], v[96:99]
	v_mfma_f32_16x16x32_bf16 v[84:87], v[148:151], v[212:215], v[84:87]
	v_mfma_f32_16x16x32_bf16 v[80:83], v[178:181], v[212:215], v[80:83]
	v_mfma_f32_16x16x32_bf16 v[68:71], v[148:151], v[220:223], v[68:71]
	v_mfma_f32_16x16x32_bf16 v[64:67], v[178:181], v[220:223], v[64:67]
	s_barrier
; #define PG8_STAGE(bufoff, gbase, voff) do { _Pragma("unroll") for (int _i = 0; _i < 2; ++_i) \
;         __builtin_amdgcn_global_load_lds((const unsigned*)((const char*)(gbase) + (voff)[_i]), (PG8_LAS unsigned*)(lds + (bufoff) + ldsw + _i * 8192), 16, 0, 0); } while (0)
; #define PG8_LDA(dst, b, h) do { _Pragma("unroll") for (int m = 0; m < 4; ++m) _Pragma("unroll") for (int k = 0; k < 2; ++k) dst[m][k] = *(const PG8_LAS bf16x8*)(lds + PG8_SA(b, h) + aoff + m * 2048 + k * 1024); } while (0)
; #define PG8_LDB(dst, b, h) do { _Pragma("unroll") for (int n = 0; n < 2; ++n) _Pragma("unroll") for (int k = 0; k < 2; ++k) dst[n][k] = *(const PG8_LAS bf16x8*)(lds + PG8_SB(b, h) + boff + n * 2048 + k * 1024); } while (0)
; #define PG8_MMA(ai, bj, At, Bt) do { __builtin_amdgcn_s_setprio(1); _Pragma("unroll") for (int m = 0; m < 4; ++m) _Pragma("unroll") for (int n = 0; n < 2; ++n) _Pragma("unroll") for (int k = 0; k < 2; ++k) \
;         acc[ai][bj][m][n] = __builtin_amdgcn_mfma_f32_16x16x32_bf16(Bt[n][k], At[m][k], acc[ai][bj][m][n], 0, 0, 0); __builtin_amdgcn_s_setprio(0); } while (0)
; #define PG8_WAIT_V(n) asm volatile("s_waitcnt vmcnt(" #n ")" ::: "memory")
; #define PG8_WAIT_L(n) asm volatile("s_waitcnt lgkmcnt(" #n ")" ::: "memory")
; #define PG8_BAR __builtin_amdgcn_s_barrier()
; #define PG8_SCHED __builtin_amdgcn_sched_barrier(0)
; template <class Epi, class Sched, bool ALIGN_EPI = false, bool SP2 = false>
; __device__ __forceinline__ void gemm_phase(PG8_LAS unsigned char* lds, const Gemm g, const Sched& S, const Epi& E, const int wid) {
;     ...
;         for (int t = 0; t < nt; t += 2) {
;     ...
;             PG8_LDB(B0, 1, 0); PG8_LDB(B1, 1, 1); PG8_SCHED; PG8_LDA(At, 1, 0); PG8_STAGE(PG8_SA(0, 1), a2 + hstep, voffA);
;             PG8_WAIT_V(8); PG8_WAIT_L(0); PG8_BAR; PG8_MMA(0, 0, At, B0); PG8_MMA(0, 1, At, B1); PG8_BAR; PG8_SCHED;
;             PG8_LDA(At, 1, 1); PG8_STAGE(PG8_SB(1, 0), b3, voffB); PG8_STAGE(PG8_SB(1, 1), b3 + hstep, voffB); PG8_STAGE(PG8_SA(1, 0), a3, voffA);
;             PG8_WAIT_V(8); PG8_WAIT_L(0); PG8_BAR; PG8_MMA(1, 0, At, B0); PG8_MMA(1, 1, At, B1); PG8_BAR; PG8_SCHED;
	s_setprio 0
	s_add_i32 s57, 0, 0x18000
	s_add_i32 s58, 0, 0x1c000
	ds_read_b128 v[128:131], v246
	ds_read_b128 v[132:135], v246 offset:1024
	ds_read_b128 v[136:139], v246 offset:2048
	ds_read_b128 v[140:143], v246 offset:3072
	ds_read_b128 v[144:147], v248
	ds_read_b128 v[148:151], v248 offset:1024
	ds_read_b128 v[174:177], v248 offset:2048
	ds_read_b128 v[178:181], v248 offset:3072
	s_add_u32 s18, s24, 0x2b0000
	s_addc_u32 s19, s25, 0
	s_mov_b32 m0, s31
	ds_read_b128 v[182:185], v199 offset:32768
	ds_read_b128 v[186:189], v199 offset:33792
	ds_read_b128 v[200:203], v199 offset:34816
	ds_read_b128 v[204:207], v199 offset:35840
	ds_read_b128 v[208:211], v199 offset:36864
	ds_read_b128 v[212:215], v199 offset:37888
	ds_read_b128 v[216:219], v199 offset:38912
	ds_read_b128 v[220:223], v199 offset:39936
	global_load_lds_dwordx4 v152, s[18:19]
	s_mov_b32 m0, s34
	s_nop 0
	global_load_lds_dwordx4 v156, s[18:19]
	s_waitcnt vmcnt(8)
	s_waitcnt lgkmcnt(0)
	s_setprio 1
	s_barrier
	v_mfma_f32_16x16x32_bf16 v[60:63], v[128:131], v[182:185], v[60:63]
	v_mfma_f32_16x16x32_bf16 v[56:59], v[136:139], v[182:185], v[56:59]
	v_mfma_f32_16x16x32_bf16 v[44:47], v[128:131], v[200:203], v[44:47]
	v_mfma_f32_16x16x32_bf16 v[40:43], v[136:139], v[200:203], v[40:43]
	v_mfma_f32_16x16x32_bf16 v[28:31], v[128:131], v[208:211], v[28:31]
	v_mfma_f32_16x16x32_bf16 v[24:27], v[136:139], v[208:211], v[24:27]
	v_mfma_f32_16x16x32_bf16 v[12:15], v[128:131], v[216:219], v[12:15]
	v_mfma_f32_16x16x32_bf16 v[8:11], v[136:139], v[216:219], v[8:11]
	v_mfma_f32_16x16x32_bf16 v[60:63], v[132:135], v[186:189], v[60:63]
	v_mfma_f32_16x16x32_bf16 v[56:59], v[140:143], v[186:189], v[56:59]
	v_mfma_f32_16x16x32_bf16 v[44:47], v[132:135], v[204:207], v[44:47]
	v_mfma_f32_16x16x32_bf16 v[40:43], v[140:143], v[204:207], v[40:43]
	v_mfma_f32_16x16x32_bf16 v[28:31], v[132:135], v[212:215], v[28:31]
	v_mfma_f32_16x16x32_bf16 v[24:27], v[140:143], v[212:215], v[24:27]
	v_mfma_f32_16x16x32_bf16 v[12:15], v[132:135], v[220:223], v[12:15]
	v_mfma_f32_16x16x32_bf16 v[8:11], v[140:143], v[220:223], v[8:11]
	v_mfma_f32_16x16x32_bf16 v[52:55], v[144:147], v[182:185], v[52:55]
	v_mfma_f32_16x16x32_bf16 v[48:51], v[174:177], v[182:185], v[48:51]
	v_mfma_f32_16x16x32_bf16 v[36:39], v[144:147], v[200:203], v[36:39]
	v_mfma_f32_16x16x32_bf16 v[32:35], v[174:177], v[200:203], v[32:35]
	v_mfma_f32_16x16x32_bf16 v[20:23], v[144:147], v[208:211], v[20:23]
	v_mfma_f32_16x16x32_bf16 v[16:19], v[174:177], v[208:211], v[16:19]
	v_mfma_f32_16x16x32_bf16 v[4:7], v[144:147], v[216:219], v[4:7]
	v_mfma_f32_16x16x32_bf16 v[0:3], v[174:177], v[216:219], v[0:3]
	v_mfma_f32_16x16x32_bf16 v[52:55], v[148:151], v[186:189], v[52:55]
	v_mfma_f32_16x16x32_bf16 v[48:51], v[178:181], v[186:189], v[48:51]
	v_mfma_f32_16x16x32_bf16 v[36:39], v[148:151], v[204:207], v[36:39]
	v_mfma_f32_16x16x32_bf16 v[32:35], v[178:181], v[204:207], v[32:35]
	v_mfma_f32_16x16x32_bf16 v[20:23], v[148:151], v[212:215], v[20:23]
	v_mfma_f32_16x16x32_bf16 v[16:19], v[178:181], v[212:215], v[16:19]
	v_mfma_f32_16x16x32_bf16 v[4:7], v[148:151], v[220:223], v[4:7]
	v_mfma_f32_16x16x32_bf16 v[0:3], v[178:181], v[220:223], v[0:3]
	s_barrier
	s_setprio 0
	s_add_u32 s98, s22, 0x80
	s_addc_u32 s99, s23, 0
	s_add_u32 s100, s24, 0x80
	s_addc_u32 s101, s25, 0
	s_add_i32 s18, s57, s28
	s_mov_b32 m0, s18
	ds_read_b128 v[182:185], v199 offset:49152
	ds_read_b128 v[186:189], v199 offset:50176
	ds_read_b128 v[200:203], v199 offset:51200
	ds_read_b128 v[204:207], v199 offset:52224
	ds_read_b128 v[208:211], v199 offset:53248
	ds_read_b128 v[212:215], v199 offset:54272
	ds_read_b128 v[216:219], v199 offset:55296
	ds_read_b128 v[220:223], v199 offset:56320
	global_load_lds_dwordx4 v154, s[98:99]
	s_add_i32 m0, s18, 0x2000
	s_add_u32 s18, s22, 0x2b0080
	s_addc_u32 s19, s23, 0
	s_add_i32 s22, s58, s28
	global_load_lds_dwordx4 v158, s[98:99]
	s_mov_b32 m0, s22
	s_nop 0
	global_load_lds_dwordx4 v154, s[18:19]
	s_add_i32 m0, s22, 0x2000
	s_nop 0
	global_load_lds_dwordx4 v158, s[18:19]
	s_mov_b32 m0, s36
	s_nop 0
	global_load_lds_dwordx4 v152, s[100:101]
	s_mov_b32 m0, s37
	s_nop 0
	global_load_lds_dwordx4 v156, s[100:101]
	s_waitcnt vmcnt(8)
	s_waitcnt lgkmcnt(0)
	s_setprio 1
	s_barrier
	v_mfma_f32_16x16x32_bf16 v[124:127], v[128:131], v[182:185], v[124:127]
	v_mfma_f32_16x16x32_bf16 v[120:123], v[136:139], v[182:185], v[120:123]
	v_mfma_f32_16x16x32_bf16 v[108:111], v[128:131], v[200:203], v[108:111]
	v_mfma_f32_16x16x32_bf16 v[104:107], v[136:139], v[200:203], v[104:107]
	v_mfma_f32_16x16x32_bf16 v[92:95], v[128:131], v[208:211], v[92:95]
	v_mfma_f32_16x16x32_bf16 v[88:91], v[136:139], v[208:211], v[88:91]
	v_mfma_f32_16x16x32_bf16 v[76:79], v[128:131], v[216:219], v[76:79]
	v_mfma_f32_16x16x32_bf16 v[72:75], v[136:139], v[216:219], v[72:75]
	v_mfma_f32_16x16x32_bf16 v[124:127], v[132:135], v[186:189], v[124:127]
	v_mfma_f32_16x16x32_bf16 v[120:123], v[140:143], v[186:189], v[120:123]
	v_mfma_f32_16x16x32_bf16 v[108:111], v[132:135], v[204:207], v[108:111]
	v_mfma_f32_16x16x32_bf16 v[104:107], v[140:143], v[204:207], v[104:107]
	v_mfma_f32_16x16x32_bf16 v[92:95], v[132:135], v[212:215], v[92:95]
	v_mfma_f32_16x16x32_bf16 v[88:91], v[140:143], v[212:215], v[88:91]
	v_mfma_f32_16x16x32_bf16 v[76:79], v[132:135], v[220:223], v[76:79]
	v_mfma_f32_16x16x32_bf16 v[72:75], v[140:143], v[220:223], v[72:75]
	v_mfma_f32_16x16x32_bf16 v[116:119], v[144:147], v[182:185], v[116:119]
	v_mfma_f32_16x16x32_bf16 v[112:115], v[174:177], v[182:185], v[112:115]
	v_mfma_f32_16x16x32_bf16 v[100:103], v[144:147], v[200:203], v[100:103]
	v_mfma_f32_16x16x32_bf16 v[96:99], v[174:177], v[200:203], v[96:99]
	v_mfma_f32_16x16x32_bf16 v[84:87], v[144:147], v[208:211], v[84:87]
	v_mfma_f32_16x16x32_bf16 v[80:83], v[174:177], v[208:211], v[80:83]
	v_mfma_f32_16x16x32_bf16 v[68:71], v[144:147], v[216:219], v[68:71]
	v_mfma_f32_16x16x32_bf16 v[64:67], v[174:177], v[216:219], v[64:67]
	v_mfma_f32_16x16x32_bf16 v[116:119], v[148:151], v[186:189], v[116:119]
	v_mfma_f32_16x16x32_bf16 v[112:115], v[178:181], v[186:189], v[112:115]
	v_mfma_f32_16x16x32_bf16 v[100:103], v[148:151], v[204:207], v[100:103]
	v_mfma_f32_16x16x32_bf16 v[96:99], v[178:181], v[204:207], v[96:99]
	v_mfma_f32_16x16x32_bf16 v[84:87], v[148:151], v[212:215], v[84:87]
	v_mfma_f32_16x16x32_bf16 v[80:83], v[178:181], v[212:215], v[80:83]
	v_mfma_f32_16x16x32_bf16 v[68:71], v[148:151], v[220:223], v[68:71]
	v_mfma_f32_16x16x32_bf16 v[64:67], v[178:181], v[220:223], v[64:67]
	s_barrier
	s_setprio 0
	s_add_u32 s54, s54, 0x100
	s_addc_u32 s55, s55, 0
	s_cmp_ge_i32 s56, s53
	s_mov_b64 s[18:19], s[20:21]
	s_mov_b32 s22, s56
	s_cbranch_scc0 .LBB0_1138
	s_branch .Lpeel_exit_3

; __device__ __forceinline__ float row_rstd(const u64* ssq, int r) { return __builtin_amdgcn_rsqf(fx_to_pos(ssq[r]) * (1.0f / 4096.0f) + RMS_EPS); }
; #define PG8_STAGE(bufoff, gbase, voff) do { _Pragma("unroll") for (int _i = 0; _i < 2; ++_i) \
;         __builtin_amdgcn_global_load_lds((const unsigned*)((const char*)(gbase) + (voff)[_i]), (PG8_LAS unsigned*)(lds + (bufoff) + ldsw + _i * 8192), 16, 0, 0); } while (0)
; #define PG8_LDA(dst, b, h) do { _Pragma("unroll") for (int m = 0; m < 4; ++m) _Pragma("unroll") for (int k = 0; k < 2; ++k) dst[m][k] = *(const PG8_LAS bf16x8*)(lds + PG8_SA(b, h) + aoff + m * 2048 + k * 1024); } while (0)
; #define PG8_LDB(dst, b, h) do { _Pragma("unroll") for (int n = 0; n < 2; ++n) _Pragma("unroll") for (int k = 0; k < 2; ++k) dst[n][k] = *(const PG8_LAS bf16x8*)(lds + PG8_SB(b, h) + boff + n * 2048 + k * 1024); } while (0)
; #define PG8_WAIT_V(n) asm volatile("s_waitcnt vmcnt(" #n ")" ::: "memory")
; #define PG8_WAIT_L(n) asm volatile("s_waitcnt lgkmcnt(" #n ")" ::: "memory")
;     __device__ __forceinline__ void operator()(const f32x4 (&acc)[2][2][4][2], const Unit& u, int wr, int wc, int fr, int fq) const {
;     ...
;                 for (int m = 0; m < 4; ++m) { const int r = row0 + ai * HALF + m * 16; const float rs = row_rstd(ssq, r) * sc;
; template <class Epi, class Sched, bool ALIGN_EPI = false, bool SP2 = false>
; __device__ __forceinline__ void gemm_phase(PG8_LAS unsigned char* lds, const Gemm g, const Sched& S, const Epi& E, const int wid) {
;     ...
;             const char* a1 = cA + (size_t)(t + 1) * kstep;
;             const char* a2 = last ? nA : cA + (size_t)(t + 2) * kstep; const char* b2 = last ? nB : cB + (size_t)(t + 2) * kstep;
;             const char* a3 = a2 + kstep; const char* b3 = b2 + kstep;
;             if (last && has_next) S.a_ready(nxt);
;             if constexpr (SP2) {
;             PG8_LDB(B0, 0, 0); PG8_LDB(B1, 0, 1); PG8_SCHED; PG8_LDA(At, 0, 0); PG8_STAGE(PG8_SA(1, 1), a1 + hstep, voffA);
;             PG8_WAIT_V(8); PG8_WAIT_L(0); PG8_BAR; PG8_MMA(0, 0, At, B0); PG8_MMA(0, 1, At, B1); PG8_BAR; PG8_SCHED;
;             PG8_LDA(At, 0, 1); PG8_STAGE(PG8_SB(0, 0), b2, voffB); PG8_STAGE(PG8_SB(0, 1), b2 + hstep, voffB); PG8_STAGE(PG8_SA(0, 0), a2, voffA);
;             PG8_WAIT_V(8); PG8_WAIT_L(0); PG8_BAR; PG8_MMA(1, 0, At, B0); PG8_MMA(1, 1, At, B1); PG8_BAR; PG8_SCHED;
.LBB0_1249:
	s_ashr_i32 s13, s12, 31
	s_lshl_b64 s[14:15], s[12:13], 21
	s_add_u32 s14, s78, s14
	s_addc_u32 s15, s79, s15
	s_and_b64 s[16:17], s[0:1], exec
	s_cselect_b32 s13, s15, s21
	s_cselect_b32 s19, s14, s20
	s_ashr_i32 s11, s10, 31
	s_lshl_b64 s[16:17], s[10:11], 21
	s_add_u32 s16, s26, s16
	s_addc_u32 s17, s27, s17
	s_and_b64 s[24:25], s[0:1], exec
	s_cselect_b32 s11, s17, s23
	s_cselect_b32 s57, s16, s22
	s_add_u32 s20, s20, 0x100080
	s_addc_u32 s21, s21, 0
	s_add_u32 s58, s22, 0x100
	s_addc_u32 s59, s23, 0
	s_mov_b32 s60, -2
	v_add_u32_e32 v246, 0x18000, v165
	ds_read_b128 v[128:131], v175
	ds_read_b128 v[150:153], v175 offset:1024
	ds_read_b128 v[154:157], v175 offset:2048
	ds_read_b128 v[158:161], v175 offset:3072
	ds_read_b128 v[180:183], v176
	ds_read_b128 v[184:187], v176 offset:1024
	ds_read_b128 v[188:191], v176 offset:2048
	ds_read_b128 v[192:195], v176 offset:3072
	s_add_u32 s22, s20, 0xfff00080
	s_addc_u32 s23, s21, -1
	s_cmp_eq_u32 s60, 60
	s_cselect_b32 s25, s13, s23
	s_cselect_b32 s24, s19, s22
	s_cselect_b32 s23, s11, s59
	s_cselect_b32 s22, s57, s58
	s_add_i32 m0, s31, 0xc000
	ds_read_b128 v[196:199], v177
	ds_read_b128 v[200:203], v177 offset:1024
	ds_read_b128 v[204:207], v177 offset:2048
	ds_read_b128 v[208:211], v177 offset:3072
	ds_read_b128 v[212:215], v177 offset:4096
	ds_read_b128 v[216:219], v177 offset:5120
	ds_read_b128 v[220:223], v177 offset:6144
	ds_read_b128 v[224:227], v177 offset:7168
	global_load_lds_dwordx4 v142, s[20:21]
	s_add_i32 m0, s31, 0xe000
	s_nop 0
	global_load_lds_dwordx4 v144, s[20:21]
	s_waitcnt vmcnt(8)
	s_waitcnt lgkmcnt(0)
	v_lshl_add_u32 v254, s18, 8, v164
	v_ashrrev_i32_e32 v255, 31, v254
	v_lshl_add_u64 v[254:255], v[254:255], 3, s[4:5]
	global_load_dwordx2 v[238:239], v[254:255], off
	global_load_dwordx2 v[240:241], v[254:255], off offset:128
	global_load_dwordx2 v[242:243], v[254:255], off offset:256
	global_load_dwordx2 v[244:245], v[254:255], off offset:384
	global_load_dwordx2 v[248:249], v[254:255], off offset:1024
	global_load_dwordx2 v[250:251], v[254:255], off offset:1152
	global_load_dwordx2 v[252:253], v[254:255], off offset:1280
	global_load_dwordx2 v[254:255], v[254:255], off offset:1408
	s_setprio 1
	s_barrier
	v_mfma_f32_16x16x32_bf16 v[124:127], v[128:131], v[196:199], 0
	v_mfma_f32_16x16x32_bf16 v[116:119], v[154:157], v[196:199], 0
	v_mfma_f32_16x16x32_bf16 v[108:111], v[128:131], v[204:207], 0
	v_mfma_f32_16x16x32_bf16 v[100:103], v[154:157], v[204:207], 0
	v_mfma_f32_16x16x32_bf16 v[92:95], v[128:131], v[212:215], 0
	v_mfma_f32_16x16x32_bf16 v[84:87], v[154:157], v[212:215], 0
	v_mfma_f32_16x16x32_bf16 v[76:79], v[128:131], v[220:223], 0
	v_mfma_f32_16x16x32_bf16 v[68:71], v[154:157], v[220:223], 0
	v_mfma_f32_16x16x32_bf16 v[124:127], v[150:153], v[200:203], v[124:127]
	v_mfma_f32_16x16x32_bf16 v[116:119], v[158:161], v[200:203], v[116:119]
	v_mfma_f32_16x16x32_bf16 v[108:111], v[150:153], v[208:211], v[108:111]
	v_mfma_f32_16x16x32_bf16 v[100:103], v[158:161], v[208:211], v[100:103]
	v_mfma_f32_16x16x32_bf16 v[92:95], v[150:153], v[216:219], v[92:95]
	v_mfma_f32_16x16x32_bf16 v[84:87], v[158:161], v[216:219], v[84:87]
	v_mfma_f32_16x16x32_bf16 v[76:79], v[150:153], v[224:227], v[76:79]
	v_mfma_f32_16x16x32_bf16 v[68:71], v[158:161], v[224:227], v[68:71]
	v_mfma_f32_16x16x32_bf16 v[120:123], v[180:183], v[196:199], 0
	v_mfma_f32_16x16x32_bf16 v[112:115], v[188:191], v[196:199], 0
	v_mfma_f32_16x16x32_bf16 v[104:107], v[180:183], v[204:207], 0
	v_mfma_f32_16x16x32_bf16 v[96:99], v[188:191], v[204:207], 0
	v_mfma_f32_16x16x32_bf16 v[88:91], v[180:183], v[212:215], 0
	v_mfma_f32_16x16x32_bf16 v[80:83], v[188:191], v[212:215], 0
	v_mfma_f32_16x16x32_bf16 v[72:75], v[180:183], v[220:223], 0
	v_mfma_f32_16x16x32_bf16 v[64:67], v[188:191], v[220:223], 0
	v_mfma_f32_16x16x32_bf16 v[120:123], v[184:187], v[200:203], v[120:123]
	v_mfma_f32_16x16x32_bf16 v[112:115], v[192:195], v[200:203], v[112:115]
	v_mfma_f32_16x16x32_bf16 v[104:107], v[184:187], v[208:211], v[104:107]
	v_mfma_f32_16x16x32_bf16 v[96:99], v[192:195], v[208:211], v[96:99]
	v_mfma_f32_16x16x32_bf16 v[88:91], v[184:187], v[216:219], v[88:91]
	v_mfma_f32_16x16x32_bf16 v[80:83], v[192:195], v[216:219], v[80:83]
	v_mfma_f32_16x16x32_bf16 v[72:75], v[184:187], v[224:227], v[72:75]
	v_mfma_f32_16x16x32_bf16 v[64:67], v[192:195], v[224:227], v[64:67]
	s_barrier
	s_setprio 0
	s_add_i32 s61, s42, s28
	s_mov_b32 m0, s61
	ds_read_b128 v[196:199], v177 offset:16384
	ds_read_b128 v[200:203], v177 offset:17408
	ds_read_b128 v[204:207], v177 offset:18432
	ds_read_b128 v[208:211], v177 offset:19456
	ds_read_b128 v[212:215], v177 offset:20480
	ds_read_b128 v[216:219], v177 offset:21504
	ds_read_b128 v[220:223], v177 offset:22528
	ds_read_b128 v[224:227], v177 offset:23552
	global_load_lds_dwordx4 v136, s[22:23]
	s_add_i32 m0, s61, 0x2000
	s_add_u32 s62, s22, 0x100000
	s_addc_u32 s63, s23, 0
	s_add_i32 s61, s43, s28
	global_load_lds_dwordx4 v132, s[22:23]
	s_mov_b32 m0, s61
	global_load_lds_dwordx4 v136, s[62:63]
	s_add_i32 m0, s61, 0x2000
	s_nop 0
	global_load_lds_dwordx4 v132, s[62:63]
	s_mov_b32 m0, s31
	s_nop 0
	global_load_lds_dwordx4 v138, s[24:25]
	s_mov_b32 m0, s34
	s_nop 0
	global_load_lds_dwordx4 v134, s[24:25]
	s_waitcnt vmcnt(8)
	s_waitcnt lgkmcnt(0)
	s_setprio 1
	s_barrier
; #define PG8_STAGE(bufoff, gbase, voff) do { _Pragma("unroll") for (int _i = 0; _i < 2; ++_i) \
;         __builtin_amdgcn_global_load_lds((const unsigned*)((const char*)(gbase) + (voff)[_i]), (PG8_LAS unsigned*)(lds + (bufoff) + ldsw + _i * 8192), 16, 0, 0); } while (0)
; #define PG8_LDA(dst, b, h) do { _Pragma("unroll") for (int m = 0; m < 4; ++m) _Pragma("unroll") for (int k = 0; k < 2; ++k) dst[m][k] = *(const PG8_LAS bf16x8*)(lds + PG8_SA(b, h) + aoff + m * 2048 + k * 1024); } while (0)
; #define PG8_LDB(dst, b, h) do { _Pragma("unroll") for (int n = 0; n < 2; ++n) _Pragma("unroll") for (int k = 0; k < 2; ++k) dst[n][k] = *(const PG8_LAS bf16x8*)(lds + PG8_SB(b, h) + boff + n * 2048 + k * 1024); } while (0)
; #define PG8_MMA(ai, bj, At, Bt) do { __builtin_amdgcn_s_setprio(1); _Pragma("unroll") for (int m = 0; m < 4; ++m) _Pragma("unroll") for (int n = 0; n < 2; ++n) _Pragma("unroll") for (int k = 0; k < 2; ++k) \
;         acc[ai][bj][m][n] = __builtin_amdgcn_mfma_f32_16x16x32_bf16(Bt[n][k], At[m][k], acc[ai][bj][m][n], 0, 0, 0); __builtin_amdgcn_s_setprio(0); } while (0)
; #define PG8_WAIT_V(n) asm volatile("s_waitcnt vmcnt(" #n ")" ::: "memory")
; #define PG8_WAIT_L(n) asm volatile("s_waitcnt lgkmcnt(" #n ")" ::: "memory")
; #define PG8_BAR __builtin_amdgcn_s_barrier()
; #define PG8_SCHED __builtin_amdgcn_sched_barrier(0)
; template <class Epi, class Sched, bool ALIGN_EPI = false, bool SP2 = false>
; __device__ __forceinline__ void gemm_phase(PG8_LAS unsigned char* lds, const Gemm g, const Sched& S, const Epi& E, const int wid) {
;     ...
;             PG8_WAIT_V(8); PG8_WAIT_L(0); PG8_BAR; PG8_MMA(1, 0, At, B0); PG8_MMA(1, 1, At, B1); PG8_BAR; PG8_SCHED;
;             PG8_LDB(B0, 1, 0); PG8_LDB(B1, 1, 1); PG8_SCHED; PG8_LDA(At, 1, 0); PG8_STAGE(PG8_SA(0, 1), a2 + hstep, voffA);
;             PG8_WAIT_V(8); PG8_WAIT_L(0); PG8_BAR; PG8_MMA(0, 0, At, B0); PG8_MMA(0, 1, At, B1); PG8_BAR; PG8_SCHED;
	v_mfma_f32_16x16x32_bf16 v[60:63], v[128:131], v[196:199], 0
	v_mfma_f32_16x16x32_bf16 v[52:55], v[154:157], v[196:199], 0
	v_mfma_f32_16x16x32_bf16 v[44:47], v[128:131], v[204:207], 0
	v_mfma_f32_16x16x32_bf16 v[36:39], v[154:157], v[204:207], 0
	v_mfma_f32_16x16x32_bf16 v[28:31], v[128:131], v[212:215], 0
	v_mfma_f32_16x16x32_bf16 v[20:23], v[154:157], v[212:215], 0
	v_mfma_f32_16x16x32_bf16 v[12:15], v[128:131], v[220:223], 0
	v_mfma_f32_16x16x32_bf16 v[4:7], v[154:157], v[220:223], 0
	v_mfma_f32_16x16x32_bf16 v[60:63], v[150:153], v[200:203], v[60:63]
	v_mfma_f32_16x16x32_bf16 v[52:55], v[158:161], v[200:203], v[52:55]
	v_mfma_f32_16x16x32_bf16 v[44:47], v[150:153], v[208:211], v[44:47]
	v_mfma_f32_16x16x32_bf16 v[36:39], v[158:161], v[208:211], v[36:39]
	v_mfma_f32_16x16x32_bf16 v[28:31], v[150:153], v[216:219], v[28:31]
	v_mfma_f32_16x16x32_bf16 v[20:23], v[158:161], v[216:219], v[20:23]
	v_mfma_f32_16x16x32_bf16 v[12:15], v[150:153], v[224:227], v[12:15]
	v_mfma_f32_16x16x32_bf16 v[4:7], v[158:161], v[224:227], v[4:7]
	v_mfma_f32_16x16x32_bf16 v[56:59], v[180:183], v[196:199], 0
	v_mfma_f32_16x16x32_bf16 v[48:51], v[188:191], v[196:199], 0
	v_mfma_f32_16x16x32_bf16 v[40:43], v[180:183], v[204:207], 0
	v_mfma_f32_16x16x32_bf16 v[32:35], v[188:191], v[204:207], 0
	v_mfma_f32_16x16x32_bf16 v[24:27], v[180:183], v[212:215], 0
	v_mfma_f32_16x16x32_bf16 v[16:19], v[188:191], v[212:215], 0
	v_mfma_f32_16x16x32_bf16 v[8:11], v[180:183], v[220:223], 0
	v_mfma_f32_16x16x32_bf16 v[0:3], v[188:191], v[220:223], 0
	v_mfma_f32_16x16x32_bf16 v[56:59], v[184:187], v[200:203], v[56:59]
	v_mfma_f32_16x16x32_bf16 v[48:51], v[192:195], v[200:203], v[48:51]
	v_mfma_f32_16x16x32_bf16 v[40:43], v[184:187], v[208:211], v[40:43]
	v_mfma_f32_16x16x32_bf16 v[32:35], v[192:195], v[208:211], v[32:35]
	v_mfma_f32_16x16x32_bf16 v[24:27], v[184:187], v[216:219], v[24:27]
	v_mfma_f32_16x16x32_bf16 v[16:19], v[192:195], v[216:219], v[16:19]
	v_mfma_f32_16x16x32_bf16 v[8:11], v[184:187], v[224:227], v[8:11]
	v_mfma_f32_16x16x32_bf16 v[0:3], v[192:195], v[224:227], v[0:3]
	s_barrier
	s_setprio 0
	s_add_i32 s61, 0, 0x18000
	s_add_i32 s62, 0, 0x1c000
	ds_read_b128 v[128:131], v246
	ds_read_b128 v[150:153], v246 offset:1024
	ds_read_b128 v[154:157], v246 offset:2048
	ds_read_b128 v[158:161], v246 offset:3072
	v_add_u32_e32 v140, s62, v165
	ds_read_b128 v[180:183], v140
	ds_read_b128 v[184:187], v140 offset:1024
	ds_read_b128 v[188:191], v140 offset:2048
	ds_read_b128 v[192:195], v140 offset:3072
	s_add_u32 s24, s24, 0x100000
	s_addc_u32 s25, s25, 0
	s_mov_b32 m0, s35
	ds_read_b128 v[196:199], v177 offset:32768
	ds_read_b128 v[200:203], v177 offset:33792
	ds_read_b128 v[204:207], v177 offset:34816
	ds_read_b128 v[208:211], v177 offset:35840
	ds_read_b128 v[212:215], v177 offset:36864
	ds_read_b128 v[216:219], v177 offset:37888
	ds_read_b128 v[220:223], v177 offset:38912
	ds_read_b128 v[224:227], v177 offset:39936
	global_load_lds_dwordx4 v138, s[24:25]
	s_mov_b32 m0, s36
	s_nop 0
	global_load_lds_dwordx4 v134, s[24:25]
	s_waitcnt vmcnt(8)
	s_waitcnt lgkmcnt(0)
	s_setprio 1
	s_barrier
	v_mfma_f32_16x16x32_bf16 v[124:127], v[128:131], v[196:199], v[124:127]
	v_mfma_f32_16x16x32_bf16 v[116:119], v[154:157], v[196:199], v[116:119]
	v_mfma_f32_16x16x32_bf16 v[108:111], v[128:131], v[204:207], v[108:111]
	v_mfma_f32_16x16x32_bf16 v[100:103], v[154:157], v[204:207], v[100:103]
	v_mfma_f32_16x16x32_bf16 v[92:95], v[128:131], v[212:215], v[92:95]
	v_mfma_f32_16x16x32_bf16 v[84:87], v[154:157], v[212:215], v[84:87]
	v_mfma_f32_16x16x32_bf16 v[76:79], v[128:131], v[220:223], v[76:79]
	v_mfma_f32_16x16x32_bf16 v[68:71], v[154:157], v[220:223], v[68:71]
	v_mfma_f32_16x16x32_bf16 v[124:127], v[150:153], v[200:203], v[124:127]
	v_mfma_f32_16x16x32_bf16 v[116:119], v[158:161], v[200:203], v[116:119]
	v_mfma_f32_16x16x32_bf16 v[108:111], v[150:153], v[208:211], v[108:111]
	v_mfma_f32_16x16x32_bf16 v[100:103], v[158:161], v[208:211], v[100:103]
	v_mfma_f32_16x16x32_bf16 v[92:95], v[150:153], v[216:219], v[92:95]
	v_mfma_f32_16x16x32_bf16 v[84:87], v[158:161], v[216:219], v[84:87]
	v_mfma_f32_16x16x32_bf16 v[76:79], v[150:153], v[224:227], v[76:79]
	v_mfma_f32_16x16x32_bf16 v[68:71], v[158:161], v[224:227], v[68:71]
	v_mfma_f32_16x16x32_bf16 v[120:123], v[180:183], v[196:199], v[120:123]
	v_mfma_f32_16x16x32_bf16 v[112:115], v[188:191], v[196:199], v[112:115]
	v_mfma_f32_16x16x32_bf16 v[104:107], v[180:183], v[204:207], v[104:107]
	v_mfma_f32_16x16x32_bf16 v[96:99], v[188:191], v[204:207], v[96:99]
	v_mfma_f32_16x16x32_bf16 v[88:91], v[180:183], v[212:215], v[88:91]
	v_mfma_f32_16x16x32_bf16 v[80:83], v[188:191], v[212:215], v[80:83]
	v_mfma_f32_16x16x32_bf16 v[72:75], v[180:183], v[220:223], v[72:75]
	v_mfma_f32_16x16x32_bf16 v[64:67], v[188:191], v[220:223], v[64:67]
	v_mfma_f32_16x16x32_bf16 v[120:123], v[184:187], v[200:203], v[120:123]
	v_mfma_f32_16x16x32_bf16 v[112:115], v[192:195], v[200:203], v[112:115]
	v_mfma_f32_16x16x32_bf16 v[104:107], v[184:187], v[208:211], v[104:107]
	v_mfma_f32_16x16x32_bf16 v[96:99], v[192:195], v[208:211], v[96:99]
	v_mfma_f32_16x16x32_bf16 v[88:91], v[184:187], v[216:219], v[88:91]
	v_mfma_f32_16x16x32_bf16 v[80:83], v[192:195], v[216:219], v[80:83]
	v_mfma_f32_16x16x32_bf16 v[72:75], v[184:187], v[224:227], v[72:75]
	v_mfma_f32_16x16x32_bf16 v[64:67], v[192:195], v[224:227], v[64:67]
	s_barrier
; #define PG8_STAGE(bufoff, gbase, voff) do { _Pragma("unroll") for (int _i = 0; _i < 2; ++_i) \
;         __builtin_amdgcn_global_load_lds((const unsigned*)((const char*)(gbase) + (voff)[_i]), (PG8_LAS unsigned*)(lds + (bufoff) + ldsw + _i * 8192), 16, 0, 0); } while (0)
; #define PG8_LDA(dst, b, h) do { _Pragma("unroll") for (int m = 0; m < 4; ++m) _Pragma("unroll") for (int k = 0; k < 2; ++k) dst[m][k] = *(const PG8_LAS bf16x8*)(lds + PG8_SA(b, h) + aoff + m * 2048 + k * 1024); } while (0)
; #define PG8_MMA(ai, bj, At, Bt) do { __builtin_amdgcn_s_setprio(1); _Pragma("unroll") for (int m = 0; m < 4; ++m) _Pragma("unroll") for (int n = 0; n < 2; ++n) _Pragma("unroll") for (int k = 0; k < 2; ++k) \
;         acc[ai][bj][m][n] = __builtin_amdgcn_mfma_f32_16x16x32_bf16(Bt[n][k], At[m][k], acc[ai][bj][m][n], 0, 0, 0); __builtin_amdgcn_s_setprio(0); } while (0)
; #define PG8_WAIT_V(n) asm volatile("s_waitcnt vmcnt(" #n ")" ::: "memory")
; #define PG8_WAIT_L(n) asm volatile("s_waitcnt lgkmcnt(" #n ")" ::: "memory")
; #define PG8_BAR __builtin_amdgcn_s_barrier()
; #define PG8_SCHED __builtin_amdgcn_sched_barrier(0)
; template <class Epi, class Sched, bool ALIGN_EPI = false, bool SP2 = false>
; __device__ __forceinline__ void gemm_phase(PG8_LAS unsigned char* lds, const Gemm g, const Sched& S, const Epi& E, const int wid) {
;     ...
;         for (int t = 0; t < nt; t += 2) {
;     ...
;             PG8_LDA(At, 1, 1); PG8_STAGE(PG8_SB(1, 0), b3, voffB); PG8_STAGE(PG8_SB(1, 1), b3 + hstep, voffB); PG8_STAGE(PG8_SA(1, 0), a3, voffA);
;             PG8_WAIT_V(8); PG8_WAIT_L(0); PG8_BAR; PG8_MMA(1, 0, At, B0); PG8_MMA(1, 1, At, B1); PG8_BAR; PG8_SCHED;
	s_setprio 0
	s_add_u32 s98, s22, 0x80
	s_addc_u32 s99, s23, 0
	s_add_u32 s100, s24, 0xfff00080
	s_addc_u32 s101, s25, -1
	s_add_i32 s24, s61, s28
	s_mov_b32 m0, s24
	ds_read_b128 v[196:199], v177 offset:49152
	ds_read_b128 v[200:203], v177 offset:50176
	ds_read_b128 v[204:207], v177 offset:51200
	ds_read_b128 v[208:211], v177 offset:52224
	ds_read_b128 v[212:215], v177 offset:53248
	ds_read_b128 v[216:219], v177 offset:54272
	ds_read_b128 v[220:223], v177 offset:55296
	ds_read_b128 v[224:227], v177 offset:56320
	global_load_lds_dwordx4 v136, s[98:99]
	s_add_i32 m0, s24, 0x2000
	s_add_u32 s22, s22, 0x100080
	s_addc_u32 s23, s23, 0
	s_add_i32 s24, s62, s28
	global_load_lds_dwordx4 v132, s[98:99]
	s_mov_b32 m0, s24
	s_nop 0
	global_load_lds_dwordx4 v136, s[22:23]
	s_add_i32 m0, s24, 0x2000
	s_nop 0
	global_load_lds_dwordx4 v132, s[22:23]
	s_mov_b32 m0, s38
	s_nop 0
	global_load_lds_dwordx4 v138, s[100:101]
	s_mov_b32 m0, s39
	s_nop 0
	global_load_lds_dwordx4 v134, s[100:101]
	s_waitcnt vmcnt(8)
	s_waitcnt lgkmcnt(0)
	s_setprio 1
	s_barrier
	v_mfma_f32_16x16x32_bf16 v[60:63], v[128:131], v[196:199], v[60:63]
	v_mfma_f32_16x16x32_bf16 v[52:55], v[154:157], v[196:199], v[52:55]
	v_mfma_f32_16x16x32_bf16 v[44:47], v[128:131], v[204:207], v[44:47]
	v_mfma_f32_16x16x32_bf16 v[36:39], v[154:157], v[204:207], v[36:39]
	v_mfma_f32_16x16x32_bf16 v[28:31], v[128:131], v[212:215], v[28:31]
	v_mfma_f32_16x16x32_bf16 v[20:23], v[154:157], v[212:215], v[20:23]
	v_mfma_f32_16x16x32_bf16 v[12:15], v[128:131], v[220:223], v[12:15]
	v_mfma_f32_16x16x32_bf16 v[4:7], v[154:157], v[220:223], v[4:7]
	v_mfma_f32_16x16x32_bf16 v[60:63], v[150:153], v[200:203], v[60:63]
	v_mfma_f32_16x16x32_bf16 v[52:55], v[158:161], v[200:203], v[52:55]
	v_mfma_f32_16x16x32_bf16 v[44:47], v[150:153], v[208:211], v[44:47]
	v_mfma_f32_16x16x32_bf16 v[36:39], v[158:161], v[208:211], v[36:39]
	v_mfma_f32_16x16x32_bf16 v[28:31], v[150:153], v[216:219], v[28:31]
	v_mfma_f32_16x16x32_bf16 v[20:23], v[158:161], v[216:219], v[20:23]
	v_mfma_f32_16x16x32_bf16 v[12:15], v[150:153], v[224:227], v[12:15]
	v_mfma_f32_16x16x32_bf16 v[4:7], v[158:161], v[224:227], v[4:7]
	v_mfma_f32_16x16x32_bf16 v[56:59], v[180:183], v[196:199], v[56:59]
	v_mfma_f32_16x16x32_bf16 v[48:51], v[188:191], v[196:199], v[48:51]
	v_mfma_f32_16x16x32_bf16 v[40:43], v[180:183], v[204:207], v[40:43]
	v_mfma_f32_16x16x32_bf16 v[32:35], v[188:191], v[204:207], v[32:35]
	v_mfma_f32_16x16x32_bf16 v[24:27], v[180:183], v[212:215], v[24:27]
	v_mfma_f32_16x16x32_bf16 v[16:19], v[188:191], v[212:215], v[16:19]
	v_mfma_f32_16x16x32_bf16 v[8:11], v[180:183], v[220:223], v[8:11]
	v_mfma_f32_16x16x32_bf16 v[0:3], v[188:191], v[220:223], v[0:3]
	v_mfma_f32_16x16x32_bf16 v[56:59], v[184:187], v[200:203], v[56:59]
	v_mfma_f32_16x16x32_bf16 v[48:51], v[192:195], v[200:203], v[48:51]
	v_mfma_f32_16x16x32_bf16 v[40:43], v[184:187], v[208:211], v[40:43]
	v_mfma_f32_16x16x32_bf16 v[32:35], v[192:195], v[208:211], v[32:35]
	v_mfma_f32_16x16x32_bf16 v[24:27], v[184:187], v[216:219], v[24:27]
	v_mfma_f32_16x16x32_bf16 v[16:19], v[192:195], v[216:219], v[16:19]
	v_mfma_f32_16x16x32_bf16 v[8:11], v[184:187], v[224:227], v[8:11]
	v_mfma_f32_16x16x32_bf16 v[0:3], v[192:195], v[224:227], v[0:3]
	s_barrier
	s_setprio 0
	s_add_i32 s60, s60, 2
	s_add_u32 s20, s20, 0x100
	s_addc_u32 s21, s21, 0
	s_add_u32 s58, s58, 0x100
	s_addc_u32 s59, s59, 0
	s_cmp_gt_u32 s60, 61
	s_cbranch_scc0 .LBB0_1250
	s_branch .Lpeel_exit_4

; #define PG8_STAGE(bufoff, gbase, voff) do { _Pragma("unroll") for (int _i = 0; _i < 2; ++_i) \
;         __builtin_amdgcn_global_load_lds((const unsigned*)((const char*)(gbase) + (voff)[_i]), (PG8_LAS unsigned*)(lds + (bufoff) + ldsw + _i * 8192), 16, 0, 0); } while (0)
; #define PG8_LDA(dst, b, h) do { _Pragma("unroll") for (int m = 0; m < 4; ++m) _Pragma("unroll") for (int k = 0; k < 2; ++k) dst[m][k] = *(const PG8_LAS bf16x8*)(lds + PG8_SA(b, h) + aoff + m * 2048 + k * 1024); } while (0)
; #define PG8_LDB(dst, b, h) do { _Pragma("unroll") for (int n = 0; n < 2; ++n) _Pragma("unroll") for (int k = 0; k < 2; ++k) dst[n][k] = *(const PG8_LAS bf16x8*)(lds + PG8_SB(b, h) + boff + n * 2048 + k * 1024); } while (0)
; #define PG8_MMA(ai, bj, At, Bt) do { __builtin_amdgcn_s_setprio(1); _Pragma("unroll") for (int m = 0; m < 4; ++m) _Pragma("unroll") for (int n = 0; n < 2; ++n) _Pragma("unroll") for (int k = 0; k < 2; ++k) \
;         acc[ai][bj][m][n] = __builtin_amdgcn_mfma_f32_16x16x32_bf16(Bt[n][k], At[m][k], acc[ai][bj][m][n], 0, 0, 0); __builtin_amdgcn_s_setprio(0); } while (0)
; #define PG8_WAIT_V(n) asm volatile("s_waitcnt vmcnt(" #n ")" ::: "memory")
; #define PG8_WAIT_L(n) asm volatile("s_waitcnt lgkmcnt(" #n ")" ::: "memory")
; #define PG8_BAR __builtin_amdgcn_s_barrier()
; #define PG8_SCHED __builtin_amdgcn_sched_barrier(0)
; template <class Epi, class Sched, bool ALIGN_EPI = false, bool SP2 = false>
; __device__ __forceinline__ void gemm_phase(PG8_LAS unsigned char* lds, const Gemm g, const Sched& S, const Epi& E, const int wid) {
;     ...
;             const char* a2 = last ? nA : cA + (size_t)(t + 2) * kstep; const char* b2 = last ? nB : cB + (size_t)(t + 2) * kstep;
;             const char* a3 = a2 + kstep; const char* b3 = b2 + kstep;
;             if (last && has_next) S.a_ready(nxt);
;             if constexpr (SP2) {
;             PG8_LDB(B0, 0, 0); PG8_LDB(B1, 0, 1); PG8_SCHED; PG8_LDA(At, 0, 0); PG8_STAGE(PG8_SA(1, 1), a1 + hstep, voffA);
;             PG8_WAIT_V(8); PG8_WAIT_L(0); PG8_BAR; PG8_MMA(0, 0, At, B0); PG8_MMA(0, 1, At, B1); PG8_BAR; PG8_SCHED;
;             PG8_LDA(At, 0, 1); PG8_STAGE(PG8_SB(0, 0), b2, voffB); PG8_STAGE(PG8_SB(0, 1), b2 + hstep, voffB); PG8_STAGE(PG8_SA(0, 0), a2, voffA);
;             PG8_WAIT_V(8); PG8_WAIT_L(0); PG8_BAR; PG8_MMA(1, 0, At, B0); PG8_MMA(1, 1, At, B1); PG8_BAR; PG8_SCHED;
.LBB0_1670:
	s_ashr_i32 s15, s14, 31
	s_lshl_b64 s[16:17], s[14:15], 22
	s_add_u32 s16, s82, s16
	s_addc_u32 s17, s83, s17
	s_and_b64 s[18:19], s[2:3], exec
	s_cselect_b32 s15, s17, s25
	s_cselect_b32 s21, s16, s24
	s_ashr_i32 s13, s12, 31
	s_lshl_b64 s[18:19], s[12:13], 22
	s_add_u32 s18, s30, s18
	s_addc_u32 s19, s31, s19
	s_and_b64 s[28:29], s[2:3], exec
	s_cselect_b32 s13, s19, s27
	s_cselect_b32 s23, s18, s26
	s_add_u32 s24, s24, 0x200080
	s_addc_u32 s25, s25, 0
	s_add_u32 s48, s26, 0x100
	s_addc_u32 s49, s27, 0
	s_mov_b32 s50, -2
	v_add_u32_e32 v246, 0x18000, v195
	v_add_u32_e32 v248, 0x1c000, v195
	ds_read_b128 v[128:131], v197
	ds_read_b128 v[132:135], v197 offset:1024
	ds_read_b128 v[136:139], v197 offset:2048
	ds_read_b128 v[140:143], v197 offset:3072
	ds_read_b128 v[144:147], v198
	ds_read_b128 v[148:151], v198 offset:1024
	ds_read_b128 v[176:179], v198 offset:2048
	ds_read_b128 v[180:183], v198 offset:3072
	s_add_u32 s26, s24, 0xffe00080
	s_addc_u32 s27, s25, -1
	s_cmpk_eq_i32 s50, 0x7c
	s_cselect_b32 s29, s15, s27
	s_cselect_b32 s28, s21, s26
	s_cselect_b32 s27, s13, s49
	s_cselect_b32 s26, s23, s48
	s_add_i32 m0, s35, 0xc000
	ds_read_b128 v[184:187], v199
	ds_read_b128 v[188:191], v199 offset:1024
	ds_read_b128 v[200:203], v199 offset:2048
	ds_read_b128 v[204:207], v199 offset:3072
	ds_read_b128 v[208:211], v199 offset:4096
	ds_read_b128 v[212:215], v199 offset:5120
	ds_read_b128 v[216:219], v199 offset:6144
	ds_read_b128 v[220:223], v199 offset:7168
	global_load_lds_dwordx4 v168, s[24:25]
	s_add_i32 m0, s35, 0xe000
	s_nop 0
	global_load_lds_dwordx4 v170, s[24:25]
	s_waitcnt vmcnt(8)
	s_waitcnt lgkmcnt(0)
	s_setprio 1
	s_barrier
	v_mfma_f32_16x16x32_bf16 v[60:63], v[128:131], v[184:187], 0
	v_mfma_f32_16x16x32_bf16 v[56:59], v[136:139], v[184:187], 0
	v_mfma_f32_16x16x32_bf16 v[44:47], v[128:131], v[200:203], 0
	v_mfma_f32_16x16x32_bf16 v[40:43], v[136:139], v[200:203], 0
	v_mfma_f32_16x16x32_bf16 v[28:31], v[128:131], v[208:211], 0
	v_mfma_f32_16x16x32_bf16 v[24:27], v[136:139], v[208:211], 0
	v_mfma_f32_16x16x32_bf16 v[12:15], v[128:131], v[216:219], 0
	v_mfma_f32_16x16x32_bf16 v[8:11], v[136:139], v[216:219], 0
	v_mfma_f32_16x16x32_bf16 v[60:63], v[132:135], v[188:191], v[60:63]
	v_mfma_f32_16x16x32_bf16 v[56:59], v[140:143], v[188:191], v[56:59]
	v_mfma_f32_16x16x32_bf16 v[44:47], v[132:135], v[204:207], v[44:47]
	v_mfma_f32_16x16x32_bf16 v[40:43], v[140:143], v[204:207], v[40:43]
	v_mfma_f32_16x16x32_bf16 v[28:31], v[132:135], v[212:215], v[28:31]
	v_mfma_f32_16x16x32_bf16 v[24:27], v[140:143], v[212:215], v[24:27]
	v_mfma_f32_16x16x32_bf16 v[12:15], v[132:135], v[220:223], v[12:15]
	v_mfma_f32_16x16x32_bf16 v[8:11], v[140:143], v[220:223], v[8:11]
	v_mfma_f32_16x16x32_bf16 v[52:55], v[144:147], v[184:187], 0
	v_mfma_f32_16x16x32_bf16 v[48:51], v[176:179], v[184:187], 0
	v_mfma_f32_16x16x32_bf16 v[36:39], v[144:147], v[200:203], 0
	v_mfma_f32_16x16x32_bf16 v[32:35], v[176:179], v[200:203], 0
	v_mfma_f32_16x16x32_bf16 v[20:23], v[144:147], v[208:211], 0
	v_mfma_f32_16x16x32_bf16 v[16:19], v[176:179], v[208:211], 0
	v_mfma_f32_16x16x32_bf16 v[4:7], v[144:147], v[216:219], 0
	v_mfma_f32_16x16x32_bf16 v[0:3], v[176:179], v[216:219], 0
	v_mfma_f32_16x16x32_bf16 v[52:55], v[148:151], v[188:191], v[52:55]
	v_mfma_f32_16x16x32_bf16 v[48:51], v[180:183], v[188:191], v[48:51]
	v_mfma_f32_16x16x32_bf16 v[36:39], v[148:151], v[204:207], v[36:39]
	v_mfma_f32_16x16x32_bf16 v[32:35], v[180:183], v[204:207], v[32:35]
	v_mfma_f32_16x16x32_bf16 v[20:23], v[148:151], v[212:215], v[20:23]
	v_mfma_f32_16x16x32_bf16 v[16:19], v[180:183], v[212:215], v[16:19]
	v_mfma_f32_16x16x32_bf16 v[4:7], v[148:151], v[220:223], v[4:7]
	v_mfma_f32_16x16x32_bf16 v[0:3], v[180:183], v[220:223], v[0:3]
	s_barrier
	s_setprio 0
	s_add_i32 s51, s44, s34
	s_mov_b32 m0, s51
	ds_read_b128 v[184:187], v199 offset:16384
	ds_read_b128 v[188:191], v199 offset:17408
	ds_read_b128 v[200:203], v199 offset:18432
	ds_read_b128 v[204:207], v199 offset:19456
	ds_read_b128 v[208:211], v199 offset:20480
	ds_read_b128 v[212:215], v199 offset:21504
	ds_read_b128 v[216:219], v199 offset:22528
	ds_read_b128 v[220:223], v199 offset:23552
	global_load_lds_dwordx4 v154, s[26:27]
	s_add_i32 m0, s51, 0x2000
	s_add_u32 s52, s26, 0x200000
	s_addc_u32 s53, s27, 0
	s_add_i32 s51, s45, s34
	global_load_lds_dwordx4 v158, s[26:27]
	s_mov_b32 m0, s51
	global_load_lds_dwordx4 v154, s[52:53]
	s_add_i32 m0, s51, 0x2000
	s_nop 0
	global_load_lds_dwordx4 v158, s[52:53]
	s_mov_b32 m0, s35
	s_nop 0
	global_load_lds_dwordx4 v152, s[28:29]
	s_mov_b32 m0, s36
	s_nop 0
	global_load_lds_dwordx4 v156, s[28:29]
	s_waitcnt vmcnt(8)
	s_waitcnt lgkmcnt(0)
	s_setprio 1
	s_barrier
; #define PG8_STAGE(bufoff, gbase, voff) do { _Pragma("unroll") for (int _i = 0; _i < 2; ++_i) \
;         __builtin_amdgcn_global_load_lds((const unsigned*)((const char*)(gbase) + (voff)[_i]), (PG8_LAS unsigned*)(lds + (bufoff) + ldsw + _i * 8192), 16, 0, 0); } while (0)
; #define PG8_LDA(dst, b, h) do { _Pragma("unroll") for (int m = 0; m < 4; ++m) _Pragma("unroll") for (int k = 0; k < 2; ++k) dst[m][k] = *(const PG8_LAS bf16x8*)(lds + PG8_SA(b, h) + aoff + m * 2048 + k * 1024); } while (0)
; #define PG8_LDB(dst, b, h) do { _Pragma("unroll") for (int n = 0; n < 2; ++n) _Pragma("unroll") for (int k = 0; k < 2; ++k) dst[n][k] = *(const PG8_LAS bf16x8*)(lds + PG8_SB(b, h) + boff + n * 2048 + k * 1024); } while (0)
; #define PG8_MMA(ai, bj, At, Bt) do { __builtin_amdgcn_s_setprio(1); _Pragma("unroll") for (int m = 0; m < 4; ++m) _Pragma("unroll") for (int n = 0; n < 2; ++n) _Pragma("unroll") for (int k = 0; k < 2; ++k) \
;         acc[ai][bj][m][n] = __builtin_amdgcn_mfma_f32_16x16x32_bf16(Bt[n][k], At[m][k], acc[ai][bj][m][n], 0, 0, 0); __builtin_amdgcn_s_setprio(0); } while (0)
; #define PG8_WAIT_V(n) asm volatile("s_waitcnt vmcnt(" #n ")" ::: "memory")
; #define PG8_WAIT_L(n) asm volatile("s_waitcnt lgkmcnt(" #n ")" ::: "memory")
; #define PG8_BAR __builtin_amdgcn_s_barrier()
; #define PG8_SCHED __builtin_amdgcn_sched_barrier(0)
; template <class Epi, class Sched, bool ALIGN_EPI = false, bool SP2 = false>
; __device__ __forceinline__ void gemm_phase(PG8_LAS unsigned char* lds, const Gemm g, const Sched& S, const Epi& E, const int wid) {
;     ...
;             PG8_WAIT_V(8); PG8_WAIT_L(0); PG8_BAR; PG8_MMA(1, 0, At, B0); PG8_MMA(1, 1, At, B1); PG8_BAR; PG8_SCHED;
;             PG8_LDB(B0, 1, 0); PG8_LDB(B1, 1, 1); PG8_SCHED; PG8_LDA(At, 1, 0); PG8_STAGE(PG8_SA(0, 1), a2 + hstep, voffA);
;             PG8_WAIT_V(8); PG8_WAIT_L(0); PG8_BAR; PG8_MMA(0, 0, At, B0); PG8_MMA(0, 1, At, B1); PG8_BAR; PG8_SCHED;
	v_mfma_f32_16x16x32_bf16 v[124:127], v[128:131], v[184:187], 0
	v_mfma_f32_16x16x32_bf16 v[120:123], v[136:139], v[184:187], 0
	v_mfma_f32_16x16x32_bf16 v[108:111], v[128:131], v[200:203], 0
	v_mfma_f32_16x16x32_bf16 v[104:107], v[136:139], v[200:203], 0
	v_mfma_f32_16x16x32_bf16 v[92:95], v[128:131], v[208:211], 0
	v_mfma_f32_16x16x32_bf16 v[88:91], v[136:139], v[208:211], 0
	v_mfma_f32_16x16x32_bf16 v[76:79], v[128:131], v[216:219], 0
	v_mfma_f32_16x16x32_bf16 v[72:75], v[136:139], v[216:219], 0
	v_mfma_f32_16x16x32_bf16 v[124:127], v[132:135], v[188:191], v[124:127]
	v_mfma_f32_16x16x32_bf16 v[120:123], v[140:143], v[188:191], v[120:123]
	v_mfma_f32_16x16x32_bf16 v[108:111], v[132:135], v[204:207], v[108:111]
	v_mfma_f32_16x16x32_bf16 v[104:107], v[140:143], v[204:207], v[104:107]
	v_mfma_f32_16x16x32_bf16 v[92:95], v[132:135], v[212:215], v[92:95]
	v_mfma_f32_16x16x32_bf16 v[88:91], v[140:143], v[212:215], v[88:91]
	v_mfma_f32_16x16x32_bf16 v[76:79], v[132:135], v[220:223], v[76:79]
	v_mfma_f32_16x16x32_bf16 v[72:75], v[140:143], v[220:223], v[72:75]
	v_mfma_f32_16x16x32_bf16 v[116:119], v[144:147], v[184:187], 0
	v_mfma_f32_16x16x32_bf16 v[112:115], v[176:179], v[184:187], 0
	v_mfma_f32_16x16x32_bf16 v[100:103], v[144:147], v[200:203], 0
	v_mfma_f32_16x16x32_bf16 v[96:99], v[176:179], v[200:203], 0
	v_mfma_f32_16x16x32_bf16 v[84:87], v[144:147], v[208:211], 0
	v_mfma_f32_16x16x32_bf16 v[80:83], v[176:179], v[208:211], 0
	v_mfma_f32_16x16x32_bf16 v[68:71], v[144:147], v[216:219], 0
	v_mfma_f32_16x16x32_bf16 v[64:67], v[176:179], v[216:219], 0
	v_mfma_f32_16x16x32_bf16 v[116:119], v[148:151], v[188:191], v[116:119]
	v_mfma_f32_16x16x32_bf16 v[112:115], v[180:183], v[188:191], v[112:115]
	v_mfma_f32_16x16x32_bf16 v[100:103], v[148:151], v[204:207], v[100:103]
	v_mfma_f32_16x16x32_bf16 v[96:99], v[180:183], v[204:207], v[96:99]
	v_mfma_f32_16x16x32_bf16 v[84:87], v[148:151], v[212:215], v[84:87]
	v_mfma_f32_16x16x32_bf16 v[80:83], v[180:183], v[212:215], v[80:83]
	v_mfma_f32_16x16x32_bf16 v[68:71], v[148:151], v[220:223], v[68:71]
	v_mfma_f32_16x16x32_bf16 v[64:67], v[180:183], v[220:223], v[64:67]
	s_barrier
	s_setprio 0
	s_add_i32 s51, 0, 0x18000
	s_add_i32 s52, 0, 0x1c000
	ds_read_b128 v[128:131], v246
	ds_read_b128 v[132:135], v246 offset:1024
	ds_read_b128 v[136:139], v246 offset:2048
	ds_read_b128 v[140:143], v246 offset:3072
	ds_read_b128 v[144:147], v248
	ds_read_b128 v[148:151], v248 offset:1024
	ds_read_b128 v[176:179], v248 offset:2048
	ds_read_b128 v[180:183], v248 offset:3072
	s_add_u32 s28, s28, 0x200000
	s_addc_u32 s29, s29, 0
	s_mov_b32 m0, s37
	ds_read_b128 v[184:187], v199 offset:32768
	ds_read_b128 v[188:191], v199 offset:33792
	ds_read_b128 v[200:203], v199 offset:34816
	ds_read_b128 v[204:207], v199 offset:35840
	ds_read_b128 v[208:211], v199 offset:36864
	ds_read_b128 v[212:215], v199 offset:37888
	ds_read_b128 v[216:219], v199 offset:38912
	ds_read_b128 v[220:223], v199 offset:39936
	global_load_lds_dwordx4 v152, s[28:29]
	s_mov_b32 m0, s38
	s_nop 0
	global_load_lds_dwordx4 v156, s[28:29]
	s_waitcnt vmcnt(8)
	s_waitcnt lgkmcnt(0)
	s_setprio 1
	s_barrier
	v_mfma_f32_16x16x32_bf16 v[60:63], v[128:131], v[184:187], v[60:63]
	v_mfma_f32_16x16x32_bf16 v[56:59], v[136:139], v[184:187], v[56:59]
	v_mfma_f32_16x16x32_bf16 v[44:47], v[128:131], v[200:203], v[44:47]
	v_mfma_f32_16x16x32_bf16 v[40:43], v[136:139], v[200:203], v[40:43]
	v_mfma_f32_16x16x32_bf16 v[28:31], v[128:131], v[208:211], v[28:31]
	v_mfma_f32_16x16x32_bf16 v[24:27], v[136:139], v[208:211], v[24:27]
	v_mfma_f32_16x16x32_bf16 v[12:15], v[128:131], v[216:219], v[12:15]
	v_mfma_f32_16x16x32_bf16 v[8:11], v[136:139], v[216:219], v[8:11]
	v_mfma_f32_16x16x32_bf16 v[60:63], v[132:135], v[188:191], v[60:63]
	v_mfma_f32_16x16x32_bf16 v[56:59], v[140:143], v[188:191], v[56:59]
	v_mfma_f32_16x16x32_bf16 v[44:47], v[132:135], v[204:207], v[44:47]
	v_mfma_f32_16x16x32_bf16 v[40:43], v[140:143], v[204:207], v[40:43]
	v_mfma_f32_16x16x32_bf16 v[28:31], v[132:135], v[212:215], v[28:31]
	v_mfma_f32_16x16x32_bf16 v[24:27], v[140:143], v[212:215], v[24:27]
	v_mfma_f32_16x16x32_bf16 v[12:15], v[132:135], v[220:223], v[12:15]
	v_mfma_f32_16x16x32_bf16 v[8:11], v[140:143], v[220:223], v[8:11]
	v_mfma_f32_16x16x32_bf16 v[52:55], v[144:147], v[184:187], v[52:55]
	v_mfma_f32_16x16x32_bf16 v[48:51], v[176:179], v[184:187], v[48:51]
	v_mfma_f32_16x16x32_bf16 v[36:39], v[144:147], v[200:203], v[36:39]
	v_mfma_f32_16x16x32_bf16 v[32:35], v[176:179], v[200:203], v[32:35]
	v_mfma_f32_16x16x32_bf16 v[20:23], v[144:147], v[208:211], v[20:23]
	v_mfma_f32_16x16x32_bf16 v[16:19], v[176:179], v[208:211], v[16:19]
	v_mfma_f32_16x16x32_bf16 v[4:7], v[144:147], v[216:219], v[4:7]
	v_mfma_f32_16x16x32_bf16 v[0:3], v[176:179], v[216:219], v[0:3]
	v_mfma_f32_16x16x32_bf16 v[52:55], v[148:151], v[188:191], v[52:55]
	v_mfma_f32_16x16x32_bf16 v[48:51], v[180:183], v[188:191], v[48:51]
	v_mfma_f32_16x16x32_bf16 v[36:39], v[148:151], v[204:207], v[36:39]
	v_mfma_f32_16x16x32_bf16 v[32:35], v[180:183], v[204:207], v[32:35]
	v_mfma_f32_16x16x32_bf16 v[20:23], v[148:151], v[212:215], v[20:23]
	v_mfma_f32_16x16x32_bf16 v[16:19], v[180:183], v[212:215], v[16:19]
	v_mfma_f32_16x16x32_bf16 v[4:7], v[148:151], v[220:223], v[4:7]
	v_mfma_f32_16x16x32_bf16 v[0:3], v[180:183], v[220:223], v[0:3]
	s_barrier
; #define PG8_STAGE(bufoff, gbase, voff) do { _Pragma("unroll") for (int _i = 0; _i < 2; ++_i) \
;         __builtin_amdgcn_global_load_lds((const unsigned*)((const char*)(gbase) + (voff)[_i]), (PG8_LAS unsigned*)(lds + (bufoff) + ldsw + _i * 8192), 16, 0, 0); } while (0)
; #define PG8_LDA(dst, b, h) do { _Pragma("unroll") for (int m = 0; m < 4; ++m) _Pragma("unroll") for (int k = 0; k < 2; ++k) dst[m][k] = *(const PG8_LAS bf16x8*)(lds + PG8_SA(b, h) + aoff + m * 2048 + k * 1024); } while (0)
; #define PG8_WAIT_V(n) asm volatile("s_waitcnt vmcnt(" #n ")" ::: "memory")
; #define PG8_WAIT_L(n) asm volatile("s_waitcnt lgkmcnt(" #n ")" ::: "memory")
; #define PG8_BAR __builtin_amdgcn_s_barrier()
; template <class Epi, class Sched, bool ALIGN_EPI = false, bool SP2 = false>
; __device__ __forceinline__ void gemm_phase(PG8_LAS unsigned char* lds, const Gemm g, const Sched& S, const Epi& E, const int wid) {
;     ...
;         for (int t = 0; t < nt; t += 2) {
;             const bool last = (t == nt - 2);
;             const char* a1 = cA + (size_t)(t + 1) * kstep;
;             const char* a2 = last ? nA : cA + (size_t)(t + 2) * kstep; const char* b2 = last ? nB : cB + (size_t)(t + 2) * kstep;
;             const char* a3 = a2 + kstep; const char* b3 = b2 + kstep;
;             if (last && has_next) S.a_ready(nxt);
;             if constexpr (SP2) {
;             PG8_LDB(B0, 0, 0); PG8_LDB(B1, 0, 1); PG8_SCHED; PG8_LDA(At, 0, 0); PG8_STAGE(PG8_SA(1, 1), a1 + hstep, voffA);
;             PG8_WAIT_V(8); PG8_WAIT_L(0); PG8_BAR; PG8_MMA(0, 0, At, B0); PG8_MMA(0, 1, At, B1); PG8_BAR; PG8_SCHED;
;             PG8_LDA(At, 0, 1); PG8_STAGE(PG8_SB(0, 0), b2, voffB); PG8_STAGE(PG8_SB(0, 1), b2 + hstep, voffB); PG8_STAGE(PG8_SA(0, 0), a2, voffA);
;             PG8_WAIT_V(8); PG8_WAIT_L(0); PG8_BAR; PG8_MMA(1, 0, At, B0); PG8_MMA(1, 1, At, B1); PG8_BAR; PG8_SCHED;
;             PG8_LDB(B0, 1, 0); PG8_LDB(B1, 1, 1); PG8_SCHED; PG8_LDA(At, 1, 0); PG8_STAGE(PG8_SA(0, 1), a2 + hstep, voffA);
;             PG8_WAIT_V(8); PG8_WAIT_L(0); PG8_BAR; PG8_MMA(0, 0, At, B0); PG8_MMA(0, 1, At, B1); PG8_BAR; PG8_SCHED;
;             PG8_LDA(At, 1, 1); PG8_STAGE(PG8_SB(1, 0), b3, voffB); PG8_STAGE(PG8_SB(1, 1), b3 + hstep, voffB); PG8_STAGE(PG8_SA(1, 0), a3, voffA);
;             PG8_WAIT_V(8); PG8_WAIT_L(0); PG8_BAR; PG8_MMA(1, 0, At, B0); PG8_MMA(1, 1, At, B1); PG8_BAR; PG8_SCHED;
	s_setprio 0
	s_add_u32 s98, s26, 0x80
	s_addc_u32 s99, s27, 0
	s_add_u32 s100, s28, 0xffe00080
	s_addc_u32 s101, s29, -1
	s_add_i32 s28, s51, s34
	s_mov_b32 m0, s28
	ds_read_b128 v[184:187], v199 offset:49152
	ds_read_b128 v[188:191], v199 offset:50176
	ds_read_b128 v[200:203], v199 offset:51200
	ds_read_b128 v[204:207], v199 offset:52224
	ds_read_b128 v[208:211], v199 offset:53248
	ds_read_b128 v[212:215], v199 offset:54272
	ds_read_b128 v[216:219], v199 offset:55296
	ds_read_b128 v[220:223], v199 offset:56320
	global_load_lds_dwordx4 v154, s[98:99]
	s_add_i32 m0, s28, 0x2000
	s_add_u32 s26, s26, 0x200080
	s_addc_u32 s27, s27, 0
	s_add_i32 s28, s52, s34
	global_load_lds_dwordx4 v158, s[98:99]
	s_mov_b32 m0, s28
	s_nop 0
	global_load_lds_dwordx4 v154, s[26:27]
	s_add_i32 m0, s28, 0x2000
	s_nop 0
	global_load_lds_dwordx4 v158, s[26:27]
	s_mov_b32 m0, s40
	s_nop 0
	global_load_lds_dwordx4 v152, s[100:101]
	s_mov_b32 m0, s41
	s_nop 0
	global_load_lds_dwordx4 v156, s[100:101]
	s_waitcnt vmcnt(8)
	s_waitcnt lgkmcnt(0)
	s_setprio 1
	s_barrier
	v_mfma_f32_16x16x32_bf16 v[124:127], v[128:131], v[184:187], v[124:127]
	v_mfma_f32_16x16x32_bf16 v[120:123], v[136:139], v[184:187], v[120:123]
	v_mfma_f32_16x16x32_bf16 v[108:111], v[128:131], v[200:203], v[108:111]
	v_mfma_f32_16x16x32_bf16 v[104:107], v[136:139], v[200:203], v[104:107]
	v_mfma_f32_16x16x32_bf16 v[92:95], v[128:131], v[208:211], v[92:95]
	v_mfma_f32_16x16x32_bf16 v[88:91], v[136:139], v[208:211], v[88:91]
	v_mfma_f32_16x16x32_bf16 v[76:79], v[128:131], v[216:219], v[76:79]
	v_mfma_f32_16x16x32_bf16 v[72:75], v[136:139], v[216:219], v[72:75]
	v_mfma_f32_16x16x32_bf16 v[124:127], v[132:135], v[188:191], v[124:127]
	v_mfma_f32_16x16x32_bf16 v[120:123], v[140:143], v[188:191], v[120:123]
	v_mfma_f32_16x16x32_bf16 v[108:111], v[132:135], v[204:207], v[108:111]
	v_mfma_f32_16x16x32_bf16 v[104:107], v[140:143], v[204:207], v[104:107]
	v_mfma_f32_16x16x32_bf16 v[92:95], v[132:135], v[212:215], v[92:95]
	v_mfma_f32_16x16x32_bf16 v[88:91], v[140:143], v[212:215], v[88:91]
	v_mfma_f32_16x16x32_bf16 v[76:79], v[132:135], v[220:223], v[76:79]
	v_mfma_f32_16x16x32_bf16 v[72:75], v[140:143], v[220:223], v[72:75]
	v_mfma_f32_16x16x32_bf16 v[116:119], v[144:147], v[184:187], v[116:119]
	v_mfma_f32_16x16x32_bf16 v[112:115], v[176:179], v[184:187], v[112:115]
	v_mfma_f32_16x16x32_bf16 v[100:103], v[144:147], v[200:203], v[100:103]
	v_mfma_f32_16x16x32_bf16 v[96:99], v[176:179], v[200:203], v[96:99]
	v_mfma_f32_16x16x32_bf16 v[84:87], v[144:147], v[208:211], v[84:87]
	v_mfma_f32_16x16x32_bf16 v[80:83], v[176:179], v[208:211], v[80:83]
	v_mfma_f32_16x16x32_bf16 v[68:71], v[144:147], v[216:219], v[68:71]
	v_mfma_f32_16x16x32_bf16 v[64:67], v[176:179], v[216:219], v[64:67]
	v_mfma_f32_16x16x32_bf16 v[116:119], v[148:151], v[188:191], v[116:119]
	v_mfma_f32_16x16x32_bf16 v[112:115], v[180:183], v[188:191], v[112:115]
	v_mfma_f32_16x16x32_bf16 v[100:103], v[148:151], v[204:207], v[100:103]
	v_mfma_f32_16x16x32_bf16 v[96:99], v[180:183], v[204:207], v[96:99]
	v_mfma_f32_16x16x32_bf16 v[84:87], v[148:151], v[212:215], v[84:87]
	v_mfma_f32_16x16x32_bf16 v[80:83], v[180:183], v[212:215], v[80:83]
	v_mfma_f32_16x16x32_bf16 v[68:71], v[148:151], v[220:223], v[68:71]
	v_mfma_f32_16x16x32_bf16 v[64:67], v[180:183], v[220:223], v[64:67]
	s_barrier
	s_setprio 0
	s_add_i32 s50, s50, 2
	s_add_u32 s24, s24, 0x100
	s_addc_u32 s25, s25, 0
	s_add_u32 s48, s48, 0x100
	s_addc_u32 s49, s49, 0
	s_cmpk_gt_u32 s50, 0x7d
	s_cbranch_scc0 .LBB0_1671
	s_branch .Lpeel_exit_5

;     __device__ __forceinline__ void operator()(const f32x4 (&acc)[2][2][4][2], const Unit& u, int wr, int wc, int fr, int fq) const {
;         const int row0 = u.pm * BM + wr * 64 + fr, col0 = u.pn * BM + wc * 32 + 8 * fq;
;         if (u.pm == MTOK / BM) {
; template <class Epi, class Sched, bool ALIGN_EPI = false, bool SP2 = false>
; __device__ __forceinline__ void gemm_phase(PG8_LAS unsigned char* lds, const Gemm g, const Sched& S, const Epi& E, const int wid) {
;     ...
;         if (!has_next) break;
.Lpeel_exit_5:
	s_and_b64 vcc, exec, s[10:11]
	s_cbranch_vccnz .LBB0_1675
	v_lshl_add_u32 v176, s22, 8, v196
	s_cmp_eq_u32 s20, 64
	s_mov_b64 s[22:23], -1
	s_cbranch_scc0 .LBB0_1676

; __device__ __forceinline__ float fx_to_pos(u64 x) { return (float)(unsigned)(x >> 32) + (float)(unsigned)x * (1.0f / 4294967296.0f); }
; #define PG8_STAGE(bufoff, gbase, voff) do { _Pragma("unroll") for (int _i = 0; _i < 2; ++_i) \
;         __builtin_amdgcn_global_load_lds((const unsigned*)((const char*)(gbase) + (voff)[_i]), (PG8_LAS unsigned*)(lds + (bufoff) + ldsw + _i * 8192), 16, 0, 0); } while (0)
; #define PG8_LDA(dst, b, h) do { _Pragma("unroll") for (int m = 0; m < 4; ++m) _Pragma("unroll") for (int k = 0; k < 2; ++k) dst[m][k] = *(const PG8_LAS bf16x8*)(lds + PG8_SA(b, h) + aoff + m * 2048 + k * 1024); } while (0)
; #define PG8_LDB(dst, b, h) do { _Pragma("unroll") for (int n = 0; n < 2; ++n) _Pragma("unroll") for (int k = 0; k < 2; ++k) dst[n][k] = *(const PG8_LAS bf16x8*)(lds + PG8_SB(b, h) + boff + n * 2048 + k * 1024); } while (0)
; #define PG8_WAIT_V(n) asm volatile("s_waitcnt vmcnt(" #n ")" ::: "memory")
; #define PG8_WAIT_L(n) asm volatile("s_waitcnt lgkmcnt(" #n ")" ::: "memory")
; #define PG8_BAR __builtin_amdgcn_s_barrier()
; __device__ __forceinline__ float row_rstd(const u64* ssq, int r) { return __builtin_amdgcn_rsqf(fx_to_pos(ssq[r]) * (1.0f / 4096.0f) + RMS_EPS); }
; template <class Epi, class Sched, bool ALIGN_EPI = false, bool SP2 = false>
; __device__ __forceinline__ void gemm_phase(PG8_LAS unsigned char* lds, const Gemm g, const Sched& S, const Epi& E, const int wid) {
;     ...
;         for (int t = 0; t < nt; t += 2) {
;             const bool last = (t == nt - 2);
;             const char* a1 = cA + (size_t)(t + 1) * kstep;
;             const char* a2 = last ? nA : cA + (size_t)(t + 2) * kstep; const char* b2 = last ? nB : cB + (size_t)(t + 2) * kstep;
;             const char* a3 = a2 + kstep; const char* b3 = b2 + kstep;
;             if (last && has_next) S.a_ready(nxt);
;             if constexpr (SP2) {
;             PG8_LDB(B0, 0, 0); PG8_LDB(B1, 0, 1); PG8_SCHED; PG8_LDA(At, 0, 0); PG8_STAGE(PG8_SA(1, 1), a1 + hstep, voffA);
;             PG8_WAIT_V(8); PG8_WAIT_L(0); PG8_BAR; PG8_MMA(0, 0, At, B0); PG8_MMA(0, 1, At, B1); PG8_BAR; PG8_SCHED;
;             PG8_LDA(At, 0, 1); PG8_STAGE(PG8_SB(0, 0), b2, voffB); PG8_STAGE(PG8_SB(0, 1), b2 + hstep, voffB); PG8_STAGE(PG8_SA(0, 0), a2, voffA);
;             PG8_WAIT_V(8); PG8_WAIT_L(0); PG8_BAR; PG8_MMA(1, 0, At, B0); PG8_MMA(1, 1, At, B1); PG8_BAR; PG8_SCHED;
.LBB0_1763:
	s_ashr_i32 s15, s14, 31
	s_lshl_b64 s[16:17], s[14:15], 21
	s_add_u32 s16, s78, s16
	s_addc_u32 s17, s79, s17
	s_and_b64 s[18:19], s[0:1], exec
	s_cselect_b32 s15, s17, s23
	s_cselect_b32 s47, s16, s22
	s_ashr_i32 s13, s12, 31
	s_lshl_b64 s[18:19], s[12:13], 21
	s_add_u32 s18, s38, s18
	s_addc_u32 s19, s39, s19
	s_and_b64 s[26:27], s[0:1], exec
	s_cselect_b32 s13, s19, s25
	s_cselect_b32 s48, s18, s24
	s_add_u32 s22, s22, 0x100080
	s_addc_u32 s23, s23, 0
	s_add_u32 s49, s24, 0x100
	s_addc_u32 s50, s25, 0
	s_mov_b32 s51, -2
	v_add_u32_e32 v246, 0x18000, v152
	v_add_u32_e32 v248, 0x1c000, v152
	ds_read_b128 v[146:149], v154
	ds_read_b128 v[158:161], v154 offset:1024
	ds_read_b128 v[162:165], v154 offset:2048
	ds_read_b128 v[166:169], v154 offset:3072
	ds_read_b128 v[170:173], v155
	ds_read_b128 v[174:177], v155 offset:1024
	ds_read_b128 v[178:181], v155 offset:2048
	ds_read_b128 v[182:185], v155 offset:3072
	s_add_u32 s24, s22, 0xfff00080
	s_addc_u32 s25, s23, -1
	s_cmp_eq_u32 s51, 60
	s_cselect_b32 s27, s15, s25
	s_cselect_b32 s26, s47, s24
	s_cselect_b32 s25, s13, s50
	s_cselect_b32 s24, s48, s49
	s_add_i32 m0, s21, 0xc000
	ds_read_b128 v[186:189], v156
	ds_read_b128 v[190:193], v156 offset:1024
	ds_read_b128 v[194:197], v156 offset:2048
	ds_read_b128 v[198:201], v156 offset:3072
	ds_read_b128 v[202:205], v156 offset:4096
	ds_read_b128 v[206:209], v156 offset:5120
	ds_read_b128 v[210:213], v156 offset:6144
	ds_read_b128 v[214:217], v156 offset:7168
	global_load_lds_dwordx4 v138, s[22:23]
	s_add_i32 m0, s21, 0xe000
	s_nop 0
	global_load_lds_dwordx4 v140, s[22:23]
	s_waitcnt vmcnt(8)
	s_waitcnt lgkmcnt(0)
	v_lshl_add_u32 v244, s20, 8, v151
	v_ashrrev_i32_e32 v245, 31, v244
	v_lshl_add_u64 v[244:245], v[244:245], 3, s[4:5]
	global_load_dwordx2 v[228:229], v[244:245], off
	global_load_dwordx2 v[230:231], v[244:245], off offset:128
	global_load_dwordx2 v[232:233], v[244:245], off offset:256
	global_load_dwordx2 v[234:235], v[244:245], off offset:384
	global_load_dwordx2 v[236:237], v[244:245], off offset:1024
	global_load_dwordx2 v[238:239], v[244:245], off offset:1152
	global_load_dwordx2 v[240:241], v[244:245], off offset:1280
	global_load_dwordx2 v[242:243], v[244:245], off offset:1408
	s_setprio 1
	s_barrier
	v_mfma_f32_16x16x32_bf16 v[124:127], v[146:149], v[186:189], 0
	v_mfma_f32_16x16x32_bf16 v[120:123], v[162:165], v[186:189], 0
	v_mfma_f32_16x16x32_bf16 v[108:111], v[146:149], v[194:197], 0
	v_mfma_f32_16x16x32_bf16 v[104:107], v[162:165], v[194:197], 0
	v_mfma_f32_16x16x32_bf16 v[92:95], v[146:149], v[202:205], 0
	v_mfma_f32_16x16x32_bf16 v[88:91], v[162:165], v[202:205], 0
	v_mfma_f32_16x16x32_bf16 v[76:79], v[146:149], v[210:213], 0
	v_mfma_f32_16x16x32_bf16 v[72:75], v[162:165], v[210:213], 0
	v_mfma_f32_16x16x32_bf16 v[124:127], v[158:161], v[190:193], v[124:127]
	v_mfma_f32_16x16x32_bf16 v[120:123], v[166:169], v[190:193], v[120:123]
	v_mfma_f32_16x16x32_bf16 v[108:111], v[158:161], v[198:201], v[108:111]
	v_mfma_f32_16x16x32_bf16 v[104:107], v[166:169], v[198:201], v[104:107]
	v_mfma_f32_16x16x32_bf16 v[92:95], v[158:161], v[206:209], v[92:95]
	v_mfma_f32_16x16x32_bf16 v[88:91], v[166:169], v[206:209], v[88:91]
	v_mfma_f32_16x16x32_bf16 v[76:79], v[158:161], v[214:217], v[76:79]
	v_mfma_f32_16x16x32_bf16 v[72:75], v[166:169], v[214:217], v[72:75]
	v_mfma_f32_16x16x32_bf16 v[116:119], v[170:173], v[186:189], 0
	v_mfma_f32_16x16x32_bf16 v[112:115], v[178:181], v[186:189], 0
	v_mfma_f32_16x16x32_bf16 v[100:103], v[170:173], v[194:197], 0
	v_mfma_f32_16x16x32_bf16 v[96:99], v[178:181], v[194:197], 0
	v_mfma_f32_16x16x32_bf16 v[84:87], v[170:173], v[202:205], 0
	v_mfma_f32_16x16x32_bf16 v[80:83], v[178:181], v[202:205], 0
	v_mfma_f32_16x16x32_bf16 v[68:71], v[170:173], v[210:213], 0
	v_mfma_f32_16x16x32_bf16 v[64:67], v[178:181], v[210:213], 0
	v_mfma_f32_16x16x32_bf16 v[116:119], v[174:177], v[190:193], v[116:119]
	v_mfma_f32_16x16x32_bf16 v[112:115], v[182:185], v[190:193], v[112:115]
	v_mfma_f32_16x16x32_bf16 v[100:103], v[174:177], v[198:201], v[100:103]
	v_mfma_f32_16x16x32_bf16 v[96:99], v[182:185], v[198:201], v[96:99]
	v_mfma_f32_16x16x32_bf16 v[84:87], v[174:177], v[206:209], v[84:87]
	v_mfma_f32_16x16x32_bf16 v[80:83], v[182:185], v[206:209], v[80:83]
	v_mfma_f32_16x16x32_bf16 v[68:71], v[174:177], v[214:217], v[68:71]
	v_mfma_f32_16x16x32_bf16 v[64:67], v[182:185], v[214:217], v[64:67]
	s_barrier
	s_setprio 0
	s_add_i32 s52, s42, s28
	s_mov_b32 m0, s52
	ds_read_b128 v[186:189], v156 offset:16384
	ds_read_b128 v[190:193], v156 offset:17408
	ds_read_b128 v[194:197], v156 offset:18432
	ds_read_b128 v[198:201], v156 offset:19456
	ds_read_b128 v[202:205], v156 offset:20480
	ds_read_b128 v[206:209], v156 offset:21504
	ds_read_b128 v[210:213], v156 offset:22528
	ds_read_b128 v[214:217], v156 offset:23552
	global_load_lds_dwordx4 v132, s[24:25]
	s_add_i32 m0, s52, 0x2000
	s_add_u32 s52, s24, 0x100000
	s_addc_u32 s53, s25, 0
	s_add_i32 s54, s43, s28
	global_load_lds_dwordx4 v128, s[24:25]
	s_mov_b32 m0, s54
	global_load_lds_dwordx4 v132, s[52:53]
	s_add_i32 m0, s54, 0x2000
	s_nop 0
	global_load_lds_dwordx4 v128, s[52:53]
	s_mov_b32 m0, s21
	s_nop 0
	global_load_lds_dwordx4 v134, s[26:27]
	s_mov_b32 m0, s31
	s_nop 0
	global_load_lds_dwordx4 v130, s[26:27]
	s_waitcnt vmcnt(8)
	s_waitcnt lgkmcnt(0)
	s_setprio 1
	s_barrier
; #define PG8_STAGE(bufoff, gbase, voff) do { _Pragma("unroll") for (int _i = 0; _i < 2; ++_i) \
;         __builtin_amdgcn_global_load_lds((const unsigned*)((const char*)(gbase) + (voff)[_i]), (PG8_LAS unsigned*)(lds + (bufoff) + ldsw + _i * 8192), 16, 0, 0); } while (0)
; #define PG8_LDA(dst, b, h) do { _Pragma("unroll") for (int m = 0; m < 4; ++m) _Pragma("unroll") for (int k = 0; k < 2; ++k) dst[m][k] = *(const PG8_LAS bf16x8*)(lds + PG8_SA(b, h) + aoff + m * 2048 + k * 1024); } while (0)
; #define PG8_LDB(dst, b, h) do { _Pragma("unroll") for (int n = 0; n < 2; ++n) _Pragma("unroll") for (int k = 0; k < 2; ++k) dst[n][k] = *(const PG8_LAS bf16x8*)(lds + PG8_SB(b, h) + boff + n * 2048 + k * 1024); } while (0)
; #define PG8_MMA(ai, bj, At, Bt) do { __builtin_amdgcn_s_setprio(1); _Pragma("unroll") for (int m = 0; m < 4; ++m) _Pragma("unroll") for (int n = 0; n < 2; ++n) _Pragma("unroll") for (int k = 0; k < 2; ++k) \
;         acc[ai][bj][m][n] = __builtin_amdgcn_mfma_f32_16x16x32_bf16(Bt[n][k], At[m][k], acc[ai][bj][m][n], 0, 0, 0); __builtin_amdgcn_s_setprio(0); } while (0)
; #define PG8_WAIT_V(n) asm volatile("s_waitcnt vmcnt(" #n ")" ::: "memory")
; #define PG8_WAIT_L(n) asm volatile("s_waitcnt lgkmcnt(" #n ")" ::: "memory")
; #define PG8_BAR __builtin_amdgcn_s_barrier()
; #define PG8_SCHED __builtin_amdgcn_sched_barrier(0)
; template <class Epi, class Sched, bool ALIGN_EPI = false, bool SP2 = false>
; __device__ __forceinline__ void gemm_phase(PG8_LAS unsigned char* lds, const Gemm g, const Sched& S, const Epi& E, const int wid) {
;     ...
;             PG8_WAIT_V(8); PG8_WAIT_L(0); PG8_BAR; PG8_MMA(1, 0, At, B0); PG8_MMA(1, 1, At, B1); PG8_BAR; PG8_SCHED;
;             PG8_LDB(B0, 1, 0); PG8_LDB(B1, 1, 1); PG8_SCHED; PG8_LDA(At, 1, 0); PG8_STAGE(PG8_SA(0, 1), a2 + hstep, voffA);
;             PG8_WAIT_V(8); PG8_WAIT_L(0); PG8_BAR; PG8_MMA(0, 0, At, B0); PG8_MMA(0, 1, At, B1); PG8_BAR; PG8_SCHED;
	v_mfma_f32_16x16x32_bf16 v[60:63], v[146:149], v[186:189], 0
	v_mfma_f32_16x16x32_bf16 v[56:59], v[162:165], v[186:189], 0
	v_mfma_f32_16x16x32_bf16 v[44:47], v[146:149], v[194:197], 0
	v_mfma_f32_16x16x32_bf16 v[40:43], v[162:165], v[194:197], 0
	v_mfma_f32_16x16x32_bf16 v[28:31], v[146:149], v[202:205], 0
	v_mfma_f32_16x16x32_bf16 v[24:27], v[162:165], v[202:205], 0
	v_mfma_f32_16x16x32_bf16 v[12:15], v[146:149], v[210:213], 0
	v_mfma_f32_16x16x32_bf16 v[8:11], v[162:165], v[210:213], 0
	v_mfma_f32_16x16x32_bf16 v[60:63], v[158:161], v[190:193], v[60:63]
	v_mfma_f32_16x16x32_bf16 v[56:59], v[166:169], v[190:193], v[56:59]
	v_mfma_f32_16x16x32_bf16 v[44:47], v[158:161], v[198:201], v[44:47]
	v_mfma_f32_16x16x32_bf16 v[40:43], v[166:169], v[198:201], v[40:43]
	v_mfma_f32_16x16x32_bf16 v[28:31], v[158:161], v[206:209], v[28:31]
	v_mfma_f32_16x16x32_bf16 v[24:27], v[166:169], v[206:209], v[24:27]
	v_mfma_f32_16x16x32_bf16 v[12:15], v[158:161], v[214:217], v[12:15]
	v_mfma_f32_16x16x32_bf16 v[8:11], v[166:169], v[214:217], v[8:11]
	v_mfma_f32_16x16x32_bf16 v[52:55], v[170:173], v[186:189], 0
	v_mfma_f32_16x16x32_bf16 v[48:51], v[178:181], v[186:189], 0
	v_mfma_f32_16x16x32_bf16 v[36:39], v[170:173], v[194:197], 0
	v_mfma_f32_16x16x32_bf16 v[32:35], v[178:181], v[194:197], 0
	v_mfma_f32_16x16x32_bf16 v[20:23], v[170:173], v[202:205], 0
	v_mfma_f32_16x16x32_bf16 v[16:19], v[178:181], v[202:205], 0
	v_mfma_f32_16x16x32_bf16 v[4:7], v[170:173], v[210:213], 0
	v_mfma_f32_16x16x32_bf16 v[0:3], v[178:181], v[210:213], 0
	v_mfma_f32_16x16x32_bf16 v[52:55], v[174:177], v[190:193], v[52:55]
	v_mfma_f32_16x16x32_bf16 v[48:51], v[182:185], v[190:193], v[48:51]
	v_mfma_f32_16x16x32_bf16 v[36:39], v[174:177], v[198:201], v[36:39]
	v_mfma_f32_16x16x32_bf16 v[32:35], v[182:185], v[198:201], v[32:35]
	v_mfma_f32_16x16x32_bf16 v[20:23], v[174:177], v[206:209], v[20:23]
	v_mfma_f32_16x16x32_bf16 v[16:19], v[182:185], v[206:209], v[16:19]
	v_mfma_f32_16x16x32_bf16 v[4:7], v[174:177], v[214:217], v[4:7]
	v_mfma_f32_16x16x32_bf16 v[0:3], v[182:185], v[214:217], v[0:3]
	s_barrier
	s_setprio 0
	s_add_i32 s52, 0, 0x18000
	s_add_i32 s53, 0, 0x1c000
	ds_read_b128 v[146:149], v246
	ds_read_b128 v[158:161], v246 offset:1024
	ds_read_b128 v[162:165], v246 offset:2048
	ds_read_b128 v[166:169], v246 offset:3072
	ds_read_b128 v[170:173], v248
	ds_read_b128 v[174:177], v248 offset:1024
	ds_read_b128 v[178:181], v248 offset:2048
	ds_read_b128 v[182:185], v248 offset:3072
	s_add_u32 s26, s26, 0x100000
	s_addc_u32 s27, s27, 0
	s_mov_b32 m0, s34
	ds_read_b128 v[186:189], v156 offset:32768
	ds_read_b128 v[190:193], v156 offset:33792
	ds_read_b128 v[194:197], v156 offset:34816
	ds_read_b128 v[198:201], v156 offset:35840
	ds_read_b128 v[202:205], v156 offset:36864
	ds_read_b128 v[206:209], v156 offset:37888
	ds_read_b128 v[210:213], v156 offset:38912
	ds_read_b128 v[214:217], v156 offset:39936
	global_load_lds_dwordx4 v134, s[26:27]
	s_mov_b32 m0, s35
	s_nop 0
	global_load_lds_dwordx4 v130, s[26:27]
	s_waitcnt vmcnt(8)
	s_waitcnt lgkmcnt(0)
	s_setprio 1
	s_barrier
	v_mfma_f32_16x16x32_bf16 v[124:127], v[146:149], v[186:189], v[124:127]
	v_mfma_f32_16x16x32_bf16 v[120:123], v[162:165], v[186:189], v[120:123]
	v_mfma_f32_16x16x32_bf16 v[108:111], v[146:149], v[194:197], v[108:111]
	v_mfma_f32_16x16x32_bf16 v[104:107], v[162:165], v[194:197], v[104:107]
	v_mfma_f32_16x16x32_bf16 v[92:95], v[146:149], v[202:205], v[92:95]
	v_mfma_f32_16x16x32_bf16 v[88:91], v[162:165], v[202:205], v[88:91]
	v_mfma_f32_16x16x32_bf16 v[76:79], v[146:149], v[210:213], v[76:79]
	v_mfma_f32_16x16x32_bf16 v[72:75], v[162:165], v[210:213], v[72:75]
	v_mfma_f32_16x16x32_bf16 v[124:127], v[158:161], v[190:193], v[124:127]
	v_mfma_f32_16x16x32_bf16 v[120:123], v[166:169], v[190:193], v[120:123]
	v_mfma_f32_16x16x32_bf16 v[108:111], v[158:161], v[198:201], v[108:111]
	v_mfma_f32_16x16x32_bf16 v[104:107], v[166:169], v[198:201], v[104:107]
	v_mfma_f32_16x16x32_bf16 v[92:95], v[158:161], v[206:209], v[92:95]
	v_mfma_f32_16x16x32_bf16 v[88:91], v[166:169], v[206:209], v[88:91]
	v_mfma_f32_16x16x32_bf16 v[76:79], v[158:161], v[214:217], v[76:79]
	v_mfma_f32_16x16x32_bf16 v[72:75], v[166:169], v[214:217], v[72:75]
	v_mfma_f32_16x16x32_bf16 v[116:119], v[170:173], v[186:189], v[116:119]
	v_mfma_f32_16x16x32_bf16 v[112:115], v[178:181], v[186:189], v[112:115]
	v_mfma_f32_16x16x32_bf16 v[100:103], v[170:173], v[194:197], v[100:103]
	v_mfma_f32_16x16x32_bf16 v[96:99], v[178:181], v[194:197], v[96:99]
	v_mfma_f32_16x16x32_bf16 v[84:87], v[170:173], v[202:205], v[84:87]
	v_mfma_f32_16x16x32_bf16 v[80:83], v[178:181], v[202:205], v[80:83]
	v_mfma_f32_16x16x32_bf16 v[68:71], v[170:173], v[210:213], v[68:71]
	v_mfma_f32_16x16x32_bf16 v[64:67], v[178:181], v[210:213], v[64:67]
	v_mfma_f32_16x16x32_bf16 v[116:119], v[174:177], v[190:193], v[116:119]
	v_mfma_f32_16x16x32_bf16 v[112:115], v[182:185], v[190:193], v[112:115]
	v_mfma_f32_16x16x32_bf16 v[100:103], v[174:177], v[198:201], v[100:103]
	v_mfma_f32_16x16x32_bf16 v[96:99], v[182:185], v[198:201], v[96:99]
	v_mfma_f32_16x16x32_bf16 v[84:87], v[174:177], v[206:209], v[84:87]
	v_mfma_f32_16x16x32_bf16 v[80:83], v[182:185], v[206:209], v[80:83]
	v_mfma_f32_16x16x32_bf16 v[68:71], v[174:177], v[214:217], v[68:71]
	v_mfma_f32_16x16x32_bf16 v[64:67], v[182:185], v[214:217], v[64:67]
	s_barrier
; #define PG8_STAGE(bufoff, gbase, voff) do { _Pragma("unroll") for (int _i = 0; _i < 2; ++_i) \
;         __builtin_amdgcn_global_load_lds((const unsigned*)((const char*)(gbase) + (voff)[_i]), (PG8_LAS unsigned*)(lds + (bufoff) + ldsw + _i * 8192), 16, 0, 0); } while (0)
; #define PG8_LDA(dst, b, h) do { _Pragma("unroll") for (int m = 0; m < 4; ++m) _Pragma("unroll") for (int k = 0; k < 2; ++k) dst[m][k] = *(const PG8_LAS bf16x8*)(lds + PG8_SA(b, h) + aoff + m * 2048 + k * 1024); } while (0)
; #define PG8_MMA(ai, bj, At, Bt) do { __builtin_amdgcn_s_setprio(1); _Pragma("unroll") for (int m = 0; m < 4; ++m) _Pragma("unroll") for (int n = 0; n < 2; ++n) _Pragma("unroll") for (int k = 0; k < 2; ++k) \
;         acc[ai][bj][m][n] = __builtin_amdgcn_mfma_f32_16x16x32_bf16(Bt[n][k], At[m][k], acc[ai][bj][m][n], 0, 0, 0); __builtin_amdgcn_s_setprio(0); } while (0)
; #define PG8_WAIT_V(n) asm volatile("s_waitcnt vmcnt(" #n ")" ::: "memory")
; #define PG8_WAIT_L(n) asm volatile("s_waitcnt lgkmcnt(" #n ")" ::: "memory")
; #define PG8_BAR __builtin_amdgcn_s_barrier()
; #define PG8_SCHED __builtin_amdgcn_sched_barrier(0)
; template <class Epi, class Sched, bool ALIGN_EPI = false, bool SP2 = false>
; __device__ __forceinline__ void gemm_phase(PG8_LAS unsigned char* lds, const Gemm g, const Sched& S, const Epi& E, const int wid) {
;     ...
;         for (int t = 0; t < nt; t += 2) {
;     ...
;             PG8_LDA(At, 1, 1); PG8_STAGE(PG8_SB(1, 0), b3, voffB); PG8_STAGE(PG8_SB(1, 1), b3 + hstep, voffB); PG8_STAGE(PG8_SA(1, 0), a3, voffA);
;             PG8_WAIT_V(8); PG8_WAIT_L(0); PG8_BAR; PG8_MMA(1, 0, At, B0); PG8_MMA(1, 1, At, B1); PG8_BAR; PG8_SCHED;
	s_setprio 0
	s_add_u32 s98, s24, 0x80
	s_addc_u32 s99, s25, 0
	s_add_u32 s100, s26, 0xfff00080
	s_addc_u32 s101, s27, -1
	s_add_i32 s26, s52, s28
	s_mov_b32 m0, s26
	ds_read_b128 v[186:189], v156 offset:49152
	ds_read_b128 v[190:193], v156 offset:50176
	ds_read_b128 v[194:197], v156 offset:51200
	ds_read_b128 v[198:201], v156 offset:52224
	ds_read_b128 v[202:205], v156 offset:53248
	ds_read_b128 v[206:209], v156 offset:54272
	ds_read_b128 v[210:213], v156 offset:55296
	ds_read_b128 v[214:217], v156 offset:56320
	global_load_lds_dwordx4 v132, s[98:99]
	s_add_i32 m0, s26, 0x2000
	s_add_u32 s24, s24, 0x100080
	s_addc_u32 s25, s25, 0
	s_add_i32 s26, s53, s28
	global_load_lds_dwordx4 v128, s[98:99]
	s_mov_b32 m0, s26
	s_nop 0
	global_load_lds_dwordx4 v132, s[24:25]
	s_add_i32 m0, s26, 0x2000
	s_nop 0
	global_load_lds_dwordx4 v128, s[24:25]
	s_mov_b32 m0, s37
	s_nop 0
	global_load_lds_dwordx4 v134, s[100:101]
	s_mov_b32 m0, s40
	s_nop 0
	global_load_lds_dwordx4 v130, s[100:101]
	s_waitcnt vmcnt(8)
	s_waitcnt lgkmcnt(0)
	s_setprio 1
	s_barrier
	v_mfma_f32_16x16x32_bf16 v[60:63], v[146:149], v[186:189], v[60:63]
	v_mfma_f32_16x16x32_bf16 v[56:59], v[162:165], v[186:189], v[56:59]
	v_mfma_f32_16x16x32_bf16 v[44:47], v[146:149], v[194:197], v[44:47]
	v_mfma_f32_16x16x32_bf16 v[40:43], v[162:165], v[194:197], v[40:43]
	v_mfma_f32_16x16x32_bf16 v[28:31], v[146:149], v[202:205], v[28:31]
	v_mfma_f32_16x16x32_bf16 v[24:27], v[162:165], v[202:205], v[24:27]
	v_mfma_f32_16x16x32_bf16 v[12:15], v[146:149], v[210:213], v[12:15]
	v_mfma_f32_16x16x32_bf16 v[8:11], v[162:165], v[210:213], v[8:11]
	v_mfma_f32_16x16x32_bf16 v[60:63], v[158:161], v[190:193], v[60:63]
	v_mfma_f32_16x16x32_bf16 v[56:59], v[166:169], v[190:193], v[56:59]
	v_mfma_f32_16x16x32_bf16 v[44:47], v[158:161], v[198:201], v[44:47]
	v_mfma_f32_16x16x32_bf16 v[40:43], v[166:169], v[198:201], v[40:43]
	v_mfma_f32_16x16x32_bf16 v[28:31], v[158:161], v[206:209], v[28:31]
	v_mfma_f32_16x16x32_bf16 v[24:27], v[166:169], v[206:209], v[24:27]
	v_mfma_f32_16x16x32_bf16 v[12:15], v[158:161], v[214:217], v[12:15]
	v_mfma_f32_16x16x32_bf16 v[8:11], v[166:169], v[214:217], v[8:11]
	v_mfma_f32_16x16x32_bf16 v[52:55], v[170:173], v[186:189], v[52:55]
	v_mfma_f32_16x16x32_bf16 v[48:51], v[178:181], v[186:189], v[48:51]
	v_mfma_f32_16x16x32_bf16 v[36:39], v[170:173], v[194:197], v[36:39]
	v_mfma_f32_16x16x32_bf16 v[32:35], v[178:181], v[194:197], v[32:35]
	v_mfma_f32_16x16x32_bf16 v[20:23], v[170:173], v[202:205], v[20:23]
	v_mfma_f32_16x16x32_bf16 v[16:19], v[178:181], v[202:205], v[16:19]
	v_mfma_f32_16x16x32_bf16 v[4:7], v[170:173], v[210:213], v[4:7]
	v_mfma_f32_16x16x32_bf16 v[0:3], v[178:181], v[210:213], v[0:3]
	v_mfma_f32_16x16x32_bf16 v[52:55], v[174:177], v[190:193], v[52:55]
	v_mfma_f32_16x16x32_bf16 v[48:51], v[182:185], v[190:193], v[48:51]
	v_mfma_f32_16x16x32_bf16 v[36:39], v[174:177], v[198:201], v[36:39]
	v_mfma_f32_16x16x32_bf16 v[32:35], v[182:185], v[198:201], v[32:35]
	v_mfma_f32_16x16x32_bf16 v[20:23], v[174:177], v[206:209], v[20:23]
	v_mfma_f32_16x16x32_bf16 v[16:19], v[182:185], v[206:209], v[16:19]
	v_mfma_f32_16x16x32_bf16 v[4:7], v[174:177], v[214:217], v[4:7]
	v_mfma_f32_16x16x32_bf16 v[0:3], v[182:185], v[214:217], v[0:3]
	s_barrier
	s_setprio 0
	s_add_i32 s51, s51, 2
	s_add_u32 s22, s22, 0x100
	s_addc_u32 s23, s23, 0
	s_add_u32 s49, s49, 0x100
	s_addc_u32 s50, s50, 0
	s_cmp_gt_u32 s51, 61
	s_cbranch_scc0 .LBB0_1764
	s_branch .Lpeel_exit_6

; #define PG8_STAGE(bufoff, gbase, voff) do { _Pragma("unroll") for (int _i = 0; _i < 2; ++_i) \
;         __builtin_amdgcn_global_load_lds((const unsigned*)((const char*)(gbase) + (voff)[_i]), (PG8_LAS unsigned*)(lds + (bufoff) + ldsw + _i * 8192), 16, 0, 0); } while (0)
; #define PG8_LDA(dst, b, h) do { _Pragma("unroll") for (int m = 0; m < 4; ++m) _Pragma("unroll") for (int k = 0; k < 2; ++k) dst[m][k] = *(const PG8_LAS bf16x8*)(lds + PG8_SA(b, h) + aoff + m * 2048 + k * 1024); } while (0)
; #define PG8_LDB(dst, b, h) do { _Pragma("unroll") for (int n = 0; n < 2; ++n) _Pragma("unroll") for (int k = 0; k < 2; ++k) dst[n][k] = *(const PG8_LAS bf16x8*)(lds + PG8_SB(b, h) + boff + n * 2048 + k * 1024); } while (0)
; #define PG8_MMA(ai, bj, At, Bt) do { __builtin_amdgcn_s_setprio(1); _Pragma("unroll") for (int m = 0; m < 4; ++m) _Pragma("unroll") for (int n = 0; n < 2; ++n) _Pragma("unroll") for (int k = 0; k < 2; ++k) \
;         acc[ai][bj][m][n] = __builtin_amdgcn_mfma_f32_16x16x32_bf16(Bt[n][k], At[m][k], acc[ai][bj][m][n], 0, 0, 0); __builtin_amdgcn_s_setprio(0); } while (0)
; #define PG8_WAIT_V(n) asm volatile("s_waitcnt vmcnt(" #n ")" ::: "memory")
; #define PG8_BAR __builtin_amdgcn_s_barrier()
; template <class Epi, class Sched, bool ALIGN_EPI = false, bool SP2 = false>
; __device__ __forceinline__ void gemm_phase(PG8_LAS unsigned char* lds, const Gemm g, const Sched& S, const Epi& E, const int wid) {
;     ...
;         for (int t = 0; t < nt; t += 2) {
;             const bool last = (t == nt - 2);
;             const char* a1 = cA + (size_t)(t + 1) * kstep;
;             const char* a2 = last ? nA : cA + (size_t)(t + 2) * kstep; const char* b2 = last ? nB : cB + (size_t)(t + 2) * kstep;
;             const char* a3 = a2 + kstep; const char* b3 = b2 + kstep;
;             if (last && has_next) S.a_ready(nxt);
;             if constexpr (SP2) {
;             PG8_LDB(B0, 0, 0); PG8_LDB(B1, 0, 1); PG8_SCHED; PG8_LDA(At, 0, 0); PG8_STAGE(PG8_SA(1, 1), a1 + hstep, voffA);
;             PG8_WAIT_V(8); PG8_WAIT_L(0); PG8_BAR; PG8_MMA(0, 0, At, B0); PG8_MMA(0, 1, At, B1); PG8_BAR; PG8_SCHED;
;             PG8_LDA(At, 0, 1); PG8_STAGE(PG8_SB(0, 0), b2, voffB); PG8_STAGE(PG8_SB(0, 1), b2 + hstep, voffB); PG8_STAGE(PG8_SA(0, 0), a2, voffA);
;             PG8_WAIT_V(8); PG8_WAIT_L(0); PG8_BAR; PG8_MMA(1, 0, At, B0); PG8_MMA(1, 1, At, B1); PG8_BAR; PG8_SCHED;
.LBB0_2054:
	s_add_u32 s40, s14, 0x100
	s_addc_u32 s41, s15, 0
	s_mov_b32 s42, -2
	v_add_u32_e32 v246, 0x18000, v153
	v_add_u32_e32 v248, 0x1c000, v153
	ds_read_b128 v[144:147], v155
	ds_read_b128 v[148:151], v155 offset:1024
	ds_read_b128 v[158:161], v155 offset:2048
	ds_read_b128 v[162:165], v155 offset:3072
	ds_read_b128 v[166:169], v156
	ds_read_b128 v[170:173], v156 offset:1024
	ds_read_b128 v[174:177], v156 offset:2048
	ds_read_b128 v[178:181], v156 offset:3072
	s_add_u32 s14, s12, 0x100
	s_addc_u32 s15, s13, 0
	s_cmpk_eq_i32 s42, 0xa8
	s_cselect_b32 s19, s3, s15
	s_cselect_b32 s18, s2, s14
	s_cselect_b32 s17, s11, s41
	s_cselect_b32 s16, s10, s40
	s_add_i32 m0, s24, 0xc000
	ds_read_b128 v[182:185], v157
	ds_read_b128 v[186:189], v157 offset:1024
	ds_read_b128 v[190:193], v157 offset:2048
	ds_read_b128 v[194:197], v157 offset:3072
	ds_read_b128 v[198:201], v157 offset:4096
	ds_read_b128 v[202:205], v157 offset:5120
	ds_read_b128 v[206:209], v157 offset:6144
	ds_read_b128 v[210:213], v157 offset:7168
	global_load_lds_dwordx4 v136, s[12:13]
	s_add_i32 m0, s24, 0xe000
	s_nop 0
	global_load_lds_dwordx4 v138, s[12:13]
	s_waitcnt vmcnt(8)
	s_waitcnt lgkmcnt(0)
	s_setprio 1
	s_barrier
	v_mfma_f32_16x16x32_bf16 v[124:127], v[144:147], v[182:185], 0
	v_mfma_f32_16x16x32_bf16 v[120:123], v[158:161], v[182:185], 0
	v_mfma_f32_16x16x32_bf16 v[108:111], v[144:147], v[190:193], 0
	v_mfma_f32_16x16x32_bf16 v[104:107], v[158:161], v[190:193], 0
	v_mfma_f32_16x16x32_bf16 v[96:99], v[144:147], v[198:201], 0
	v_mfma_f32_16x16x32_bf16 v[88:91], v[158:161], v[198:201], 0
	v_mfma_f32_16x16x32_bf16 v[80:83], v[144:147], v[206:209], 0
	v_mfma_f32_16x16x32_bf16 v[72:75], v[158:161], v[206:209], 0
	v_mfma_f32_16x16x32_bf16 v[124:127], v[148:151], v[186:189], v[124:127]
	v_mfma_f32_16x16x32_bf16 v[120:123], v[162:165], v[186:189], v[120:123]
	v_mfma_f32_16x16x32_bf16 v[108:111], v[148:151], v[194:197], v[108:111]
	v_mfma_f32_16x16x32_bf16 v[104:107], v[162:165], v[194:197], v[104:107]
	v_mfma_f32_16x16x32_bf16 v[96:99], v[148:151], v[202:205], v[96:99]
	v_mfma_f32_16x16x32_bf16 v[88:91], v[162:165], v[202:205], v[88:91]
	v_mfma_f32_16x16x32_bf16 v[80:83], v[148:151], v[210:213], v[80:83]
	v_mfma_f32_16x16x32_bf16 v[72:75], v[162:165], v[210:213], v[72:75]
	v_mfma_f32_16x16x32_bf16 v[116:119], v[166:169], v[182:185], 0
	v_mfma_f32_16x16x32_bf16 v[112:115], v[174:177], v[182:185], 0
	v_mfma_f32_16x16x32_bf16 v[100:103], v[166:169], v[190:193], 0
	v_mfma_f32_16x16x32_bf16 v[92:95], v[174:177], v[190:193], 0
	v_mfma_f32_16x16x32_bf16 v[84:87], v[166:169], v[198:201], 0
	v_mfma_f32_16x16x32_bf16 v[76:79], v[174:177], v[198:201], 0
	v_mfma_f32_16x16x32_bf16 v[68:71], v[166:169], v[206:209], 0
	v_mfma_f32_16x16x32_bf16 v[64:67], v[174:177], v[206:209], 0
	v_mfma_f32_16x16x32_bf16 v[116:119], v[170:173], v[186:189], v[116:119]
	v_mfma_f32_16x16x32_bf16 v[112:115], v[178:181], v[186:189], v[112:115]
	v_mfma_f32_16x16x32_bf16 v[100:103], v[170:173], v[194:197], v[100:103]
	v_mfma_f32_16x16x32_bf16 v[92:95], v[178:181], v[194:197], v[92:95]
	v_mfma_f32_16x16x32_bf16 v[84:87], v[170:173], v[202:205], v[84:87]
	v_mfma_f32_16x16x32_bf16 v[76:79], v[178:181], v[202:205], v[76:79]
	v_mfma_f32_16x16x32_bf16 v[68:71], v[170:173], v[210:213], v[68:71]
	v_mfma_f32_16x16x32_bf16 v[64:67], v[178:181], v[210:213], v[64:67]
	s_barrier
	s_setprio 0
	s_add_i32 s12, s34, s23
	s_mov_b32 m0, s12
	ds_read_b128 v[182:185], v157 offset:16384
	ds_read_b128 v[186:189], v157 offset:17408
	ds_read_b128 v[190:193], v157 offset:18432
	ds_read_b128 v[194:197], v157 offset:19456
	ds_read_b128 v[198:201], v157 offset:20480
	ds_read_b128 v[202:205], v157 offset:21504
	ds_read_b128 v[206:209], v157 offset:22528
	ds_read_b128 v[210:213], v157 offset:23552
	global_load_lds_dwordx4 v130, s[16:17]
	s_add_i32 m0, s12, 0x2000
	s_add_u32 s12, s16, 0x2b0000
	s_addc_u32 s13, s17, 0
	s_add_i32 s43, s35, s23
	global_load_lds_dwordx4 v134, s[16:17]
	s_mov_b32 m0, s43
	global_load_lds_dwordx4 v130, s[12:13]
	s_add_i32 m0, s43, 0x2000
	s_nop 0
	global_load_lds_dwordx4 v134, s[12:13]
	s_mov_b32 m0, s24
	s_nop 0
	global_load_lds_dwordx4 v128, s[18:19]
	s_mov_b32 m0, s25
	s_nop 0
	global_load_lds_dwordx4 v132, s[18:19]
	s_waitcnt vmcnt(8)
	s_waitcnt lgkmcnt(0)
	s_setprio 1
	s_barrier
	v_mfma_f32_16x16x32_bf16 v[60:63], v[144:147], v[182:185], 0
	v_mfma_f32_16x16x32_bf16 v[56:59], v[158:161], v[182:185], 0
	v_mfma_f32_16x16x32_bf16 v[48:51], v[144:147], v[190:193], 0
	v_mfma_f32_16x16x32_bf16 v[40:43], v[158:161], v[190:193], 0
	v_mfma_f32_16x16x32_bf16 v[32:35], v[144:147], v[198:201], 0
	v_mfma_f32_16x16x32_bf16 v[24:27], v[158:161], v[198:201], 0
	v_mfma_f32_16x16x32_bf16 v[16:19], v[144:147], v[206:209], 0
	v_mfma_f32_16x16x32_bf16 v[8:11], v[158:161], v[206:209], 0
	v_mfma_f32_16x16x32_bf16 v[60:63], v[148:151], v[186:189], v[60:63]
	v_mfma_f32_16x16x32_bf16 v[56:59], v[162:165], v[186:189], v[56:59]
	v_mfma_f32_16x16x32_bf16 v[48:51], v[148:151], v[194:197], v[48:51]
	v_mfma_f32_16x16x32_bf16 v[40:43], v[162:165], v[194:197], v[40:43]
	v_mfma_f32_16x16x32_bf16 v[32:35], v[148:151], v[202:205], v[32:35]
	v_mfma_f32_16x16x32_bf16 v[24:27], v[162:165], v[202:205], v[24:27]
	v_mfma_f32_16x16x32_bf16 v[16:19], v[148:151], v[210:213], v[16:19]
	v_mfma_f32_16x16x32_bf16 v[8:11], v[162:165], v[210:213], v[8:11]
	v_mfma_f32_16x16x32_bf16 v[52:55], v[166:169], v[182:185], 0
	v_mfma_f32_16x16x32_bf16 v[44:47], v[174:177], v[182:185], 0
	v_mfma_f32_16x16x32_bf16 v[36:39], v[166:169], v[190:193], 0
	v_mfma_f32_16x16x32_bf16 v[28:31], v[174:177], v[190:193], 0
	v_mfma_f32_16x16x32_bf16 v[20:23], v[166:169], v[198:201], 0
	v_mfma_f32_16x16x32_bf16 v[12:15], v[174:177], v[198:201], 0
	v_mfma_f32_16x16x32_bf16 v[4:7], v[166:169], v[206:209], 0
	v_mfma_f32_16x16x32_bf16 v[0:3], v[174:177], v[206:209], 0
	v_mfma_f32_16x16x32_bf16 v[52:55], v[170:173], v[186:189], v[52:55]
	v_mfma_f32_16x16x32_bf16 v[44:47], v[178:181], v[186:189], v[44:47]
	v_mfma_f32_16x16x32_bf16 v[36:39], v[170:173], v[194:197], v[36:39]
	v_mfma_f32_16x16x32_bf16 v[28:31], v[178:181], v[194:197], v[28:31]
	v_mfma_f32_16x16x32_bf16 v[20:23], v[170:173], v[202:205], v[20:23]
	v_mfma_f32_16x16x32_bf16 v[12:15], v[178:181], v[202:205], v[12:15]
	v_mfma_f32_16x16x32_bf16 v[4:7], v[170:173], v[210:213], v[4:7]
	v_mfma_f32_16x16x32_bf16 v[0:3], v[178:181], v[210:213], v[0:3]
	s_barrier
; #define PG8_STAGE(bufoff, gbase, voff) do { _Pragma("unroll") for (int _i = 0; _i < 2; ++_i) \
;         __builtin_amdgcn_global_load_lds((const unsigned*)((const char*)(gbase) + (voff)[_i]), (PG8_LAS unsigned*)(lds + (bufoff) + ldsw + _i * 8192), 16, 0, 0); } while (0)
; #define PG8_LDA(dst, b, h) do { _Pragma("unroll") for (int m = 0; m < 4; ++m) _Pragma("unroll") for (int k = 0; k < 2; ++k) dst[m][k] = *(const PG8_LAS bf16x8*)(lds + PG8_SA(b, h) + aoff + m * 2048 + k * 1024); } while (0)
; #define PG8_LDB(dst, b, h) do { _Pragma("unroll") for (int n = 0; n < 2; ++n) _Pragma("unroll") for (int k = 0; k < 2; ++k) dst[n][k] = *(const PG8_LAS bf16x8*)(lds + PG8_SB(b, h) + boff + n * 2048 + k * 1024); } while (0)
; #define PG8_MMA(ai, bj, At, Bt) do { __builtin_amdgcn_s_setprio(1); _Pragma("unroll") for (int m = 0; m < 4; ++m) _Pragma("unroll") for (int n = 0; n < 2; ++n) _Pragma("unroll") for (int k = 0; k < 2; ++k) \
;         acc[ai][bj][m][n] = __builtin_amdgcn_mfma_f32_16x16x32_bf16(Bt[n][k], At[m][k], acc[ai][bj][m][n], 0, 0, 0); __builtin_amdgcn_s_setprio(0); } while (0)
; #define PG8_WAIT_V(n) asm volatile("s_waitcnt vmcnt(" #n ")" ::: "memory")
; #define PG8_WAIT_L(n) asm volatile("s_waitcnt lgkmcnt(" #n ")" ::: "memory")
; #define PG8_BAR __builtin_amdgcn_s_barrier()
; #define PG8_SCHED __builtin_amdgcn_sched_barrier(0)
; template <class Epi, class Sched, bool ALIGN_EPI = false, bool SP2 = false>
; __device__ __forceinline__ void gemm_phase(PG8_LAS unsigned char* lds, const Gemm g, const Sched& S, const Epi& E, const int wid) {
;     ...
;             PG8_LDB(B0, 1, 0); PG8_LDB(B1, 1, 1); PG8_SCHED; PG8_LDA(At, 1, 0); PG8_STAGE(PG8_SA(0, 1), a2 + hstep, voffA);
;             PG8_WAIT_V(8); PG8_WAIT_L(0); PG8_BAR; PG8_MMA(0, 0, At, B0); PG8_MMA(0, 1, At, B1); PG8_BAR; PG8_SCHED;
;             PG8_LDA(At, 1, 1); PG8_STAGE(PG8_SB(1, 0), b3, voffB); PG8_STAGE(PG8_SB(1, 1), b3 + hstep, voffB); PG8_STAGE(PG8_SA(1, 0), a3, voffA);
;             PG8_WAIT_V(8); PG8_WAIT_L(0); PG8_BAR; PG8_MMA(1, 0, At, B0); PG8_MMA(1, 1, At, B1); PG8_BAR; PG8_SCHED;
	s_setprio 0
	s_add_i32 s43, 0, 0x18000
	s_add_i32 s44, 0, 0x1c000
	ds_read_b128 v[144:147], v246
	ds_read_b128 v[148:151], v246 offset:1024
	ds_read_b128 v[158:161], v246 offset:2048
	ds_read_b128 v[162:165], v246 offset:3072
	ds_read_b128 v[166:169], v248
	ds_read_b128 v[170:173], v248 offset:1024
	ds_read_b128 v[174:177], v248 offset:2048
	ds_read_b128 v[178:181], v248 offset:3072
	s_add_u32 s12, s18, 0x2b0000
	s_addc_u32 s13, s19, 0
	s_mov_b32 m0, s26
	ds_read_b128 v[182:185], v157 offset:32768
	ds_read_b128 v[186:189], v157 offset:33792
	ds_read_b128 v[190:193], v157 offset:34816
	ds_read_b128 v[194:197], v157 offset:35840
	ds_read_b128 v[198:201], v157 offset:36864
	ds_read_b128 v[202:205], v157 offset:37888
	ds_read_b128 v[206:209], v157 offset:38912
	ds_read_b128 v[210:213], v157 offset:39936
	global_load_lds_dwordx4 v128, s[12:13]
	s_mov_b32 m0, s27
	s_nop 0
	global_load_lds_dwordx4 v132, s[12:13]
	s_waitcnt vmcnt(8)
	s_waitcnt lgkmcnt(0)
	s_setprio 1
	s_barrier
	v_mfma_f32_16x16x32_bf16 v[124:127], v[144:147], v[182:185], v[124:127]
	v_mfma_f32_16x16x32_bf16 v[120:123], v[158:161], v[182:185], v[120:123]
	v_mfma_f32_16x16x32_bf16 v[108:111], v[144:147], v[190:193], v[108:111]
	v_mfma_f32_16x16x32_bf16 v[104:107], v[158:161], v[190:193], v[104:107]
	v_mfma_f32_16x16x32_bf16 v[96:99], v[144:147], v[198:201], v[96:99]
	v_mfma_f32_16x16x32_bf16 v[88:91], v[158:161], v[198:201], v[88:91]
	v_mfma_f32_16x16x32_bf16 v[80:83], v[144:147], v[206:209], v[80:83]
	v_mfma_f32_16x16x32_bf16 v[72:75], v[158:161], v[206:209], v[72:75]
	v_mfma_f32_16x16x32_bf16 v[124:127], v[148:151], v[186:189], v[124:127]
	v_mfma_f32_16x16x32_bf16 v[120:123], v[162:165], v[186:189], v[120:123]
	v_mfma_f32_16x16x32_bf16 v[108:111], v[148:151], v[194:197], v[108:111]
	v_mfma_f32_16x16x32_bf16 v[104:107], v[162:165], v[194:197], v[104:107]
	v_mfma_f32_16x16x32_bf16 v[96:99], v[148:151], v[202:205], v[96:99]
	v_mfma_f32_16x16x32_bf16 v[88:91], v[162:165], v[202:205], v[88:91]
	v_mfma_f32_16x16x32_bf16 v[80:83], v[148:151], v[210:213], v[80:83]
	v_mfma_f32_16x16x32_bf16 v[72:75], v[162:165], v[210:213], v[72:75]
	v_mfma_f32_16x16x32_bf16 v[116:119], v[166:169], v[182:185], v[116:119]
	v_mfma_f32_16x16x32_bf16 v[112:115], v[174:177], v[182:185], v[112:115]
	v_mfma_f32_16x16x32_bf16 v[100:103], v[166:169], v[190:193], v[100:103]
	v_mfma_f32_16x16x32_bf16 v[92:95], v[174:177], v[190:193], v[92:95]
	v_mfma_f32_16x16x32_bf16 v[84:87], v[166:169], v[198:201], v[84:87]
	v_mfma_f32_16x16x32_bf16 v[76:79], v[174:177], v[198:201], v[76:79]
	v_mfma_f32_16x16x32_bf16 v[68:71], v[166:169], v[206:209], v[68:71]
	v_mfma_f32_16x16x32_bf16 v[64:67], v[174:177], v[206:209], v[64:67]
	v_mfma_f32_16x16x32_bf16 v[116:119], v[170:173], v[186:189], v[116:119]
	v_mfma_f32_16x16x32_bf16 v[112:115], v[178:181], v[186:189], v[112:115]
	v_mfma_f32_16x16x32_bf16 v[100:103], v[170:173], v[194:197], v[100:103]
	v_mfma_f32_16x16x32_bf16 v[92:95], v[178:181], v[194:197], v[92:95]
	v_mfma_f32_16x16x32_bf16 v[84:87], v[170:173], v[202:205], v[84:87]
	v_mfma_f32_16x16x32_bf16 v[76:79], v[178:181], v[202:205], v[76:79]
	v_mfma_f32_16x16x32_bf16 v[68:71], v[170:173], v[210:213], v[68:71]
	v_mfma_f32_16x16x32_bf16 v[64:67], v[178:181], v[210:213], v[64:67]
	s_barrier
	s_setprio 0
	s_add_u32 s98, s16, 0x80
	s_addc_u32 s99, s17, 0
	s_add_u32 s100, s18, 0x80
	s_addc_u32 s101, s19, 0
	s_add_i32 s12, s43, s23
	s_mov_b32 m0, s12
	ds_read_b128 v[182:185], v157 offset:49152
	ds_read_b128 v[186:189], v157 offset:50176
	ds_read_b128 v[190:193], v157 offset:51200
	ds_read_b128 v[194:197], v157 offset:52224
	ds_read_b128 v[198:201], v157 offset:53248
	ds_read_b128 v[202:205], v157 offset:54272
	ds_read_b128 v[206:209], v157 offset:55296
	ds_read_b128 v[210:213], v157 offset:56320
	global_load_lds_dwordx4 v130, s[98:99]
	s_add_i32 m0, s12, 0x2000
	s_add_u32 s12, s16, 0x2b0080
	s_addc_u32 s13, s17, 0
	s_add_i32 s16, s44, s23
	global_load_lds_dwordx4 v134, s[98:99]
	s_mov_b32 m0, s16
	s_nop 0
	global_load_lds_dwordx4 v130, s[12:13]
	s_add_i32 m0, s16, 0x2000
	s_nop 0
	global_load_lds_dwordx4 v134, s[12:13]
	s_mov_b32 m0, s29
	s_nop 0
	global_load_lds_dwordx4 v128, s[100:101]
	s_mov_b32 m0, s30
	s_nop 0
	global_load_lds_dwordx4 v132, s[100:101]
	s_waitcnt vmcnt(8)
	s_waitcnt lgkmcnt(0)
	s_setprio 1
	s_barrier
	v_mfma_f32_16x16x32_bf16 v[60:63], v[144:147], v[182:185], v[60:63]
	v_mfma_f32_16x16x32_bf16 v[56:59], v[158:161], v[182:185], v[56:59]
	v_mfma_f32_16x16x32_bf16 v[48:51], v[144:147], v[190:193], v[48:51]
	v_mfma_f32_16x16x32_bf16 v[40:43], v[158:161], v[190:193], v[40:43]
	v_mfma_f32_16x16x32_bf16 v[32:35], v[144:147], v[198:201], v[32:35]
	v_mfma_f32_16x16x32_bf16 v[24:27], v[158:161], v[198:201], v[24:27]
	v_mfma_f32_16x16x32_bf16 v[16:19], v[144:147], v[206:209], v[16:19]
	v_mfma_f32_16x16x32_bf16 v[8:11], v[158:161], v[206:209], v[8:11]
	v_mfma_f32_16x16x32_bf16 v[60:63], v[148:151], v[186:189], v[60:63]
	v_mfma_f32_16x16x32_bf16 v[56:59], v[162:165], v[186:189], v[56:59]
	v_mfma_f32_16x16x32_bf16 v[48:51], v[148:151], v[194:197], v[48:51]
	v_mfma_f32_16x16x32_bf16 v[40:43], v[162:165], v[194:197], v[40:43]
	v_mfma_f32_16x16x32_bf16 v[32:35], v[148:151], v[202:205], v[32:35]
	v_mfma_f32_16x16x32_bf16 v[24:27], v[162:165], v[202:205], v[24:27]
	v_mfma_f32_16x16x32_bf16 v[16:19], v[148:151], v[210:213], v[16:19]
	v_mfma_f32_16x16x32_bf16 v[8:11], v[162:165], v[210:213], v[8:11]
	v_mfma_f32_16x16x32_bf16 v[52:55], v[166:169], v[182:185], v[52:55]
	v_mfma_f32_16x16x32_bf16 v[44:47], v[174:177], v[182:185], v[44:47]
	v_mfma_f32_16x16x32_bf16 v[36:39], v[166:169], v[190:193], v[36:39]
	v_mfma_f32_16x16x32_bf16 v[28:31], v[174:177], v[190:193], v[28:31]
	v_mfma_f32_16x16x32_bf16 v[20:23], v[166:169], v[198:201], v[20:23]
	v_mfma_f32_16x16x32_bf16 v[12:15], v[174:177], v[198:201], v[12:15]
	v_mfma_f32_16x16x32_bf16 v[4:7], v[166:169], v[206:209], v[4:7]
	v_mfma_f32_16x16x32_bf16 v[0:3], v[174:177], v[206:209], v[0:3]
	v_mfma_f32_16x16x32_bf16 v[52:55], v[170:173], v[186:189], v[52:55]
	v_mfma_f32_16x16x32_bf16 v[44:47], v[178:181], v[186:189], v[44:47]
	v_mfma_f32_16x16x32_bf16 v[36:39], v[170:173], v[194:197], v[36:39]
	v_mfma_f32_16x16x32_bf16 v[28:31], v[178:181], v[194:197], v[28:31]
	v_mfma_f32_16x16x32_bf16 v[20:23], v[170:173], v[202:205], v[20:23]
	v_mfma_f32_16x16x32_bf16 v[12:15], v[178:181], v[202:205], v[12:15]
	v_mfma_f32_16x16x32_bf16 v[4:7], v[170:173], v[210:213], v[4:7]
	v_mfma_f32_16x16x32_bf16 v[0:3], v[178:181], v[210:213], v[0:3]
	s_barrier
	s_setprio 0
	s_add_i32 s42, s42, 2
	s_add_u32 s40, s40, 0x100
	s_addc_u32 s41, s41, 0
	s_cmpk_gt_u32 s42, 0xa9
	s_mov_b64 s[12:13], s[14:15]
	s_cbranch_scc0 .LBB0_2055
	s_branch .Lpeel_exit_7
